# gate epilogue: hf params preloaded + counted row waits; tile stores kept in flight across tile boundary (Z,RES); transposer next-block loads overlapped
# speedup vs baseline: 1.0056x; 1.0056x over previous
; __device__ __forceinline__ int lane_id_hw() { int l; asm volatile("v_mbcnt_lo_u32_b32 %0, -1, 0\n\tv_mbcnt_hi_u32_b32 %0, -1, %0" : "=v"(l)); return l; }
; __device__ __forceinline__ float softplus_neg(float l) { const float e = __expf(-l); return (e < 0.03f) ? e * (1.0f - e * (0.5f - e * (0.33333333f - 0.25f * e))) : __logf(1.0f + e); }
;     __device__ __forceinline__ void operator()(const f32x4 (&acc)[2][2][4][2], const Unit& u, int wr, int wc, int fr, int fq) const {
;         { const int l_ = lane_id_hw(); fr = l_ & 15; fq = l_ >> 4; }
;         const int row0 = u.pm * BM + wr * 64 + fr, c0 = (u.pn >> 1) * 256 + (u.pn & 1) * 128 + wc * 32 + 8 * fq;
; #pragma unroll
;         for (int hf = 0; hf < 2; ++hf) {
;             const f32x4 lv = *(const f32x4*)(lam + c0 + 4 * hf), bav = *(const f32x4*)(b_a + c0 + 4 * hf), biv = *(const f32x4*)(b_i + c0 + 4 * hf);
;             f32x4 sp;
; #pragma unroll
;             for (int j = 0; j < 4; ++j) sp[j] = 8.0f * softplus_neg(lv[j]);
.LBB0_189:
	v_mbcnt_lo_u32_b32 v170, -1, 0
	v_mbcnt_hi_u32_b32 v170, -1, v170
	s_lshl_b32 s38, s59, 7
	v_ashrrev_i32_e32 v82, 1, v170
	s_or_b32 s0, s38, s50
	v_and_b32_e32 v82, -8, v82
	v_add_u32_e32 v152, s0, v82
	v_ashrrev_i32_e32 v153, 31, v152
	v_readlane_b32 s24, v253, 57
	v_lshlrev_b64 v[82:83], 2, v[152:153]
	v_readlane_b32 s26, v253, 59
	v_readlane_b32 s27, v253, 60
	s_load_dwordx2 s[0:1], s[68:69], 0xa0
	v_readlane_b32 s25, v253, 58
	v_lshl_add_u64 v[154:155], s[26:27], 0, v[82:83]
	global_load_dwordx4 v[138:141], v[154:155], off
	v_lshl_add_u64 v[158:159], s[24:25], 0, v[82:83]
	s_waitcnt lgkmcnt(0)
	v_lshl_add_u64 v[156:157], s[0:1], 0, v[82:83]
	global_load_dwordx4 v[86:89], v[156:157], off
	global_load_dwordx4 v[82:85], v[158:159], off
	global_load_dwordx4 v[176:179], v[154:155], off offset:16
	global_load_dwordx4 v[180:183], v[156:157], off offset:16
	global_load_dwordx4 v[184:187], v[158:159], off offset:16
	s_waitcnt vmcnt(0)
	v_mul_f32_e32 v138, 0xbfb8aa3b, v138
	v_exp_f32_e32 v138, v138
	s_nop 0
	v_cmp_ngt_f32_e32 vcc, s64, v138
	s_and_saveexec_b64 s[0:1], vcc
	s_xor_b64 s[36:37], exec, s[0:1]
	s_cbranch_execz .LBB0_191
	v_add_f32_e32 v138, 1.0, v138
	v_cmp_gt_f32_e32 vcc, s60, v138
	s_nop 1
	v_cndmask_b32_e64 v160, 0, 32, vcc
	v_ldexp_f32 v138, v138, v160
	v_log_f32_e32 v138, v138
	s_nop 0
	v_mul_f32_e32 v160, 0x3f317217, v138
	v_fma_f32 v160, v138, s65, -v160
	v_fmac_f32_e32 v160, 0x3377d1cf, v138
	v_fmac_f32_e32 v160, 0x3f317217, v138
	v_cmp_lt_f32_e64 s[6:7], |v138|, s66
	s_nop 1
	v_cndmask_b32_e64 v138, v138, v160, s[6:7]
	v_cndmask_b32_e32 v160, 0, v252, vcc
	v_sub_f32_e32 v162, v138, v160

; __device__ __forceinline__ float bf_lo(unsigned w) { return __uint_as_float(w << 16); }
; __device__ __forceinline__ float bf_hi(unsigned w) { return __uint_as_float(w & 0xffff0000u); }
; __device__ __forceinline__ unsigned pack_f16(float lo, float hi) { const _Float16 a = (_Float16)lo, b = (_Float16)hi; return (unsigned)__builtin_bit_cast(unsigned short, a) | ((unsigned)__builtin_bit_cast(unsigned short, b) << 16); }
;     __device__ __forceinline__ void operator()(const f32x4 (&acc)[2][2][4][2], const Unit& u, int wr, int wc, int fr, int fq) const {
;     ...
;             for (int ai = 0; ai < 2; ++ai)
; #pragma unroll
;                 for (int m = 0; m < 4; ++m) {
;                     const int row = row0 + ai * HALF + m * 16; const size_t off = (size_t)row * D + c0 + 4 * hf;
;                     const u32x2 xw = *(const u32x2*)(xrc + off); const float xr[4] = {bf_lo(xw.x), bf_hi(xw.x), bf_lo(xw.y), bf_hi(xw.y)};
;                     u32x4 w;
; #pragma unroll
;                     for (int j2 = 0; j2 < 2; ++j2) { const int j = 2 * j2;
;                         const f32x2v rp = (f32x2v){acc[ai][0][m][hf][j], acc[ai][0][m][hf][j + 1]} + (f32x2v){bav[j], bav[j + 1]}, ip = (f32x2v){acc[ai][1][m][hf][j], acc[ai][1][m][hf][j + 1]} + (f32x2v){biv[j], biv[j + 1]};
;                         const f32x2v er = rp * (-1.4426950408889634f), ei = ip * (-1.4426950408889634f);
;                         f32x2v tr, ti; tr.x = __builtin_amdgcn_exp2f(er.x); tr.y = __builtin_amdgcn_exp2f(er.y); ti.x = __builtin_amdgcn_exp2f(ei.x); ti.y = __builtin_amdgcn_exp2f(ei.y);
;                         const f32x2v dr = tr + 1.0f, di = ti + 1.0f; f32x2v r, ig; r.x = __builtin_amdgcn_rcpf(dr.x); r.y = __builtin_amdgcn_rcpf(dr.y); ig.x = __builtin_amdgcn_rcpf(di.x); ig.y = __builtin_amdgcn_rcpf(di.y);
;                         const f32x2v la = r * (f32x2v){-sp[j], -sp[j + 1]}, e2 = la * 2.8853900817779268f;
;                         f32x2v a2; a2.x = __builtin_amdgcn_exp2f(e2.x); a2.y = __builtin_amdgcn_exp2f(e2.y);
;                         const f32x2v om = __builtin_elementwise_max(1.0f - a2, (f32x2v){0.f, 0.f}); f32x2v mult; mult.x = __builtin_amdgcn_sqrtf(om.x); mult.y = __builtin_amdgcn_sqrtf(om.y);
;                         const f32x2v bt = (mult * ig) * (f32x2v){xr[j], xr[j + 1]};
;                         w[j] = pack_f16(la.x, bt.x); w[j + 1] = pack_f16(la.y, bt.y); }
.LBB0_203:
	s_andn2_saveexec_b64 s[0:1], s[36:37]
	v_fmamk_f32 v139, v138, 0xbe800000, v249
	v_fma_f32 v139, -v138, v139, 0.5
	v_fma_f32 v139, -v138, v139, 1.0
	v_mul_f32_e32 v161, v138, v139
	s_or_b64 exec, exec, s[0:1]
	s_lshl_b32 s39, s58, 8
	v_and_b32_e32 v171, 15, v170
	s_add_i32 s0, s39, s49
	v_or_b32_e32 v140, s0, v171
	v_ashrrev_i32_e32 v141, 31, v140
	v_lshlrev_b64 v[138:139], 10, v[140:141]
	v_lshl_add_u64 v[164:165], v[138:139], 0, v[152:153]
	v_lshlrev_b32_e32 v238, 1, v164
	v_add_u32_e32 v239, 0x0, v238
	global_load_dwordx2 v[222:223], v239, s[8:9]
	v_add_u32_e32 v239, 0x8000, v238
	global_load_dwordx2 v[224:225], v239, s[8:9]
	v_add_u32_e32 v239, 0x10000, v238
	global_load_dwordx2 v[226:227], v239, s[8:9]
	v_add_u32_e32 v239, 0x18000, v238
	global_load_dwordx2 v[228:229], v239, s[8:9]
	v_add_u32_e32 v239, 0x40000, v238
	global_load_dwordx2 v[230:231], v239, s[8:9]
	v_add_u32_e32 v239, 0x48000, v238
	global_load_dwordx2 v[232:233], v239, s[8:9]
	v_add_u32_e32 v239, 0x50000, v238
	global_load_dwordx2 v[234:235], v239, s[8:9]
	v_add_u32_e32 v239, 0x58000, v238
	global_load_dwordx2 v[236:237], v239, s[8:9]
	v_pk_add_f32 v[134:135], v[134:135], v[86:87]
	s_mov_b32 s0, 0xc1000000
	v_pk_mul_f32 v[134:135], v[134:135], s[88:89] op_sel_hi:[1,0]
	v_pk_add_f32 v[130:131], v[130:131], v[82:83]
	v_exp_f32_e32 v134, v134
	v_exp_f32_e32 v135, v135
	v_pk_mul_f32 v[130:131], v[130:131], s[88:89] op_sel_hi:[1,0]
	v_pk_add_f32 v[136:137], v[136:137], v[88:89]
	v_exp_f32_e32 v130, v130
	v_pk_add_f32 v[134:135], v[134:135], 1.0 op_sel_hi:[1,0]
	v_exp_f32_e32 v131, v131
	v_rcp_f32_e32 v174, v134
	v_rcp_f32_e32 v175, v135
	v_pk_mul_f32 v[134:135], v[162:163], s[0:1] op_sel_hi:[1,0]
	v_pk_add_f32 v[130:131], v[130:131], 1.0 op_sel_hi:[1,0]
	v_pk_add_f32 v[132:133], v[132:133], v[84:85]
	v_pk_mul_f32 v[162:163], v[174:175], v[134:135]
	v_rcp_f32_e32 v130, v130
	v_pk_mul_f32 v[174:175], v[162:163], s[82:83] op_sel_hi:[1,0]
	v_rcp_f32_e32 v131, v131
	v_exp_f32_e32 v174, v174
	v_exp_f32_e32 v175, v175
	v_pk_mul_f32 v[132:133], v[132:133], s[88:89] op_sel_hi:[1,0]
	v_pk_add_f32 v[126:127], v[126:127], v[86:87]
	v_exp_f32_e32 v132, v132
	v_pk_add_f32 v[174:175], v[174:175], 1.0 op_sel_hi:[1,0] neg_lo:[1,0] neg_hi:[1,0]
	v_exp_f32_e32 v133, v133
	v_max_f32_e32 v141, 0, v175
	v_max_f32_e32 v174, 0, v174
	v_sqrt_f32_e32 v174, v174
	v_sqrt_f32_e32 v175, v141
	v_cvt_f16_f32_e32 v141, v162
	v_pk_add_f32 v[132:133], v[132:133], 1.0 op_sel_hi:[1,0]
	v_pk_mul_f32 v[126:127], v[126:127], s[88:89] op_sel_hi:[1,0]
	v_pk_mul_f32 v[130:131], v[130:131], v[174:175]
	v_exp_f32_e32 v126, v126
	v_exp_f32_e32 v127, v127
	v_pk_add_f32 v[122:123], v[122:123], v[82:83]
	v_pk_add_f32 v[128:129], v[128:129], v[88:89]
	v_pk_mul_f32 v[122:123], v[122:123], s[88:89] op_sel_hi:[1,0]
	v_pk_add_f32 v[126:127], v[126:127], 1.0 op_sel_hi:[1,0]
	v_exp_f32_e32 v122, v122
	v_rcp_f32_e32 v126, v126
	v_rcp_f32_e32 v127, v127
	v_exp_f32_e32 v123, v123
	v_pk_add_f32 v[124:125], v[124:125], v[84:85]
	v_pk_add_f32 v[118:119], v[118:119], v[86:87]
	v_pk_mul_f32 v[126:127], v[126:127], v[134:135]
	v_pk_add_f32 v[122:123], v[122:123], 1.0 op_sel_hi:[1,0]
	v_pk_mul_f32 v[124:125], v[124:125], s[88:89] op_sel_hi:[1,0]
	v_rcp_f32_e32 v122, v122
	v_rcp_f32_e32 v123, v123
	v_exp_f32_e32 v124, v124
	v_exp_f32_e32 v125, v125
	v_pk_mul_f32 v[118:119], v[118:119], s[88:89] op_sel_hi:[1,0]
	v_pk_add_f32 v[114:115], v[114:115], v[82:83]
	v_exp_f32_e32 v118, v118
	v_pk_add_f32 v[124:125], v[124:125], 1.0 op_sel_hi:[1,0]
	v_exp_f32_e32 v119, v119
	v_rcp_f32_e32 v124, v124
	v_rcp_f32_e32 v125, v125
	v_pk_mul_f32 v[114:115], v[114:115], s[88:89] op_sel_hi:[1,0]
	v_pk_add_f32 v[118:119], v[118:119], 1.0 op_sel_hi:[1,0]
	v_exp_f32_e32 v114, v114
	v_rcp_f32_e32 v118, v118
	v_rcp_f32_e32 v119, v119
	v_exp_f32_e32 v115, v115
	v_pk_add_f32 v[120:121], v[120:121], v[88:89]
	v_pk_add_f32 v[116:117], v[116:117], v[84:85]
	v_pk_mul_f32 v[118:119], v[118:119], v[134:135]
	v_pk_add_f32 v[114:115], v[114:115], 1.0 op_sel_hi:[1,0]
	v_pk_mul_f32 v[116:117], v[116:117], s[88:89] op_sel_hi:[1,0]
	v_rcp_f32_e32 v114, v114
	v_rcp_f32_e32 v115, v115
	v_exp_f32_e32 v116, v116
	v_exp_f32_e32 v117, v117
	v_pk_add_f32 v[110:111], v[110:111], v[86:87]
	v_pk_add_f32 v[106:107], v[106:107], v[82:83]
	v_pk_mul_f32 v[110:111], v[110:111], s[88:89] op_sel_hi:[1,0]
	s_waitcnt vmcnt(7) lgkmcnt(0)
; __device__ __forceinline__ float bf_lo(unsigned w) { return __uint_as_float(w << 16); }
; __device__ __forceinline__ float bf_hi(unsigned w) { return __uint_as_float(w & 0xffff0000u); }
; __device__ __forceinline__ unsigned pack_f16(float lo, float hi) { const _Float16 a = (_Float16)lo, b = (_Float16)hi; return (unsigned)__builtin_bit_cast(unsigned short, a) | ((unsigned)__builtin_bit_cast(unsigned short, b) << 16); }
;     __device__ __forceinline__ void operator()(const f32x4 (&acc)[2][2][4][2], const Unit& u, int wr, int wc, int fr, int fq) const {
;     ...
;                     const int row = row0 + ai * HALF + m * 16; const size_t off = (size_t)row * D + c0 + 4 * hf;
;                     const u32x2 xw = *(const u32x2*)(xrc + off); const float xr[4] = {bf_lo(xw.x), bf_hi(xw.x), bf_lo(xw.y), bf_hi(xw.y)};
;                     u32x4 w;
; #pragma unroll
;                     for (int j2 = 0; j2 < 2; ++j2) { const int j = 2 * j2;
;                         const f32x2v rp = (f32x2v){acc[ai][0][m][hf][j], acc[ai][0][m][hf][j + 1]} + (f32x2v){bav[j], bav[j + 1]}, ip = (f32x2v){acc[ai][1][m][hf][j], acc[ai][1][m][hf][j + 1]} + (f32x2v){biv[j], biv[j + 1]};
;                         const f32x2v er = rp * (-1.4426950408889634f), ei = ip * (-1.4426950408889634f);
;                         f32x2v tr, ti; tr.x = __builtin_amdgcn_exp2f(er.x); tr.y = __builtin_amdgcn_exp2f(er.y); ti.x = __builtin_amdgcn_exp2f(ei.x); ti.y = __builtin_amdgcn_exp2f(ei.y);
;                         const f32x2v dr = tr + 1.0f, di = ti + 1.0f; f32x2v r, ig; r.x = __builtin_amdgcn_rcpf(dr.x); r.y = __builtin_amdgcn_rcpf(dr.y); ig.x = __builtin_amdgcn_rcpf(di.x); ig.y = __builtin_amdgcn_rcpf(di.y);
;                         const f32x2v la = r * (f32x2v){-sp[j], -sp[j + 1]}, e2 = la * 2.8853900817779268f;
;                         f32x2v a2; a2.x = __builtin_amdgcn_exp2f(e2.x); a2.y = __builtin_amdgcn_exp2f(e2.y);
;                         const f32x2v om = __builtin_elementwise_max(1.0f - a2, (f32x2v){0.f, 0.f}); f32x2v mult; mult.x = __builtin_amdgcn_sqrtf(om.x); mult.y = __builtin_amdgcn_sqrtf(om.y);
;                         const f32x2v bt = (mult * ig) * (f32x2v){xr[j], xr[j + 1]};
;                         w[j] = pack_f16(la.x, bt.x); w[j + 1] = pack_f16(la.y, bt.y); }
;                     *(u32x4*)(AB + off) = w;
;                     asm volatile("" ::: "memory");
	v_lshlrev_b32_e32 v172, 16, v222
	v_and_b32_e32 v173, 0xffff0000, v222
	v_pk_mul_f32 v[130:131], v[130:131], v[172:173]
	v_lshlrev_b32_e32 v166, 16, v223
	v_cvt_f16_f32_sdwa v130, v130 dst_sel:WORD_1 dst_unused:UNUSED_PAD src0_sel:DWORD
	v_cvt_f16_f32_sdwa v131, v131 dst_sel:WORD_1 dst_unused:UNUSED_PAD src0_sel:DWORD
	v_and_b32_e32 v167, 0xffff0000, v223
	v_add_u32_e32 v239, 0x8, v238
	global_load_dwordx2 v[222:223], v239, s[8:9]
	v_pk_add_f32 v[116:117], v[116:117], 1.0 op_sel_hi:[1,0]
	v_or_b32_e32 v172, v130, v141
	v_cvt_f16_f32_e32 v130, v163
	v_rcp_f32_e32 v116, v116
	v_rcp_f32_e32 v117, v117
	v_exp_f32_e32 v110, v110
	v_or_b32_e32 v173, v131, v130
	v_pk_mul_f32 v[130:131], v[136:137], s[88:89] op_sel_hi:[1,0]
	v_rcp_f32_e32 v136, v132
	v_exp_f32_e32 v130, v130
	v_exp_f32_e32 v131, v131
	v_rcp_f32_e32 v137, v133
	v_pk_mul_f32 v[132:133], v[160:161], s[0:1] op_sel_hi:[1,0]
	v_exp_f32_e32 v111, v111
	v_pk_add_f32 v[130:131], v[130:131], 1.0 op_sel_hi:[1,0]
	v_pk_mul_f32 v[106:107], v[106:107], s[88:89] op_sel_hi:[1,0]
	v_rcp_f32_e32 v130, v130
	v_rcp_f32_e32 v131, v131
	v_pk_add_f32 v[110:111], v[110:111], 1.0 op_sel_hi:[1,0]
	v_exp_f32_e32 v106, v106
	v_rcp_f32_e32 v110, v110
	v_pk_mul_f32 v[130:131], v[130:131], v[132:133]
	v_rcp_f32_e32 v111, v111
	v_pk_mul_f32 v[160:161], v[130:131], s[82:83] op_sel_hi:[1,0]
	v_cvt_f16_f32_e32 v130, v130
	v_exp_f32_e32 v160, v160
	v_exp_f32_e32 v161, v161
	v_pk_mul_f32 v[110:111], v[110:111], v[134:135]
	v_exp_f32_e32 v107, v107
	v_pk_add_f32 v[112:113], v[112:113], v[88:89]
	v_pk_add_f32 v[160:161], v[160:161], 1.0 op_sel_hi:[1,0] neg_lo:[1,0] neg_hi:[1,0]
	v_pk_add_f32 v[108:109], v[108:109], v[84:85]
	v_max_f32_e32 v141, 0, v161
	v_max_f32_e32 v160, 0, v160
	v_sqrt_f32_e32 v160, v160
	v_sqrt_f32_e32 v161, v141
	v_pk_add_f32 v[106:107], v[106:107], 1.0 op_sel_hi:[1,0]
	v_pk_mul_f32 v[108:109], v[108:109], s[88:89] op_sel_hi:[1,0]
	v_rcp_f32_e32 v106, v106
	v_pk_mul_f32 v[136:137], v[136:137], v[160:161]
	v_rcp_f32_e32 v107, v107
	v_pk_mul_f32 v[136:137], v[136:137], v[166:167]
	v_exp_f32_e32 v108, v108
	v_cvt_f16_f32_sdwa v136, v136 dst_sel:WORD_1 dst_unused:UNUSED_PAD src0_sel:DWORD
	v_exp_f32_e32 v109, v109
	s_mov_b64 s[6:7], 0x20000
	v_pk_add_f32 v[102:103], v[102:103], v[86:87]
	v_or_b32_e32 v174, v136, v130
	v_cvt_f16_f32_e32 v130, v131
	v_cvt_f16_f32_sdwa v131, v137 dst_sel:WORD_1 dst_unused:UNUSED_PAD src0_sel:DWORD
	v_pk_add_f32 v[108:109], v[108:109], 1.0 op_sel_hi:[1,0]
	v_pk_mul_f32 v[102:103], v[102:103], s[88:89] op_sel_hi:[1,0]
	v_rcp_f32_e32 v108, v108
	v_or_b32_e32 v175, v131, v130
	v_lshl_add_u64 v[130:131], v[164:165], 2, s[20:21]
	global_store_dwordx4 v[130:131], v[172:175], off
	v_or_b32_e32 v130, 16, v140
	v_ashrrev_i32_e32 v131, 31, v130
	v_lshlrev_b64 v[130:131], 10, v[130:131]
	v_lshl_add_u64 v[136:137], v[130:131], 0, v[152:153]
	v_pk_mul_f32 v[164:165], v[126:127], s[82:83] op_sel_hi:[1,0]
	v_cvt_f16_f32_e32 v126, v126
	v_exp_f32_e32 v164, v164
	v_exp_f32_e32 v165, v165
	v_rcp_f32_e32 v109, v109
	v_exp_f32_e32 v102, v102
	v_exp_f32_e32 v103, v103
	v_pk_add_f32 v[164:165], v[164:165], 1.0 op_sel_hi:[1,0] neg_lo:[1,0] neg_hi:[1,0]
	v_pk_add_f32 v[98:99], v[98:99], v[82:83]
	v_max_f32_e32 v141, 0, v165
	v_max_f32_e32 v164, 0, v164
	v_sqrt_f32_e32 v164, v164
	v_sqrt_f32_e32 v165, v141
	v_pk_add_f32 v[102:103], v[102:103], 1.0 op_sel_hi:[1,0]
	v_pk_mul_f32 v[98:99], v[98:99], s[88:89] op_sel_hi:[1,0]
	v_rcp_f32_e32 v102, v102
	v_pk_mul_f32 v[122:123], v[122:123], v[164:165]
	v_rcp_f32_e32 v103, v103
	v_exp_f32_e32 v98, v98
	v_exp_f32_e32 v99, v99
	v_pk_add_f32 v[104:105], v[104:105], v[88:89]
	v_pk_mul_f32 v[102:103], v[102:103], v[134:135]
	v_pk_add_f32 v[100:101], v[100:101], v[84:85]
	v_pk_add_f32 v[98:99], v[98:99], 1.0 op_sel_hi:[1,0]
	v_pk_mul_f32 v[100:101], v[100:101], s[88:89] op_sel_hi:[1,0]
	v_rcp_f32_e32 v98, v98
	v_rcp_f32_e32 v99, v99
	v_exp_f32_e32 v100, v100
	v_exp_f32_e32 v101, v101
	v_pk_add_f32 v[94:95], v[94:95], v[86:87]
	v_pk_add_f32 v[90:91], v[90:91], v[82:83]
	v_pk_mul_f32 v[94:95], v[94:95], s[88:89] op_sel_hi:[1,0]
	v_pk_add_f32 v[100:101], v[100:101], 1.0 op_sel_hi:[1,0]
	v_exp_f32_e32 v94, v94
	v_rcp_f32_e32 v100, v100
	v_rcp_f32_e32 v101, v101
	v_exp_f32_e32 v95, v95
	v_pk_mul_f32 v[90:91], v[90:91], s[88:89] op_sel_hi:[1,0]
	v_pk_add_f32 v[96:97], v[96:97], v[88:89]
	v_exp_f32_e32 v90, v90
	v_pk_add_f32 v[94:95], v[94:95], 1.0 op_sel_hi:[1,0]
	v_exp_f32_e32 v91, v91
	v_rcp_f32_e32 v94, v94
	v_rcp_f32_e32 v95, v95
	v_pk_add_f32 v[92:93], v[92:93], v[84:85]
	v_pk_add_f32 v[90:91], v[90:91], 1.0 op_sel_hi:[1,0]
	v_pk_mul_f32 v[92:93], v[92:93], s[88:89] op_sel_hi:[1,0]
	v_pk_mul_f32 v[94:95], v[94:95], v[134:135]
	v_rcp_f32_e32 v90, v90
	v_rcp_f32_e32 v91, v91
	v_exp_f32_e32 v92, v92
	v_exp_f32_e32 v93, v93
	v_pk_add_f32 v[78:79], v[78:79], v[86:87]
	v_pk_add_f32 v[74:75], v[74:75], v[82:83]
	v_pk_mul_f32 v[78:79], v[78:79], s[88:89] op_sel_hi:[1,0]
	v_pk_add_f32 v[92:93], v[92:93], 1.0 op_sel_hi:[1,0]
	v_exp_f32_e32 v78, v78
	v_rcp_f32_e32 v92, v92
	v_rcp_f32_e32 v93, v93
	v_exp_f32_e32 v79, v79
	v_pk_mul_f32 v[74:75], v[74:75], s[88:89] op_sel_hi:[1,0]
	v_pk_add_f32 v[80:81], v[80:81], v[88:89]
	v_exp_f32_e32 v74, v74
	v_pk_add_f32 v[78:79], v[78:79], 1.0 op_sel_hi:[1,0]
	v_exp_f32_e32 v75, v75
	v_rcp_f32_e32 v78, v78
	v_rcp_f32_e32 v79, v79
	v_pk_add_f32 v[76:77], v[76:77], v[84:85]
	v_pk_add_f32 v[74:75], v[74:75], 1.0 op_sel_hi:[1,0]
	v_pk_mul_f32 v[76:77], v[76:77], s[88:89] op_sel_hi:[1,0]
	v_pk_mul_f32 v[78:79], v[78:79], v[134:135]
	v_rcp_f32_e32 v74, v74
	v_rcp_f32_e32 v75, v75
	v_exp_f32_e32 v76, v76
	v_exp_f32_e32 v77, v77
	v_pk_add_f32 v[70:71], v[70:71], v[86:87]
	v_pk_add_f32 v[66:67], v[66:67], v[82:83]
	v_pk_mul_f32 v[70:71], v[70:71], s[88:89] op_sel_hi:[1,0]
	v_pk_add_f32 v[76:77], v[76:77], 1.0 op_sel_hi:[1,0]
	s_waitcnt vmcnt(8) lgkmcnt(0)
; __device__ __forceinline__ float bf_lo(unsigned w) { return __uint_as_float(w << 16); }
; __device__ __forceinline__ float bf_hi(unsigned w) { return __uint_as_float(w & 0xffff0000u); }
; __device__ __forceinline__ unsigned pack_f16(float lo, float hi) { const _Float16 a = (_Float16)lo, b = (_Float16)hi; return (unsigned)__builtin_bit_cast(unsigned short, a) | ((unsigned)__builtin_bit_cast(unsigned short, b) << 16); }
;     __device__ __forceinline__ void operator()(const f32x4 (&acc)[2][2][4][2], const Unit& u, int wr, int wc, int fr, int fq) const {
;     ...
;                     const int row = row0 + ai * HALF + m * 16; const size_t off = (size_t)row * D + c0 + 4 * hf;
;                     const u32x2 xw = *(const u32x2*)(xrc + off); const float xr[4] = {bf_lo(xw.x), bf_hi(xw.x), bf_lo(xw.y), bf_hi(xw.y)};
;                     u32x4 w;
; #pragma unroll
;                     for (int j2 = 0; j2 < 2; ++j2) { const int j = 2 * j2;
;                         const f32x2v rp = (f32x2v){acc[ai][0][m][hf][j], acc[ai][0][m][hf][j + 1]} + (f32x2v){bav[j], bav[j + 1]}, ip = (f32x2v){acc[ai][1][m][hf][j], acc[ai][1][m][hf][j + 1]} + (f32x2v){biv[j], biv[j + 1]};
;                         const f32x2v er = rp * (-1.4426950408889634f), ei = ip * (-1.4426950408889634f);
;                         f32x2v tr, ti; tr.x = __builtin_amdgcn_exp2f(er.x); tr.y = __builtin_amdgcn_exp2f(er.y); ti.x = __builtin_amdgcn_exp2f(ei.x); ti.y = __builtin_amdgcn_exp2f(ei.y);
;                         const f32x2v dr = tr + 1.0f, di = ti + 1.0f; f32x2v r, ig; r.x = __builtin_amdgcn_rcpf(dr.x); r.y = __builtin_amdgcn_rcpf(dr.y); ig.x = __builtin_amdgcn_rcpf(di.x); ig.y = __builtin_amdgcn_rcpf(di.y);
;                         const f32x2v la = r * (f32x2v){-sp[j], -sp[j + 1]}, e2 = la * 2.8853900817779268f;
;                         f32x2v a2; a2.x = __builtin_amdgcn_exp2f(e2.x); a2.y = __builtin_amdgcn_exp2f(e2.y);
;                         const f32x2v om = __builtin_elementwise_max(1.0f - a2, (f32x2v){0.f, 0.f}); f32x2v mult; mult.x = __builtin_amdgcn_sqrtf(om.x); mult.y = __builtin_amdgcn_sqrtf(om.y);
;                         const f32x2v bt = (mult * ig) * (f32x2v){xr[j], xr[j + 1]};
;                         w[j] = pack_f16(la.x, bt.x); w[j + 1] = pack_f16(la.y, bt.y); }
;                     *(u32x4*)(AB + off) = w;
;                     asm volatile("" ::: "memory");
	v_lshlrev_b32_e32 v162, 16, v224
	v_and_b32_e32 v163, 0xffff0000, v224
	v_pk_mul_f32 v[122:123], v[122:123], v[162:163]
	v_lshlrev_b32_e32 v160, 16, v225
	v_cvt_f16_f32_sdwa v122, v122 dst_sel:WORD_1 dst_unused:UNUSED_PAD src0_sel:DWORD
	v_cvt_f16_f32_sdwa v123, v123 dst_sel:WORD_1 dst_unused:UNUSED_PAD src0_sel:DWORD
	v_and_b32_e32 v161, 0xffff0000, v225
	v_add_u32_e32 v239, 0x8008, v238
	global_load_dwordx2 v[224:225], v239, s[8:9]
	v_rcp_f32_e32 v76, v76
	v_or_b32_e32 v122, v122, v126
	v_cvt_f16_f32_e32 v126, v127
	v_rcp_f32_e32 v77, v77
	v_exp_f32_e32 v70, v70
	v_exp_f32_e32 v71, v71
	v_or_b32_e32 v123, v123, v126
	v_pk_mul_f32 v[126:127], v[128:129], s[88:89] op_sel_hi:[1,0]
	v_pk_mul_f32 v[66:67], v[66:67], s[88:89] op_sel_hi:[1,0]
	v_exp_f32_e32 v126, v126
	v_exp_f32_e32 v127, v127
	v_pk_add_f32 v[70:71], v[70:71], 1.0 op_sel_hi:[1,0]
	v_exp_f32_e32 v66, v66
	v_rcp_f32_e32 v70, v70
	v_pk_add_f32 v[126:127], v[126:127], 1.0 op_sel_hi:[1,0]
	v_rcp_f32_e32 v71, v71
	v_rcp_f32_e32 v126, v126
	v_rcp_f32_e32 v127, v127
	v_exp_f32_e32 v67, v67
	v_pk_mul_f32 v[70:71], v[70:71], v[134:135]
	v_pk_add_f32 v[72:73], v[72:73], v[88:89]
	v_pk_mul_f32 v[126:127], v[126:127], v[132:133]
	v_pk_mul_f32 v[82:83], v[70:71], s[82:83] op_sel_hi:[1,0]
	v_pk_mul_f32 v[128:129], v[126:127], s[82:83] op_sel_hi:[1,0]
	v_cvt_f16_f32_e32 v126, v126
	v_exp_f32_e32 v128, v128
	v_exp_f32_e32 v129, v129
	v_exp_f32_e32 v82, v82
	v_exp_f32_e32 v83, v83
	v_pk_add_f32 v[66:67], v[66:67], 1.0 op_sel_hi:[1,0]
	v_pk_add_f32 v[128:129], v[128:129], 1.0 op_sel_hi:[1,0] neg_lo:[1,0] neg_hi:[1,0]
	v_rcp_f32_e32 v66, v66
	v_max_f32_e32 v129, 0, v129
	v_max_f32_e32 v128, 0, v128
	v_sqrt_f32_e32 v128, v128
	v_sqrt_f32_e32 v129, v129
	v_pk_add_f32 v[82:83], v[82:83], 1.0 op_sel_hi:[1,0] neg_lo:[1,0] neg_hi:[1,0]
	v_rcp_f32_e32 v67, v67
	v_max_f32_e32 v83, 0, v83
	v_pk_mul_f32 v[124:125], v[124:125], v[128:129]
	v_max_f32_e32 v82, 0, v82
	v_pk_mul_f32 v[124:125], v[124:125], v[160:161]
	v_sqrt_f32_e32 v82, v82
	v_cvt_f16_f32_sdwa v124, v124 dst_sel:WORD_1 dst_unused:UNUSED_PAD src0_sel:DWORD
	v_cvt_f16_f32_sdwa v125, v125 dst_sel:WORD_1 dst_unused:UNUSED_PAD src0_sel:DWORD
	v_sqrt_f32_e32 v83, v83
	v_cvt_f16_f32_e32 v70, v70
	v_or_b32_e32 v124, v124, v126
	v_cvt_f16_f32_e32 v126, v127
	v_pk_mul_f32 v[66:67], v[66:67], v[82:83]
	v_pk_add_f32 v[68:69], v[68:69], v[84:85]
	v_or_b32_e32 v125, v125, v126
	v_lshl_add_u64 v[126:127], v[136:137], 2, s[20:21]
	global_store_dwordx4 v[126:127], v[122:125], off
	v_pk_mul_f32 v[136:137], v[118:119], s[82:83] op_sel_hi:[1,0]
	v_cvt_f16_f32_e32 v118, v118
	v_or_b32_e32 v122, 32, v140
	v_ashrrev_i32_e32 v123, 31, v122
	v_lshlrev_b64 v[122:123], 10, v[122:123]
	v_lshl_add_u64 v[124:125], v[122:123], 0, v[152:153]
	v_exp_f32_e32 v136, v136
	v_exp_f32_e32 v137, v137
	v_pk_mul_f32 v[68:69], v[68:69], s[88:89] op_sel_hi:[1,0]
	v_pk_add_f32 v[136:137], v[136:137], 1.0 op_sel_hi:[1,0] neg_lo:[1,0] neg_hi:[1,0]
	s_nop 0
	v_max_f32_e32 v137, 0, v137
	v_max_f32_e32 v136, 0, v136
	v_sqrt_f32_e32 v136, v136
	v_sqrt_f32_e32 v137, v137
	v_exp_f32_e32 v68, v68
	v_exp_f32_e32 v69, v69
	v_pk_mul_f32 v[114:115], v[114:115], v[136:137]
	v_pk_add_f32 v[68:69], v[68:69], 1.0 op_sel_hi:[1,0]
	s_nop 0
	v_rcp_f32_e32 v68, v68
	v_rcp_f32_e32 v69, v69
	s_waitcnt vmcnt(9) lgkmcnt(0)
	v_lshlrev_b32_e32 v128, 16, v226
	v_and_b32_e32 v129, 0xffff0000, v226
	v_pk_mul_f32 v[114:115], v[114:115], v[128:129]
	v_lshlrev_b32_e32 v126, 16, v227
	v_cvt_f16_f32_sdwa v114, v114 dst_sel:WORD_1 dst_unused:UNUSED_PAD src0_sel:DWORD
	v_cvt_f16_f32_sdwa v115, v115 dst_sel:WORD_1 dst_unused:UNUSED_PAD src0_sel:DWORD
	v_and_b32_e32 v127, 0xffff0000, v227
	v_add_u32_e32 v239, 0x10008, v238
	global_load_dwordx2 v[226:227], v239, s[8:9]
	v_or_b32_e32 v114, v114, v118
	v_cvt_f16_f32_e32 v118, v119
	v_or_b32_e32 v115, v115, v118
	v_pk_mul_f32 v[118:119], v[120:121], s[88:89] op_sel_hi:[1,0]
	s_nop 0
	v_exp_f32_e32 v118, v118
	v_exp_f32_e32 v119, v119
	s_nop 0
	v_pk_add_f32 v[118:119], v[118:119], 1.0 op_sel_hi:[1,0]
	s_nop 0
	v_rcp_f32_e32 v118, v118
	v_rcp_f32_e32 v119, v119
	s_nop 0
	v_pk_mul_f32 v[118:119], v[118:119], v[132:133]
	s_nop 0
	v_pk_mul_f32 v[120:121], v[118:119], s[82:83] op_sel_hi:[1,0]
	v_cvt_f16_f32_e32 v118, v118
	v_exp_f32_e32 v120, v120
	v_exp_f32_e32 v121, v121
	s_nop 0
	v_pk_add_f32 v[120:121], v[120:121], 1.0 op_sel_hi:[1,0] neg_lo:[1,0] neg_hi:[1,0]
	s_nop 0
	v_max_f32_e32 v121, 0, v121
	v_max_f32_e32 v120, 0, v120
	v_sqrt_f32_e32 v120, v120
	v_sqrt_f32_e32 v121, v121
	s_nop 0
	v_pk_mul_f32 v[116:117], v[116:117], v[120:121]
	s_nop 0
	v_pk_mul_f32 v[116:117], v[116:117], v[126:127]
	s_nop 0
	v_cvt_f16_f32_sdwa v116, v116 dst_sel:WORD_1 dst_unused:UNUSED_PAD src0_sel:DWORD
	v_cvt_f16_f32_sdwa v117, v117 dst_sel:WORD_1 dst_unused:UNUSED_PAD src0_sel:DWORD
	v_or_b32_e32 v116, v116, v118
	v_cvt_f16_f32_e32 v118, v119
	v_or_b32_e32 v117, v117, v118
	v_lshl_add_u64 v[118:119], v[124:125], 2, s[20:21]
	global_store_dwordx4 v[118:119], v[114:117], off
	v_pk_mul_f32 v[124:125], v[110:111], s[82:83] op_sel_hi:[1,0]
	v_cvt_f16_f32_e32 v110, v110
	v_or_b32_e32 v114, 48, v140
	v_ashrrev_i32_e32 v115, 31, v114
	v_lshlrev_b64 v[114:115], 10, v[114:115]
	v_lshl_add_u64 v[116:117], v[114:115], 0, v[152:153]
	v_exp_f32_e32 v124, v124
	v_exp_f32_e32 v125, v125
	s_waitcnt vmcnt(10) lgkmcnt(0)
; __device__ __forceinline__ float bf_lo(unsigned w) { return __uint_as_float(w << 16); }
; __device__ __forceinline__ float bf_hi(unsigned w) { return __uint_as_float(w & 0xffff0000u); }
; __device__ __forceinline__ unsigned pack_f16(float lo, float hi) { const _Float16 a = (_Float16)lo, b = (_Float16)hi; return (unsigned)__builtin_bit_cast(unsigned short, a) | ((unsigned)__builtin_bit_cast(unsigned short, b) << 16); }
;     __device__ __forceinline__ void operator()(const f32x4 (&acc)[2][2][4][2], const Unit& u, int wr, int wc, int fr, int fq) const {
;     ...
;                     const int row = row0 + ai * HALF + m * 16; const size_t off = (size_t)row * D + c0 + 4 * hf;
;                     const u32x2 xw = *(const u32x2*)(xrc + off); const float xr[4] = {bf_lo(xw.x), bf_hi(xw.x), bf_lo(xw.y), bf_hi(xw.y)};
;                     u32x4 w;
; #pragma unroll
;                     for (int j2 = 0; j2 < 2; ++j2) { const int j = 2 * j2;
;                         const f32x2v rp = (f32x2v){acc[ai][0][m][hf][j], acc[ai][0][m][hf][j + 1]} + (f32x2v){bav[j], bav[j + 1]}, ip = (f32x2v){acc[ai][1][m][hf][j], acc[ai][1][m][hf][j + 1]} + (f32x2v){biv[j], biv[j + 1]};
;                         const f32x2v er = rp * (-1.4426950408889634f), ei = ip * (-1.4426950408889634f);
;                         f32x2v tr, ti; tr.x = __builtin_amdgcn_exp2f(er.x); tr.y = __builtin_amdgcn_exp2f(er.y); ti.x = __builtin_amdgcn_exp2f(ei.x); ti.y = __builtin_amdgcn_exp2f(ei.y);
;                         const f32x2v dr = tr + 1.0f, di = ti + 1.0f; f32x2v r, ig; r.x = __builtin_amdgcn_rcpf(dr.x); r.y = __builtin_amdgcn_rcpf(dr.y); ig.x = __builtin_amdgcn_rcpf(di.x); ig.y = __builtin_amdgcn_rcpf(di.y);
;                         const f32x2v la = r * (f32x2v){-sp[j], -sp[j + 1]}, e2 = la * 2.8853900817779268f;
;                         f32x2v a2; a2.x = __builtin_amdgcn_exp2f(e2.x); a2.y = __builtin_amdgcn_exp2f(e2.y);
;                         const f32x2v om = __builtin_elementwise_max(1.0f - a2, (f32x2v){0.f, 0.f}); f32x2v mult; mult.x = __builtin_amdgcn_sqrtf(om.x); mult.y = __builtin_amdgcn_sqrtf(om.y);
;                         const f32x2v bt = (mult * ig) * (f32x2v){xr[j], xr[j + 1]};
;                         w[j] = pack_f16(la.x, bt.x); w[j + 1] = pack_f16(la.y, bt.y); }
;                     *(u32x4*)(AB + off) = w;
;                     asm volatile("" ::: "memory");
	v_lshlrev_b32_e32 v120, 16, v228
	v_pk_add_f32 v[124:125], v[124:125], 1.0 op_sel_hi:[1,0] neg_lo:[1,0] neg_hi:[1,0]
	v_and_b32_e32 v121, 0xffff0000, v228
	v_max_f32_e32 v125, 0, v125
	v_max_f32_e32 v124, 0, v124
	v_sqrt_f32_e32 v124, v124
	v_sqrt_f32_e32 v125, v125
	v_lshlrev_b32_e32 v118, 16, v229
	v_and_b32_e32 v119, 0xffff0000, v229
	v_add_u32_e32 v239, 0x18008, v238
	global_load_dwordx2 v[228:229], v239, s[8:9]
	v_pk_mul_f32 v[106:107], v[106:107], v[124:125]
	s_nop 0
	v_pk_mul_f32 v[106:107], v[106:107], v[120:121]
	s_nop 0
	v_cvt_f16_f32_sdwa v106, v106 dst_sel:WORD_1 dst_unused:UNUSED_PAD src0_sel:DWORD
	v_cvt_f16_f32_sdwa v107, v107 dst_sel:WORD_1 dst_unused:UNUSED_PAD src0_sel:DWORD
	v_or_b32_e32 v106, v106, v110
	v_cvt_f16_f32_e32 v110, v111
	v_or_b32_e32 v107, v107, v110
	v_pk_mul_f32 v[110:111], v[112:113], s[88:89] op_sel_hi:[1,0]
	s_nop 0
	v_exp_f32_e32 v110, v110
	v_exp_f32_e32 v111, v111
	s_nop 0
	v_pk_add_f32 v[110:111], v[110:111], 1.0 op_sel_hi:[1,0]
	s_nop 0
	v_rcp_f32_e32 v110, v110
	v_rcp_f32_e32 v111, v111
	s_nop 0
	v_pk_mul_f32 v[110:111], v[110:111], v[132:133]
	s_nop 0
	v_pk_mul_f32 v[112:113], v[110:111], s[82:83] op_sel_hi:[1,0]
	v_cvt_f16_f32_e32 v110, v110
	v_exp_f32_e32 v112, v112
	v_exp_f32_e32 v113, v113
	s_nop 0
	v_pk_add_f32 v[112:113], v[112:113], 1.0 op_sel_hi:[1,0] neg_lo:[1,0] neg_hi:[1,0]
	s_nop 0
	v_max_f32_e32 v113, 0, v113
	v_max_f32_e32 v112, 0, v112
	v_sqrt_f32_e32 v112, v112
	v_sqrt_f32_e32 v113, v113
	s_nop 0
	v_pk_mul_f32 v[108:109], v[108:109], v[112:113]
	s_nop 0
	v_pk_mul_f32 v[108:109], v[108:109], v[118:119]
	s_nop 0
	v_cvt_f16_f32_sdwa v108, v108 dst_sel:WORD_1 dst_unused:UNUSED_PAD src0_sel:DWORD
	v_cvt_f16_f32_sdwa v109, v109 dst_sel:WORD_1 dst_unused:UNUSED_PAD src0_sel:DWORD
	v_or_b32_e32 v108, v108, v110
	v_cvt_f16_f32_e32 v110, v111
	v_or_b32_e32 v109, v109, v110
	v_lshl_add_u64 v[110:111], v[116:117], 2, s[20:21]
	global_store_dwordx4 v[110:111], v[106:109], off
	v_pk_mul_f32 v[116:117], v[102:103], s[82:83] op_sel_hi:[1,0]
	v_cvt_f16_f32_e32 v102, v102
	v_lshl_add_u64 v[106:107], v[138:139], 0, s[6:7]
	v_lshl_add_u64 v[108:109], v[106:107], 0, v[152:153]
	v_exp_f32_e32 v116, v116
	v_exp_f32_e32 v117, v117
	s_mov_b64 s[6:7], 0x24000
	v_pk_add_f32 v[116:117], v[116:117], 1.0 op_sel_hi:[1,0] neg_lo:[1,0] neg_hi:[1,0]
	s_nop 0
	v_max_f32_e32 v117, 0, v117
	v_max_f32_e32 v116, 0, v116
	v_sqrt_f32_e32 v116, v116
	v_sqrt_f32_e32 v117, v117
	s_waitcnt vmcnt(11) lgkmcnt(0)
	v_lshlrev_b32_e32 v112, 16, v230
	v_and_b32_e32 v113, 0xffff0000, v230
	v_pk_mul_f32 v[98:99], v[98:99], v[116:117]
	v_lshlrev_b32_e32 v110, 16, v231
	v_pk_mul_f32 v[98:99], v[98:99], v[112:113]
	v_and_b32_e32 v111, 0xffff0000, v231
	v_add_u32_e32 v239, 0x40008, v238
	global_load_dwordx2 v[230:231], v239, s[8:9]
	v_cvt_f16_f32_sdwa v98, v98 dst_sel:WORD_1 dst_unused:UNUSED_PAD src0_sel:DWORD
	v_cvt_f16_f32_sdwa v99, v99 dst_sel:WORD_1 dst_unused:UNUSED_PAD src0_sel:DWORD
	v_or_b32_e32 v98, v98, v102
	v_cvt_f16_f32_e32 v102, v103
	v_or_b32_e32 v99, v99, v102
	v_pk_mul_f32 v[102:103], v[104:105], s[88:89] op_sel_hi:[1,0]
	s_nop 0
	v_exp_f32_e32 v102, v102
	v_exp_f32_e32 v103, v103
	s_nop 0
	v_pk_add_f32 v[102:103], v[102:103], 1.0 op_sel_hi:[1,0]
	s_nop 0
	v_rcp_f32_e32 v102, v102
	v_rcp_f32_e32 v103, v103
	s_nop 0
	v_pk_mul_f32 v[102:103], v[102:103], v[132:133]
	s_nop 0
	v_pk_mul_f32 v[104:105], v[102:103], s[82:83] op_sel_hi:[1,0]
	v_cvt_f16_f32_e32 v102, v102
	v_exp_f32_e32 v104, v104
	v_exp_f32_e32 v105, v105
	s_nop 0
	v_pk_add_f32 v[104:105], v[104:105], 1.0 op_sel_hi:[1,0] neg_lo:[1,0] neg_hi:[1,0]
	s_nop 0
	v_max_f32_e32 v105, 0, v105
	v_max_f32_e32 v104, 0, v104
	v_sqrt_f32_e32 v104, v104
	v_sqrt_f32_e32 v105, v105
	s_nop 0
	v_pk_mul_f32 v[100:101], v[100:101], v[104:105]
	s_nop 0
	v_pk_mul_f32 v[100:101], v[100:101], v[110:111]
	s_nop 0
	v_cvt_f16_f32_sdwa v100, v100 dst_sel:WORD_1 dst_unused:UNUSED_PAD src0_sel:DWORD
	v_cvt_f16_f32_sdwa v101, v101 dst_sel:WORD_1 dst_unused:UNUSED_PAD src0_sel:DWORD
	v_or_b32_e32 v100, v100, v102
	v_cvt_f16_f32_e32 v102, v103
	v_or_b32_e32 v101, v101, v102
	v_lshl_add_u64 v[102:103], v[108:109], 2, s[20:21]
	global_store_dwordx4 v[102:103], v[98:101], off
	v_pk_mul_f32 v[108:109], v[94:95], s[82:83] op_sel_hi:[1,0]
	v_cvt_f16_f32_e32 v94, v94
	v_lshl_add_u64 v[98:99], v[138:139], 0, s[6:7]
	v_lshl_add_u64 v[100:101], v[98:99], 0, v[152:153]
	v_exp_f32_e32 v108, v108
	v_exp_f32_e32 v109, v109
	s_mov_b64 s[6:7], 0x28000
	v_pk_add_f32 v[108:109], v[108:109], 1.0 op_sel_hi:[1,0] neg_lo:[1,0] neg_hi:[1,0]
	s_nop 0
	v_max_f32_e32 v109, 0, v109
	v_max_f32_e32 v108, 0, v108
	v_sqrt_f32_e32 v108, v108
	v_sqrt_f32_e32 v109, v109
	s_waitcnt vmcnt(12) lgkmcnt(0)
; __device__ __forceinline__ float bf_lo(unsigned w) { return __uint_as_float(w << 16); }
; __device__ __forceinline__ float bf_hi(unsigned w) { return __uint_as_float(w & 0xffff0000u); }
;     __device__ __forceinline__ void operator()(const f32x4 (&acc)[2][2][4][2], const Unit& u, int wr, int wc, int fr, int fq) const {
;     ...
;             const f32x4 lv = *(const f32x4*)(lam + c0 + 4 * hf), bav = *(const f32x4*)(b_a + c0 + 4 * hf), biv = *(const f32x4*)(b_i + c0 + 4 * hf);
;             f32x4 sp;
; #pragma unroll
;             for (int j = 0; j < 4; ++j) sp[j] = 8.0f * softplus_neg(lv[j]);
;     ...
;                     const int row = row0 + ai * HALF + m * 16; const size_t off = (size_t)row * D + c0 + 4 * hf;
;                     const u32x2 xw = *(const u32x2*)(xrc + off); const float xr[4] = {bf_lo(xw.x), bf_hi(xw.x), bf_lo(xw.y), bf_hi(xw.y)};
;                     u32x4 w;
; #pragma unroll
;                     for (int j2 = 0; j2 < 2; ++j2) { const int j = 2 * j2;
;                         const f32x2v rp = (f32x2v){acc[ai][0][m][hf][j], acc[ai][0][m][hf][j + 1]} + (f32x2v){bav[j], bav[j + 1]}, ip = (f32x2v){acc[ai][1][m][hf][j], acc[ai][1][m][hf][j + 1]} + (f32x2v){biv[j], biv[j + 1]};
;                         const f32x2v er = rp * (-1.4426950408889634f), ei = ip * (-1.4426950408889634f);
;                         f32x2v tr, ti; tr.x = __builtin_amdgcn_exp2f(er.x); tr.y = __builtin_amdgcn_exp2f(er.y); ti.x = __builtin_amdgcn_exp2f(ei.x); ti.y = __builtin_amdgcn_exp2f(ei.y);
;                         const f32x2v dr = tr + 1.0f, di = ti + 1.0f; f32x2v r, ig; r.x = __builtin_amdgcn_rcpf(dr.x); r.y = __builtin_amdgcn_rcpf(dr.y); ig.x = __builtin_amdgcn_rcpf(di.x); ig.y = __builtin_amdgcn_rcpf(di.y);
;                         const f32x2v la = r * (f32x2v){-sp[j], -sp[j + 1]}, e2 = la * 2.8853900817779268f;
;                         f32x2v a2; a2.x = __builtin_amdgcn_exp2f(e2.x); a2.y = __builtin_amdgcn_exp2f(e2.y);
;                         const f32x2v om = __builtin_elementwise_max(1.0f - a2, (f32x2v){0.f, 0.f}); f32x2v mult; mult.x = __builtin_amdgcn_sqrtf(om.x); mult.y = __builtin_amdgcn_sqrtf(om.y);
;                         const f32x2v bt = (mult * ig) * (f32x2v){xr[j], xr[j + 1]};
;                         w[j] = pack_f16(la.x, bt.x); w[j + 1] = pack_f16(la.y, bt.y); }
;                     *(u32x4*)(AB + off) = w;
	v_lshlrev_b32_e32 v104, 16, v232
	v_and_b32_e32 v105, 0xffff0000, v232
	v_pk_mul_f32 v[90:91], v[90:91], v[108:109]
	v_lshlrev_b32_e32 v102, 16, v233
	v_pk_mul_f32 v[90:91], v[90:91], v[104:105]
	v_and_b32_e32 v103, 0xffff0000, v233
	v_add_u32_e32 v239, 0x48008, v238
	global_load_dwordx2 v[232:233], v239, s[8:9]
	v_cvt_f16_f32_sdwa v90, v90 dst_sel:WORD_1 dst_unused:UNUSED_PAD src0_sel:DWORD
	v_cvt_f16_f32_sdwa v91, v91 dst_sel:WORD_1 dst_unused:UNUSED_PAD src0_sel:DWORD
	v_or_b32_e32 v90, v90, v94
	v_cvt_f16_f32_e32 v94, v95
	v_or_b32_e32 v91, v91, v94
	v_pk_mul_f32 v[94:95], v[96:97], s[88:89] op_sel_hi:[1,0]
	s_nop 0
	v_exp_f32_e32 v94, v94
	v_exp_f32_e32 v95, v95
	s_nop 0
	v_pk_add_f32 v[94:95], v[94:95], 1.0 op_sel_hi:[1,0]
	s_nop 0
	v_rcp_f32_e32 v94, v94
	v_rcp_f32_e32 v95, v95
	s_nop 0
	v_pk_mul_f32 v[94:95], v[94:95], v[132:133]
	s_nop 0
	v_pk_mul_f32 v[96:97], v[94:95], s[82:83] op_sel_hi:[1,0]
	v_cvt_f16_f32_e32 v94, v94
	v_exp_f32_e32 v96, v96
	v_exp_f32_e32 v97, v97
	s_nop 0
	v_pk_add_f32 v[96:97], v[96:97], 1.0 op_sel_hi:[1,0] neg_lo:[1,0] neg_hi:[1,0]
	s_nop 0
	v_max_f32_e32 v97, 0, v97
	v_max_f32_e32 v96, 0, v96
	v_sqrt_f32_e32 v96, v96
	v_sqrt_f32_e32 v97, v97
	s_nop 0
	v_pk_mul_f32 v[92:93], v[92:93], v[96:97]
	s_nop 0
	v_pk_mul_f32 v[92:93], v[92:93], v[102:103]
	s_nop 0
	v_cvt_f16_f32_sdwa v92, v92 dst_sel:WORD_1 dst_unused:UNUSED_PAD src0_sel:DWORD
	v_cvt_f16_f32_sdwa v93, v93 dst_sel:WORD_1 dst_unused:UNUSED_PAD src0_sel:DWORD
	v_or_b32_e32 v92, v92, v94
	v_cvt_f16_f32_e32 v94, v95
	v_or_b32_e32 v93, v93, v94
	v_lshl_add_u64 v[94:95], v[100:101], 2, s[20:21]
	global_store_dwordx4 v[94:95], v[90:93], off
	v_pk_mul_f32 v[100:101], v[78:79], s[82:83] op_sel_hi:[1,0]
	v_cvt_f16_f32_e32 v78, v78
	v_lshl_add_u64 v[90:91], v[138:139], 0, s[6:7]
	v_lshl_add_u64 v[92:93], v[90:91], 0, v[152:153]
	v_exp_f32_e32 v100, v100
	v_exp_f32_e32 v101, v101
	s_mov_b64 s[6:7], 0x2c000
	v_pk_add_f32 v[100:101], v[100:101], 1.0 op_sel_hi:[1,0] neg_lo:[1,0] neg_hi:[1,0]
	s_nop 0
	v_max_f32_e32 v101, 0, v101
	v_max_f32_e32 v100, 0, v100
	v_sqrt_f32_e32 v100, v100
	v_sqrt_f32_e32 v101, v101
	s_waitcnt vmcnt(13) lgkmcnt(0)
	v_lshlrev_b32_e32 v96, 16, v234
	v_and_b32_e32 v97, 0xffff0000, v234
	v_pk_mul_f32 v[74:75], v[74:75], v[100:101]
	v_lshlrev_b32_e32 v94, 16, v235
	v_pk_mul_f32 v[74:75], v[74:75], v[96:97]
	v_and_b32_e32 v95, 0xffff0000, v235
	v_add_u32_e32 v239, 0x50008, v238
	global_load_dwordx2 v[234:235], v239, s[8:9]
	v_cvt_f16_f32_sdwa v74, v74 dst_sel:WORD_1 dst_unused:UNUSED_PAD src0_sel:DWORD
	v_cvt_f16_f32_sdwa v75, v75 dst_sel:WORD_1 dst_unused:UNUSED_PAD src0_sel:DWORD
	v_or_b32_e32 v74, v74, v78
	v_cvt_f16_f32_e32 v78, v79
	v_or_b32_e32 v75, v75, v78
	v_pk_mul_f32 v[78:79], v[80:81], s[88:89] op_sel_hi:[1,0]
	s_nop 0
	v_exp_f32_e32 v78, v78
	v_exp_f32_e32 v79, v79
	s_nop 0
	v_pk_add_f32 v[78:79], v[78:79], 1.0 op_sel_hi:[1,0]
	s_nop 0
	v_rcp_f32_e32 v78, v78
	v_rcp_f32_e32 v79, v79
	s_nop 0
	v_pk_mul_f32 v[78:79], v[78:79], v[132:133]
	s_nop 0
	v_pk_mul_f32 v[80:81], v[78:79], s[82:83] op_sel_hi:[1,0]
	v_cvt_f16_f32_e32 v78, v78
	v_exp_f32_e32 v80, v80
	v_exp_f32_e32 v81, v81
	s_nop 0
	v_pk_add_f32 v[80:81], v[80:81], 1.0 op_sel_hi:[1,0] neg_lo:[1,0] neg_hi:[1,0]
	s_nop 0
	v_max_f32_e32 v81, 0, v81
	v_max_f32_e32 v80, 0, v80
	v_sqrt_f32_e32 v80, v80
	v_sqrt_f32_e32 v81, v81
	s_nop 0
	v_pk_mul_f32 v[76:77], v[76:77], v[80:81]
	s_nop 0
	v_pk_mul_f32 v[76:77], v[76:77], v[94:95]
	s_nop 0
	v_cvt_f16_f32_sdwa v76, v76 dst_sel:WORD_1 dst_unused:UNUSED_PAD src0_sel:DWORD
	v_cvt_f16_f32_sdwa v77, v77 dst_sel:WORD_1 dst_unused:UNUSED_PAD src0_sel:DWORD
	v_or_b32_e32 v76, v76, v78
	v_cvt_f16_f32_e32 v78, v79
	v_or_b32_e32 v77, v77, v78
	v_lshl_add_u64 v[78:79], v[92:93], 2, s[20:21]
	global_store_dwordx4 v[78:79], v[74:77], off
	v_lshl_add_u64 v[78:79], v[138:139], 0, s[6:7]
	s_nop 0
	v_lshl_add_u64 v[74:75], v[78:79], 0, v[152:153]
	s_waitcnt vmcnt(14) lgkmcnt(0)
	v_lshlrev_b32_e32 v80, 16, v236
	v_and_b32_e32 v81, 0xffff0000, v236
	v_pk_mul_f32 v[66:67], v[66:67], v[80:81]
	v_lshlrev_b32_e32 v76, 16, v237
	v_cvt_f16_f32_sdwa v66, v66 dst_sel:WORD_1 dst_unused:UNUSED_PAD src0_sel:DWORD
	v_cvt_f16_f32_sdwa v67, v67 dst_sel:WORD_1 dst_unused:UNUSED_PAD src0_sel:DWORD
	v_and_b32_e32 v77, 0xffff0000, v237
	v_add_u32_e32 v239, 0x58008, v238
	global_load_dwordx2 v[236:237], v239, s[8:9]
	v_or_b32_e32 v66, v66, v70
	v_cvt_f16_f32_e32 v70, v71
	v_or_b32_e32 v67, v67, v70
	v_pk_mul_f32 v[70:71], v[72:73], s[88:89] op_sel_hi:[1,0]
	s_nop 0
	v_exp_f32_e32 v70, v70
	v_exp_f32_e32 v71, v71
	s_nop 0
	v_pk_add_f32 v[70:71], v[70:71], 1.0 op_sel_hi:[1,0]
	s_nop 0
	v_rcp_f32_e32 v70, v70
	v_rcp_f32_e32 v71, v71
	s_nop 0
	v_pk_mul_f32 v[70:71], v[70:71], v[132:133]
	s_nop 0
	v_pk_mul_f32 v[72:73], v[70:71], s[82:83] op_sel_hi:[1,0]
	v_cvt_f16_f32_e32 v70, v70
	v_exp_f32_e32 v72, v72
	v_exp_f32_e32 v73, v73
	s_nop 0
	v_pk_add_f32 v[72:73], v[72:73], 1.0 op_sel_hi:[1,0] neg_lo:[1,0] neg_hi:[1,0]
	s_nop 0
	v_max_f32_e32 v73, 0, v73
	v_max_f32_e32 v72, 0, v72
	v_sqrt_f32_e32 v72, v72
	v_sqrt_f32_e32 v73, v73
	s_nop 0
	v_pk_mul_f32 v[68:69], v[68:69], v[72:73]
	s_nop 0
	v_pk_mul_f32 v[68:69], v[68:69], v[76:77]
	s_nop 0
	v_cvt_f16_f32_sdwa v68, v68 dst_sel:WORD_1 dst_unused:UNUSED_PAD src0_sel:DWORD
	v_cvt_f16_f32_sdwa v69, v69 dst_sel:WORD_1 dst_unused:UNUSED_PAD src0_sel:DWORD
	v_or_b32_e32 v68, v68, v70
	v_cvt_f16_f32_e32 v70, v71
	v_or_b32_e32 v69, v69, v70
	v_lshl_add_u64 v[70:71], v[74:75], 2, s[20:21]
	global_store_dwordx4 v[70:71], v[66:69], off
	v_mov_b32_e32 v74, v176
	v_mov_b32_e32 v75, v177
	v_mov_b32_e32 v76, v178
	v_mov_b32_e32 v77, v179
	v_mov_b32_e32 v70, v180
	v_mov_b32_e32 v71, v181
	v_mov_b32_e32 v72, v182
	v_mov_b32_e32 v73, v183
	v_mov_b32_e32 v66, v184
	v_mov_b32_e32 v67, v185
	v_mov_b32_e32 v68, v186
	v_mov_b32_e32 v69, v187
	v_mul_f32_e32 v74, 0xbfb8aa3b, v74
	v_exp_f32_e32 v74, v74
	s_nop 0
	v_cmp_ngt_f32_e32 vcc, s64, v74
	s_and_saveexec_b64 s[0:1], vcc
	s_xor_b64 s[36:37], exec, s[0:1]
	s_cbranch_execz .LBB0_207
	v_add_f32_e32 v74, 1.0, v74
	v_cmp_gt_f32_e32 vcc, s60, v74
	s_nop 1
	v_cndmask_b32_e64 v80, 0, 32, vcc
	v_ldexp_f32 v74, v74, v80
	v_log_f32_e32 v74, v74
	s_nop 0
	v_mul_f32_e32 v80, 0x3f317217, v74
	v_fma_f32 v80, v74, s65, -v80
	v_fmac_f32_e32 v80, 0x3377d1cf, v74
	v_fmac_f32_e32 v80, 0x3f317217, v74
	v_cmp_lt_f32_e64 s[6:7], |v74|, s66
	s_nop 1
	v_cndmask_b32_e64 v74, v74, v80, s[6:7]
	v_cndmask_b32_e32 v80, 0, v252, vcc
	v_sub_f32_e32 v80, v74, v80

; __device__ __forceinline__ float bf_lo(unsigned w) { return __uint_as_float(w << 16); }
; __device__ __forceinline__ float bf_hi(unsigned w) { return __uint_as_float(w & 0xffff0000u); }
; __device__ __forceinline__ unsigned pack_f16(float lo, float hi) { const _Float16 a = (_Float16)lo, b = (_Float16)hi; return (unsigned)__builtin_bit_cast(unsigned short, a) | ((unsigned)__builtin_bit_cast(unsigned short, b) << 16); }
;     __device__ __forceinline__ void operator()(const f32x4 (&acc)[2][2][4][2], const Unit& u, int wr, int wc, int fr, int fq) const {
;     ...
;                     const int row = row0 + ai * HALF + m * 16; const size_t off = (size_t)row * D + c0 + 4 * hf;
;                     const u32x2 xw = *(const u32x2*)(xrc + off); const float xr[4] = {bf_lo(xw.x), bf_hi(xw.x), bf_lo(xw.y), bf_hi(xw.y)};
;                     u32x4 w;
; #pragma unroll
;                     for (int j2 = 0; j2 < 2; ++j2) { const int j = 2 * j2;
;                         const f32x2v rp = (f32x2v){acc[ai][0][m][hf][j], acc[ai][0][m][hf][j + 1]} + (f32x2v){bav[j], bav[j + 1]}, ip = (f32x2v){acc[ai][1][m][hf][j], acc[ai][1][m][hf][j + 1]} + (f32x2v){biv[j], biv[j + 1]};
;                         const f32x2v er = rp * (-1.4426950408889634f), ei = ip * (-1.4426950408889634f);
;                         f32x2v tr, ti; tr.x = __builtin_amdgcn_exp2f(er.x); tr.y = __builtin_amdgcn_exp2f(er.y); ti.x = __builtin_amdgcn_exp2f(ei.x); ti.y = __builtin_amdgcn_exp2f(ei.y);
;                         const f32x2v dr = tr + 1.0f, di = ti + 1.0f; f32x2v r, ig; r.x = __builtin_amdgcn_rcpf(dr.x); r.y = __builtin_amdgcn_rcpf(dr.y); ig.x = __builtin_amdgcn_rcpf(di.x); ig.y = __builtin_amdgcn_rcpf(di.y);
;                         const f32x2v la = r * (f32x2v){-sp[j], -sp[j + 1]}, e2 = la * 2.8853900817779268f;
;                         f32x2v a2; a2.x = __builtin_amdgcn_exp2f(e2.x); a2.y = __builtin_amdgcn_exp2f(e2.y);
;                         const f32x2v om = __builtin_elementwise_max(1.0f - a2, (f32x2v){0.f, 0.f}); f32x2v mult; mult.x = __builtin_amdgcn_sqrtf(om.x); mult.y = __builtin_amdgcn_sqrtf(om.y);
;                         const f32x2v bt = (mult * ig) * (f32x2v){xr[j], xr[j + 1]};
;                         w[j] = pack_f16(la.x, bt.x); w[j + 1] = pack_f16(la.y, bt.y); }
;                     *(u32x4*)(AB + off) = w;
.LBB0_219:
	s_andn2_saveexec_b64 s[0:1], s[36:37]
	v_fmamk_f32 v75, v76, 0xbe800000, v249
	v_fma_f32 v75, -v76, v75, 0.5
	v_fma_f32 v75, -v76, v75, 1.0
	v_mul_f32_e32 v75, v76, v75
	s_or_b64 exec, exec, s[0:1]
	v_or_b32_e32 v152, 4, v152
	v_lshl_add_u64 v[76:77], v[152:153], 0, v[138:139]
	v_pk_add_f32 v[62:63], v[62:63], v[70:71]
	v_pk_add_f32 v[58:59], v[58:59], v[66:67]
	v_pk_mul_f32 v[62:63], v[62:63], s[88:89] op_sel_hi:[1,0]
	v_pk_mul_f32 v[58:59], v[58:59], s[88:89] op_sel_hi:[1,0]
	v_exp_f32_e32 v62, v62
	v_exp_f32_e32 v63, v63
	v_exp_f32_e32 v58, v58
	v_exp_f32_e32 v59, v59
	s_mov_b32 s0, 0xc1000000
	v_pk_add_f32 v[62:63], v[62:63], 1.0 op_sel_hi:[1,0]
	v_pk_add_f32 v[64:65], v[64:65], v[72:73]
	v_rcp_f32_e32 v62, v62
	v_rcp_f32_e32 v63, v63
	v_pk_add_f32 v[58:59], v[58:59], 1.0 op_sel_hi:[1,0]
	v_pk_mul_f32 v[64:65], v[64:65], s[88:89] op_sel_hi:[1,0]
	v_rcp_f32_e32 v86, v58
	v_rcp_f32_e32 v87, v59
	v_pk_mul_f32 v[58:59], v[80:81], s[0:1] op_sel_hi:[1,0]
	v_exp_f32_e32 v64, v64
	v_pk_mul_f32 v[62:63], v[62:63], v[58:59]
	v_exp_f32_e32 v65, v65
	v_pk_mul_f32 v[80:81], v[62:63], s[82:83] op_sel_hi:[1,0]
	v_cvt_f16_f32_e32 v62, v62
	v_exp_f32_e32 v80, v80
	v_exp_f32_e32 v81, v81
	v_pk_add_f32 v[60:61], v[60:61], v[68:69]
	v_cvt_f16_f32_e32 v63, v63
	v_pk_mul_f32 v[60:61], v[60:61], s[88:89] op_sel_hi:[1,0]
	v_pk_add_f32 v[80:81], v[80:81], 1.0 op_sel_hi:[1,0] neg_lo:[1,0] neg_hi:[1,0]
	v_exp_f32_e32 v60, v60
	v_max_f32_e32 v81, 0, v81
	v_max_f32_e32 v80, 0, v80
	v_sqrt_f32_e32 v80, v80
	v_sqrt_f32_e32 v81, v81
	v_exp_f32_e32 v61, v61
	v_pk_add_f32 v[64:65], v[64:65], 1.0 op_sel_hi:[1,0]
	v_pk_add_f32 v[54:55], v[54:55], v[70:71]
	v_pk_mul_f32 v[80:81], v[86:87], v[80:81]
	v_rcp_f32_e32 v64, v64
	v_rcp_f32_e32 v65, v65
	v_pk_add_f32 v[60:61], v[60:61], 1.0 op_sel_hi:[1,0]
	v_pk_mul_f32 v[54:55], v[54:55], s[88:89] op_sel_hi:[1,0]
	v_pk_add_f32 v[50:51], v[50:51], v[66:67]
	v_exp_f32_e32 v54, v54
	v_exp_f32_e32 v55, v55
	v_pk_mul_f32 v[50:51], v[50:51], s[88:89] op_sel_hi:[1,0]
	v_pk_add_f32 v[56:57], v[56:57], v[72:73]
	v_exp_f32_e32 v50, v50
	v_pk_add_f32 v[54:55], v[54:55], 1.0 op_sel_hi:[1,0]
	v_exp_f32_e32 v51, v51
	v_rcp_f32_e32 v54, v54
	v_rcp_f32_e32 v55, v55
	v_pk_add_f32 v[52:53], v[52:53], v[68:69]
	v_pk_add_f32 v[50:51], v[50:51], 1.0 op_sel_hi:[1,0]
	v_pk_mul_f32 v[52:53], v[52:53], s[88:89] op_sel_hi:[1,0]
	v_pk_mul_f32 v[54:55], v[54:55], v[58:59]
	v_rcp_f32_e32 v50, v50
	v_rcp_f32_e32 v51, v51
	v_exp_f32_e32 v52, v52
	v_exp_f32_e32 v53, v53
	v_pk_add_f32 v[46:47], v[46:47], v[70:71]
	v_pk_add_f32 v[42:43], v[42:43], v[66:67]
	v_pk_mul_f32 v[46:47], v[46:47], s[88:89] op_sel_hi:[1,0]
	v_pk_add_f32 v[52:53], v[52:53], 1.0 op_sel_hi:[1,0]
	v_exp_f32_e32 v46, v46
	v_rcp_f32_e32 v52, v52
	v_rcp_f32_e32 v53, v53
	v_exp_f32_e32 v47, v47
	v_pk_mul_f32 v[42:43], v[42:43], s[88:89] op_sel_hi:[1,0]
	v_pk_add_f32 v[48:49], v[48:49], v[72:73]
	v_exp_f32_e32 v42, v42
	v_pk_add_f32 v[46:47], v[46:47], 1.0 op_sel_hi:[1,0]
	v_exp_f32_e32 v43, v43
	v_rcp_f32_e32 v46, v46
	v_rcp_f32_e32 v47, v47
	v_pk_add_f32 v[44:45], v[44:45], v[68:69]
	v_pk_add_f32 v[42:43], v[42:43], 1.0 op_sel_hi:[1,0]
	v_pk_mul_f32 v[44:45], v[44:45], s[88:89] op_sel_hi:[1,0]
	v_pk_mul_f32 v[46:47], v[46:47], v[58:59]
	s_waitcnt vmcnt(15) lgkmcnt(0)
	v_lshlrev_b32_e32 v84, 16, v222
	v_and_b32_e32 v85, 0xffff0000, v222
	v_pk_mul_f32 v[80:81], v[80:81], v[84:85]
	v_lshlrev_b32_e32 v82, 16, v223
	v_cvt_f16_f32_sdwa v80, v80 dst_sel:WORD_1 dst_unused:UNUSED_PAD src0_sel:DWORD
	v_and_b32_e32 v83, 0xffff0000, v223
	v_rcp_f32_e32 v42, v42
	v_rcp_f32_e32 v43, v43
	v_or_b32_e32 v62, v80, v62
	v_cvt_f16_f32_sdwa v80, v81 dst_sel:WORD_1 dst_unused:UNUSED_PAD src0_sel:DWORD
	v_rcp_f32_e32 v81, v61
	v_exp_f32_e32 v44, v44
	v_exp_f32_e32 v45, v45
	v_or_b32_e32 v63, v80, v63
	v_rcp_f32_e32 v80, v60
	v_pk_mul_f32 v[60:61], v[74:75], s[0:1] op_sel_hi:[1,0]
	v_pk_add_f32 v[44:45], v[44:45], 1.0 op_sel_hi:[1,0]
	v_pk_mul_f32 v[64:65], v[64:65], v[60:61]
	v_rcp_f32_e32 v44, v44
	v_pk_mul_f32 v[74:75], v[64:65], s[82:83] op_sel_hi:[1,0]
	v_cvt_f16_f32_e32 v64, v64
	v_exp_f32_e32 v74, v74
	v_exp_f32_e32 v75, v75
	v_cvt_f16_f32_e32 v65, v65
	v_rcp_f32_e32 v45, v45
	v_pk_add_f32 v[38:39], v[38:39], v[70:71]
	v_pk_add_f32 v[74:75], v[74:75], 1.0 op_sel_hi:[1,0] neg_lo:[1,0] neg_hi:[1,0]
	v_pk_mul_f32 v[38:39], v[38:39], s[88:89] op_sel_hi:[1,0]
	v_max_f32_e32 v75, 0, v75
	v_max_f32_e32 v74, 0, v74
	v_sqrt_f32_e32 v74, v74
	v_sqrt_f32_e32 v75, v75
	v_exp_f32_e32 v38, v38
	v_exp_f32_e32 v39, v39
	v_pk_add_f32 v[34:35], v[34:35], v[66:67]
	v_pk_mul_f32 v[74:75], v[80:81], v[74:75]
	v_pk_mul_f32 v[34:35], v[34:35], s[88:89] op_sel_hi:[1,0]
	v_pk_mul_f32 v[74:75], v[74:75], v[82:83]
	v_pk_add_f32 v[38:39], v[38:39], 1.0 op_sel_hi:[1,0]
	v_cvt_f16_f32_sdwa v74, v74 dst_sel:WORD_1 dst_unused:UNUSED_PAD src0_sel:DWORD
	v_rcp_f32_e32 v38, v38
	v_rcp_f32_e32 v39, v39
	v_exp_f32_e32 v34, v34
	v_or_b32_e32 v64, v74, v64
	v_cvt_f16_f32_sdwa v74, v75 dst_sel:WORD_1 dst_unused:UNUSED_PAD src0_sel:DWORD
	v_pk_mul_f32 v[38:39], v[38:39], v[58:59]
	v_exp_f32_e32 v35, v35
	v_pk_add_f32 v[40:41], v[40:41], v[72:73]
	v_or_b32_e32 v65, v74, v65
	v_lshl_add_u64 v[74:75], v[76:77], 2, s[20:21]
	global_store_dwordx4 v[74:75], v[62:65], off
	v_pk_mul_f32 v[76:77], v[54:55], s[82:83] op_sel_hi:[1,0]
	v_cvt_f16_f32_e32 v54, v54
	v_lshl_add_u64 v[62:63], v[130:131], 0, v[152:153]
	v_exp_f32_e32 v76, v76
	v_exp_f32_e32 v77, v77
	v_pk_add_f32 v[34:35], v[34:35], 1.0 op_sel_hi:[1,0]
	v_pk_add_f32 v[36:37], v[36:37], v[68:69]
	v_rcp_f32_e32 v34, v34
	v_pk_add_f32 v[76:77], v[76:77], 1.0 op_sel_hi:[1,0] neg_lo:[1,0] neg_hi:[1,0]
; __device__ __forceinline__ float bf_lo(unsigned w) { return __uint_as_float(w << 16); }
; __device__ __forceinline__ float bf_hi(unsigned w) { return __uint_as_float(w & 0xffff0000u); }
; __device__ __forceinline__ unsigned pack_f16(float lo, float hi) { const _Float16 a = (_Float16)lo, b = (_Float16)hi; return (unsigned)__builtin_bit_cast(unsigned short, a) | ((unsigned)__builtin_bit_cast(unsigned short, b) << 16); }
;     __device__ __forceinline__ void operator()(const f32x4 (&acc)[2][2][4][2], const Unit& u, int wr, int wc, int fr, int fq) const {
;     ...
;                     const int row = row0 + ai * HALF + m * 16; const size_t off = (size_t)row * D + c0 + 4 * hf;
;                     const u32x2 xw = *(const u32x2*)(xrc + off); const float xr[4] = {bf_lo(xw.x), bf_hi(xw.x), bf_lo(xw.y), bf_hi(xw.y)};
;                     u32x4 w;
; #pragma unroll
;                     for (int j2 = 0; j2 < 2; ++j2) { const int j = 2 * j2;
;                         const f32x2v rp = (f32x2v){acc[ai][0][m][hf][j], acc[ai][0][m][hf][j + 1]} + (f32x2v){bav[j], bav[j + 1]}, ip = (f32x2v){acc[ai][1][m][hf][j], acc[ai][1][m][hf][j + 1]} + (f32x2v){biv[j], biv[j + 1]};
;                         const f32x2v er = rp * (-1.4426950408889634f), ei = ip * (-1.4426950408889634f);
;                         f32x2v tr, ti; tr.x = __builtin_amdgcn_exp2f(er.x); tr.y = __builtin_amdgcn_exp2f(er.y); ti.x = __builtin_amdgcn_exp2f(ei.x); ti.y = __builtin_amdgcn_exp2f(ei.y);
;                         const f32x2v dr = tr + 1.0f, di = ti + 1.0f; f32x2v r, ig; r.x = __builtin_amdgcn_rcpf(dr.x); r.y = __builtin_amdgcn_rcpf(dr.y); ig.x = __builtin_amdgcn_rcpf(di.x); ig.y = __builtin_amdgcn_rcpf(di.y);
;                         const f32x2v la = r * (f32x2v){-sp[j], -sp[j + 1]}, e2 = la * 2.8853900817779268f;
;                         f32x2v a2; a2.x = __builtin_amdgcn_exp2f(e2.x); a2.y = __builtin_amdgcn_exp2f(e2.y);
;                         const f32x2v om = __builtin_elementwise_max(1.0f - a2, (f32x2v){0.f, 0.f}); f32x2v mult; mult.x = __builtin_amdgcn_sqrtf(om.x); mult.y = __builtin_amdgcn_sqrtf(om.y);
;                         const f32x2v bt = (mult * ig) * (f32x2v){xr[j], xr[j + 1]};
;                         w[j] = pack_f16(la.x, bt.x); w[j + 1] = pack_f16(la.y, bt.y); }
;                     *(u32x4*)(AB + off) = w;
	v_rcp_f32_e32 v35, v35
	v_max_f32_e32 v77, 0, v77
	v_max_f32_e32 v76, 0, v76
	v_sqrt_f32_e32 v76, v76
	v_sqrt_f32_e32 v77, v77
	v_pk_mul_f32 v[36:37], v[36:37], s[88:89] op_sel_hi:[1,0]
	v_pk_add_f32 v[30:31], v[30:31], v[70:71]
	v_exp_f32_e32 v36, v36
	v_pk_mul_f32 v[50:51], v[50:51], v[76:77]
	v_exp_f32_e32 v37, v37
	v_pk_mul_f32 v[30:31], v[30:31], s[88:89] op_sel_hi:[1,0]
	v_pk_add_f32 v[26:27], v[26:27], v[66:67]
	v_exp_f32_e32 v30, v30
	v_pk_add_f32 v[36:37], v[36:37], 1.0 op_sel_hi:[1,0]
	v_exp_f32_e32 v31, v31
	v_rcp_f32_e32 v36, v36
	v_rcp_f32_e32 v37, v37
	v_pk_mul_f32 v[26:27], v[26:27], s[88:89] op_sel_hi:[1,0]
	v_pk_add_f32 v[30:31], v[30:31], 1.0 op_sel_hi:[1,0]
	v_exp_f32_e32 v26, v26
	v_rcp_f32_e32 v30, v30
	v_rcp_f32_e32 v31, v31
	v_exp_f32_e32 v27, v27
	v_pk_add_f32 v[32:33], v[32:33], v[72:73]
	v_pk_add_f32 v[28:29], v[28:29], v[68:69]
	v_pk_mul_f32 v[30:31], v[30:31], v[58:59]
	v_pk_add_f32 v[26:27], v[26:27], 1.0 op_sel_hi:[1,0]
	v_pk_mul_f32 v[28:29], v[28:29], s[88:89] op_sel_hi:[1,0]
	v_rcp_f32_e32 v26, v26
	v_rcp_f32_e32 v27, v27
	v_exp_f32_e32 v28, v28
	v_exp_f32_e32 v29, v29
	v_pk_add_f32 v[22:23], v[22:23], v[70:71]
	v_pk_add_f32 v[18:19], v[18:19], v[66:67]
	v_pk_mul_f32 v[22:23], v[22:23], s[88:89] op_sel_hi:[1,0]
	v_pk_add_f32 v[28:29], v[28:29], 1.0 op_sel_hi:[1,0]
	v_exp_f32_e32 v22, v22
	v_rcp_f32_e32 v28, v28
	v_rcp_f32_e32 v29, v29
	v_exp_f32_e32 v23, v23
	v_pk_mul_f32 v[18:19], v[18:19], s[88:89] op_sel_hi:[1,0]
	v_pk_add_f32 v[24:25], v[24:25], v[72:73]
	v_exp_f32_e32 v18, v18
	v_pk_add_f32 v[22:23], v[22:23], 1.0 op_sel_hi:[1,0]
	v_exp_f32_e32 v19, v19
	v_rcp_f32_e32 v22, v22
	v_rcp_f32_e32 v23, v23
	v_pk_add_f32 v[20:21], v[20:21], v[68:69]
	v_pk_add_f32 v[18:19], v[18:19], 1.0 op_sel_hi:[1,0]
	v_pk_mul_f32 v[20:21], v[20:21], s[88:89] op_sel_hi:[1,0]
	v_pk_mul_f32 v[22:23], v[22:23], v[58:59]
	v_rcp_f32_e32 v18, v18
	v_rcp_f32_e32 v19, v19
	v_exp_f32_e32 v20, v20
	v_exp_f32_e32 v21, v21
	v_pk_add_f32 v[14:15], v[14:15], v[70:71]
	v_pk_add_f32 v[10:11], v[10:11], v[66:67]
	v_pk_mul_f32 v[14:15], v[14:15], s[88:89] op_sel_hi:[1,0]
	v_pk_add_f32 v[20:21], v[20:21], 1.0 op_sel_hi:[1,0]
	v_exp_f32_e32 v14, v14
	v_rcp_f32_e32 v20, v20
	v_rcp_f32_e32 v21, v21
	v_exp_f32_e32 v15, v15
	v_pk_mul_f32 v[10:11], v[10:11], s[88:89] op_sel_hi:[1,0]
	v_pk_add_f32 v[16:17], v[16:17], v[72:73]
	v_exp_f32_e32 v10, v10
	v_pk_add_f32 v[14:15], v[14:15], 1.0 op_sel_hi:[1,0]
	v_exp_f32_e32 v11, v11
	v_rcp_f32_e32 v14, v14
	v_rcp_f32_e32 v15, v15
	v_pk_add_f32 v[12:13], v[12:13], v[68:69]
	v_pk_add_f32 v[10:11], v[10:11], 1.0 op_sel_hi:[1,0]
	v_pk_mul_f32 v[12:13], v[12:13], s[88:89] op_sel_hi:[1,0]
	s_waitcnt vmcnt(14) lgkmcnt(0)
	v_lshlrev_b32_e32 v74, 16, v224
	v_and_b32_e32 v75, 0xffff0000, v224
	v_pk_mul_f32 v[50:51], v[50:51], v[74:75]
	v_lshlrev_b32_e32 v64, 16, v225
	v_cvt_f16_f32_sdwa v50, v50 dst_sel:WORD_1 dst_unused:UNUSED_PAD src0_sel:DWORD
	v_cvt_f16_f32_sdwa v51, v51 dst_sel:WORD_1 dst_unused:UNUSED_PAD src0_sel:DWORD
	v_and_b32_e32 v65, 0xffff0000, v225
	v_pk_mul_f32 v[14:15], v[14:15], v[58:59]
	v_or_b32_e32 v50, v50, v54
	v_cvt_f16_f32_e32 v54, v55
	v_rcp_f32_e32 v10, v10
	v_rcp_f32_e32 v11, v11
	v_exp_f32_e32 v12, v12
	v_or_b32_e32 v51, v51, v54
	v_pk_mul_f32 v[54:55], v[56:57], s[88:89] op_sel_hi:[1,0]
	v_exp_f32_e32 v13, v13
	v_exp_f32_e32 v54, v54
	v_exp_f32_e32 v55, v55
	v_pk_add_f32 v[6:7], v[6:7], v[70:71]
	v_pk_add_f32 v[12:13], v[12:13], 1.0 op_sel_hi:[1,0]
	v_pk_mul_f32 v[6:7], v[6:7], s[88:89] op_sel_hi:[1,0]
	v_pk_add_f32 v[54:55], v[54:55], 1.0 op_sel_hi:[1,0]
	v_rcp_f32_e32 v12, v12
	v_rcp_f32_e32 v54, v54
	v_rcp_f32_e32 v55, v55
	v_rcp_f32_e32 v13, v13
	v_exp_f32_e32 v6, v6
	v_exp_f32_e32 v7, v7
	v_pk_mul_f32 v[54:55], v[54:55], v[60:61]
	v_pk_add_f32 v[2:3], v[2:3], v[66:67]
	v_pk_mul_f32 v[56:57], v[54:55], s[82:83] op_sel_hi:[1,0]
	v_cvt_f16_f32_e32 v54, v54
	v_exp_f32_e32 v56, v56
	v_exp_f32_e32 v57, v57
	v_pk_add_f32 v[6:7], v[6:7], 1.0 op_sel_hi:[1,0]
	v_pk_mul_f32 v[2:3], v[2:3], s[88:89] op_sel_hi:[1,0]
	v_rcp_f32_e32 v6, v6
	v_pk_add_f32 v[56:57], v[56:57], 1.0 op_sel_hi:[1,0] neg_lo:[1,0] neg_hi:[1,0]
	v_rcp_f32_e32 v7, v7
	v_max_f32_e32 v57, 0, v57
	v_max_f32_e32 v56, 0, v56
	v_sqrt_f32_e32 v56, v56
	v_sqrt_f32_e32 v57, v57
	v_pk_mul_f32 v[6:7], v[6:7], v[58:59]
	v_exp_f32_e32 v2, v2
	v_exp_f32_e32 v3, v3
	v_pk_mul_f32 v[52:53], v[52:53], v[56:57]
	v_pk_mul_f32 v[56:57], v[46:47], s[82:83] op_sel_hi:[1,0]
	v_pk_mul_f32 v[52:53], v[52:53], v[64:65]
	v_exp_f32_e32 v56, v56
	v_cvt_f16_f32_sdwa v52, v52 dst_sel:WORD_1 dst_unused:UNUSED_PAD src0_sel:DWORD
	v_cvt_f16_f32_sdwa v53, v53 dst_sel:WORD_1 dst_unused:UNUSED_PAD src0_sel:DWORD
	v_exp_f32_e32 v57, v57
	v_cvt_f16_f32_e32 v46, v46
	v_or_b32_e32 v52, v52, v54
	v_cvt_f16_f32_e32 v54, v55
	v_pk_add_f32 v[56:57], v[56:57], 1.0 op_sel_hi:[1,0] neg_lo:[1,0] neg_hi:[1,0]
	v_pk_add_f32 v[2:3], v[2:3], 1.0 op_sel_hi:[1,0]
	v_max_f32_e32 v57, 0, v57
	v_or_b32_e32 v53, v53, v54
	v_lshl_add_u64 v[54:55], v[62:63], 2, s[20:21]
	global_store_dwordx4 v[54:55], v[50:53], off
	v_max_f32_e32 v56, 0, v56
	v_sqrt_f32_e32 v56, v56
	v_lshl_add_u64 v[50:51], v[122:123], 0, v[152:153]
	v_sqrt_f32_e32 v57, v57
	v_rcp_f32_e32 v2, v2
	v_rcp_f32_e32 v3, v3
	v_pk_add_f32 v[8:9], v[8:9], v[72:73]
	v_pk_mul_f32 v[42:43], v[42:43], v[56:57]
	v_pk_add_f32 v[4:5], v[4:5], v[68:69]
	s_movk_i32 s0, 0x1000
	v_pk_mul_f32 v[4:5], v[4:5], s[88:89] op_sel_hi:[1,0]
	s_mov_b64 s[6:7], -1
	v_exp_f32_e32 v4, v4
	v_exp_f32_e32 v5, v5
	s_waitcnt vmcnt(13) lgkmcnt(0)
; __device__ __forceinline__ float bf_lo(unsigned w) { return __uint_as_float(w << 16); }
; __device__ __forceinline__ float bf_hi(unsigned w) { return __uint_as_float(w & 0xffff0000u); }
; __device__ __forceinline__ unsigned pack_f16(float lo, float hi) { const _Float16 a = (_Float16)lo, b = (_Float16)hi; return (unsigned)__builtin_bit_cast(unsigned short, a) | ((unsigned)__builtin_bit_cast(unsigned short, b) << 16); }
;     __device__ __forceinline__ void operator()(const f32x4 (&acc)[2][2][4][2], const Unit& u, int wr, int wc, int fr, int fq) const {
;     ...
;                     const int row = row0 + ai * HALF + m * 16; const size_t off = (size_t)row * D + c0 + 4 * hf;
;                     const u32x2 xw = *(const u32x2*)(xrc + off); const float xr[4] = {bf_lo(xw.x), bf_hi(xw.x), bf_lo(xw.y), bf_hi(xw.y)};
;                     u32x4 w;
; #pragma unroll
;                     for (int j2 = 0; j2 < 2; ++j2) { const int j = 2 * j2;
;                         const f32x2v rp = (f32x2v){acc[ai][0][m][hf][j], acc[ai][0][m][hf][j + 1]} + (f32x2v){bav[j], bav[j + 1]}, ip = (f32x2v){acc[ai][1][m][hf][j], acc[ai][1][m][hf][j + 1]} + (f32x2v){biv[j], biv[j + 1]};
;                         const f32x2v er = rp * (-1.4426950408889634f), ei = ip * (-1.4426950408889634f);
;                         f32x2v tr, ti; tr.x = __builtin_amdgcn_exp2f(er.x); tr.y = __builtin_amdgcn_exp2f(er.y); ti.x = __builtin_amdgcn_exp2f(ei.x); ti.y = __builtin_amdgcn_exp2f(ei.y);
;                         const f32x2v dr = tr + 1.0f, di = ti + 1.0f; f32x2v r, ig; r.x = __builtin_amdgcn_rcpf(dr.x); r.y = __builtin_amdgcn_rcpf(dr.y); ig.x = __builtin_amdgcn_rcpf(di.x); ig.y = __builtin_amdgcn_rcpf(di.y);
;                         const f32x2v la = r * (f32x2v){-sp[j], -sp[j + 1]}, e2 = la * 2.8853900817779268f;
;                         f32x2v a2; a2.x = __builtin_amdgcn_exp2f(e2.x); a2.y = __builtin_amdgcn_exp2f(e2.y);
;                         const f32x2v om = __builtin_elementwise_max(1.0f - a2, (f32x2v){0.f, 0.f}); f32x2v mult; mult.x = __builtin_amdgcn_sqrtf(om.x); mult.y = __builtin_amdgcn_sqrtf(om.y);
;                         const f32x2v bt = (mult * ig) * (f32x2v){xr[j], xr[j + 1]};
;                         w[j] = pack_f16(la.x, bt.x); w[j + 1] = pack_f16(la.y, bt.y); }
;                     *(u32x4*)(AB + off) = w;
	v_lshlrev_b32_e32 v54, 16, v226
	v_and_b32_e32 v55, 0xffff0000, v226
	v_pk_mul_f32 v[42:43], v[42:43], v[54:55]
	v_lshlrev_b32_e32 v52, 16, v227
	v_cvt_f16_f32_sdwa v42, v42 dst_sel:WORD_1 dst_unused:UNUSED_PAD src0_sel:DWORD
	v_cvt_f16_f32_sdwa v43, v43 dst_sel:WORD_1 dst_unused:UNUSED_PAD src0_sel:DWORD
	v_and_b32_e32 v53, 0xffff0000, v227
	v_pk_add_f32 v[4:5], v[4:5], 1.0 op_sel_hi:[1,0]
	v_or_b32_e32 v42, v42, v46
	v_cvt_f16_f32_e32 v46, v47
	v_rcp_f32_e32 v4, v4
	v_rcp_f32_e32 v5, v5
	v_or_b32_e32 v43, v43, v46
	v_pk_mul_f32 v[46:47], v[48:49], s[88:89] op_sel_hi:[1,0]
	s_nop 0
	v_exp_f32_e32 v46, v46
	v_exp_f32_e32 v47, v47
	s_nop 0
	v_pk_add_f32 v[46:47], v[46:47], 1.0 op_sel_hi:[1,0]
	s_nop 0
	v_rcp_f32_e32 v46, v46
	v_rcp_f32_e32 v47, v47
	s_nop 0
	v_pk_mul_f32 v[46:47], v[46:47], v[60:61]
	s_nop 0
	v_pk_mul_f32 v[48:49], v[46:47], s[82:83] op_sel_hi:[1,0]
	v_cvt_f16_f32_e32 v46, v46
	v_exp_f32_e32 v48, v48
	v_exp_f32_e32 v49, v49
	s_nop 0
	v_pk_add_f32 v[48:49], v[48:49], 1.0 op_sel_hi:[1,0] neg_lo:[1,0] neg_hi:[1,0]
	s_nop 0
	v_max_f32_e32 v49, 0, v49
	v_max_f32_e32 v48, 0, v48
	v_sqrt_f32_e32 v48, v48
	v_sqrt_f32_e32 v49, v49
	s_nop 0
	v_pk_mul_f32 v[44:45], v[44:45], v[48:49]
	s_nop 0
	v_pk_mul_f32 v[44:45], v[44:45], v[52:53]
	v_pk_mul_f32 v[48:49], v[38:39], s[82:83] op_sel_hi:[1,0]
	v_cvt_f16_f32_sdwa v44, v44 dst_sel:WORD_1 dst_unused:UNUSED_PAD src0_sel:DWORD
	v_cvt_f16_f32_sdwa v45, v45 dst_sel:WORD_1 dst_unused:UNUSED_PAD src0_sel:DWORD
	v_exp_f32_e32 v48, v48
	v_exp_f32_e32 v49, v49
	v_or_b32_e32 v44, v44, v46
	v_cvt_f16_f32_e32 v46, v47
	v_cvt_f16_f32_e32 v38, v38
	v_pk_add_f32 v[48:49], v[48:49], 1.0 op_sel_hi:[1,0] neg_lo:[1,0] neg_hi:[1,0]
	v_or_b32_e32 v45, v45, v46
	v_lshl_add_u64 v[46:47], v[50:51], 2, s[20:21]
	global_store_dwordx4 v[46:47], v[42:45], off
	v_max_f32_e32 v49, 0, v49
	v_max_f32_e32 v48, 0, v48
	v_lshl_add_u64 v[42:43], v[114:115], 0, v[152:153]
	v_sqrt_f32_e32 v48, v48
	v_sqrt_f32_e32 v49, v49
	s_waitcnt vmcnt(12) lgkmcnt(0)
	v_lshlrev_b32_e32 v46, 16, v228
	v_and_b32_e32 v47, 0xffff0000, v228
	v_pk_mul_f32 v[34:35], v[34:35], v[48:49]
	v_lshlrev_b32_e32 v44, 16, v229
	v_pk_mul_f32 v[34:35], v[34:35], v[46:47]
	v_and_b32_e32 v45, 0xffff0000, v229
	v_cvt_f16_f32_sdwa v34, v34 dst_sel:WORD_1 dst_unused:UNUSED_PAD src0_sel:DWORD
	v_cvt_f16_f32_sdwa v35, v35 dst_sel:WORD_1 dst_unused:UNUSED_PAD src0_sel:DWORD
	v_or_b32_e32 v34, v34, v38
	v_cvt_f16_f32_e32 v38, v39
	v_or_b32_e32 v35, v35, v38
	v_pk_mul_f32 v[38:39], v[40:41], s[88:89] op_sel_hi:[1,0]
	s_nop 0
	v_exp_f32_e32 v38, v38
	v_exp_f32_e32 v39, v39
	s_nop 0
	v_pk_add_f32 v[38:39], v[38:39], 1.0 op_sel_hi:[1,0]
	s_nop 0
	v_rcp_f32_e32 v38, v38
	v_rcp_f32_e32 v39, v39
	s_nop 0
	v_pk_mul_f32 v[38:39], v[38:39], v[60:61]
	s_nop 0
	v_pk_mul_f32 v[40:41], v[38:39], s[82:83] op_sel_hi:[1,0]
	v_cvt_f16_f32_e32 v38, v38
	v_exp_f32_e32 v40, v40
	v_exp_f32_e32 v41, v41
	s_nop 0
	v_pk_add_f32 v[40:41], v[40:41], 1.0 op_sel_hi:[1,0] neg_lo:[1,0] neg_hi:[1,0]
	s_nop 0
	v_max_f32_e32 v41, 0, v41
	v_max_f32_e32 v40, 0, v40
	v_sqrt_f32_e32 v40, v40
	v_sqrt_f32_e32 v41, v41
	s_nop 0
	v_pk_mul_f32 v[36:37], v[36:37], v[40:41]
	s_nop 0
	v_pk_mul_f32 v[36:37], v[36:37], v[44:45]
	v_pk_mul_f32 v[40:41], v[30:31], s[82:83] op_sel_hi:[1,0]
	v_cvt_f16_f32_sdwa v36, v36 dst_sel:WORD_1 dst_unused:UNUSED_PAD src0_sel:DWORD
	v_cvt_f16_f32_sdwa v37, v37 dst_sel:WORD_1 dst_unused:UNUSED_PAD src0_sel:DWORD
	v_exp_f32_e32 v40, v40
	v_exp_f32_e32 v41, v41
	v_or_b32_e32 v36, v36, v38
	v_cvt_f16_f32_e32 v38, v39
	v_cvt_f16_f32_e32 v30, v30
	v_pk_add_f32 v[40:41], v[40:41], 1.0 op_sel_hi:[1,0] neg_lo:[1,0] neg_hi:[1,0]
	v_or_b32_e32 v37, v37, v38
	v_lshl_add_u64 v[38:39], v[42:43], 2, s[20:21]
	global_store_dwordx4 v[38:39], v[34:37], off
	v_max_f32_e32 v41, 0, v41
	v_max_f32_e32 v40, 0, v40
	v_lshl_add_u64 v[34:35], v[106:107], 0, v[152:153]
	v_sqrt_f32_e32 v40, v40
	v_sqrt_f32_e32 v41, v41
	s_waitcnt vmcnt(11) lgkmcnt(0)
	v_lshlrev_b32_e32 v38, 16, v230
	v_and_b32_e32 v39, 0xffff0000, v230
	v_pk_mul_f32 v[26:27], v[26:27], v[40:41]
	v_lshlrev_b32_e32 v36, 16, v231
	v_pk_mul_f32 v[26:27], v[26:27], v[38:39]
	v_and_b32_e32 v37, 0xffff0000, v231
	v_cvt_f16_f32_sdwa v26, v26 dst_sel:WORD_1 dst_unused:UNUSED_PAD src0_sel:DWORD
	v_cvt_f16_f32_sdwa v27, v27 dst_sel:WORD_1 dst_unused:UNUSED_PAD src0_sel:DWORD
	v_or_b32_e32 v26, v26, v30
	v_cvt_f16_f32_e32 v30, v31
	v_or_b32_e32 v27, v27, v30
	v_pk_mul_f32 v[30:31], v[32:33], s[88:89] op_sel_hi:[1,0]
	s_nop 0
	v_exp_f32_e32 v30, v30
	v_exp_f32_e32 v31, v31
	s_nop 0
	v_pk_add_f32 v[30:31], v[30:31], 1.0 op_sel_hi:[1,0]
	s_nop 0
	v_rcp_f32_e32 v30, v30
	v_rcp_f32_e32 v31, v31
	s_nop 0
	v_pk_mul_f32 v[30:31], v[30:31], v[60:61]
	s_nop 0
	v_pk_mul_f32 v[32:33], v[30:31], s[82:83] op_sel_hi:[1,0]
	v_cvt_f16_f32_e32 v30, v30
	v_exp_f32_e32 v32, v32
	v_exp_f32_e32 v33, v33
	s_nop 0
	v_pk_add_f32 v[32:33], v[32:33], 1.0 op_sel_hi:[1,0] neg_lo:[1,0] neg_hi:[1,0]
	s_nop 0
	v_max_f32_e32 v33, 0, v33
	v_max_f32_e32 v32, 0, v32
	v_sqrt_f32_e32 v32, v32
	v_sqrt_f32_e32 v33, v33
	s_nop 0
	v_pk_mul_f32 v[28:29], v[28:29], v[32:33]
	s_nop 0
	v_pk_mul_f32 v[28:29], v[28:29], v[36:37]
	v_pk_mul_f32 v[32:33], v[22:23], s[82:83] op_sel_hi:[1,0]
	v_cvt_f16_f32_sdwa v28, v28 dst_sel:WORD_1 dst_unused:UNUSED_PAD src0_sel:DWORD
	v_cvt_f16_f32_sdwa v29, v29 dst_sel:WORD_1 dst_unused:UNUSED_PAD src0_sel:DWORD
	v_exp_f32_e32 v32, v32
	v_exp_f32_e32 v33, v33
	v_or_b32_e32 v28, v28, v30
	v_cvt_f16_f32_e32 v30, v31
	v_cvt_f16_f32_e32 v22, v22
	v_pk_add_f32 v[32:33], v[32:33], 1.0 op_sel_hi:[1,0] neg_lo:[1,0] neg_hi:[1,0]
	v_or_b32_e32 v29, v29, v30
	v_lshl_add_u64 v[30:31], v[34:35], 2, s[20:21]
	global_store_dwordx4 v[30:31], v[26:29], off
	v_max_f32_e32 v33, 0, v33
	v_max_f32_e32 v32, 0, v32
	v_lshl_add_u64 v[26:27], v[98:99], 0, v[152:153]
	v_sqrt_f32_e32 v32, v32
	v_sqrt_f32_e32 v33, v33
	s_waitcnt vmcnt(10) lgkmcnt(0)
; __device__ __forceinline__ float bf_lo(unsigned w) { return __uint_as_float(w << 16); }
; __device__ __forceinline__ float bf_hi(unsigned w) { return __uint_as_float(w & 0xffff0000u); }
;     __device__ __forceinline__ void operator()(const f32x4 (&acc)[2][2][4][2], const Unit& u, int wr, int wc, int fr, int fq) const {
;     ...
;                     const int row = row0 + ai * HALF + m * 16; const size_t off = (size_t)row * D + c0 + 4 * hf;
;                     const u32x2 xw = *(const u32x2*)(xrc + off); const float xr[4] = {bf_lo(xw.x), bf_hi(xw.x), bf_lo(xw.y), bf_hi(xw.y)};
;                     u32x4 w;
; #pragma unroll
;                     for (int j2 = 0; j2 < 2; ++j2) { const int j = 2 * j2;
;                         const f32x2v rp = (f32x2v){acc[ai][0][m][hf][j], acc[ai][0][m][hf][j + 1]} + (f32x2v){bav[j], bav[j + 1]}, ip = (f32x2v){acc[ai][1][m][hf][j], acc[ai][1][m][hf][j + 1]} + (f32x2v){biv[j], biv[j + 1]};
;                         const f32x2v er = rp * (-1.4426950408889634f), ei = ip * (-1.4426950408889634f);
;                         f32x2v tr, ti; tr.x = __builtin_amdgcn_exp2f(er.x); tr.y = __builtin_amdgcn_exp2f(er.y); ti.x = __builtin_amdgcn_exp2f(ei.x); ti.y = __builtin_amdgcn_exp2f(ei.y);
;                         const f32x2v dr = tr + 1.0f, di = ti + 1.0f; f32x2v r, ig; r.x = __builtin_amdgcn_rcpf(dr.x); r.y = __builtin_amdgcn_rcpf(dr.y); ig.x = __builtin_amdgcn_rcpf(di.x); ig.y = __builtin_amdgcn_rcpf(di.y);
;                         const f32x2v la = r * (f32x2v){-sp[j], -sp[j + 1]}, e2 = la * 2.8853900817779268f;
;                         f32x2v a2; a2.x = __builtin_amdgcn_exp2f(e2.x); a2.y = __builtin_amdgcn_exp2f(e2.y);
;                         const f32x2v om = __builtin_elementwise_max(1.0f - a2, (f32x2v){0.f, 0.f}); f32x2v mult; mult.x = __builtin_amdgcn_sqrtf(om.x); mult.y = __builtin_amdgcn_sqrtf(om.y);
;                         const f32x2v bt = (mult * ig) * (f32x2v){xr[j], xr[j + 1]};
;                         w[j] = pack_f16(la.x, bt.x); w[j + 1] = pack_f16(la.y, bt.y); }
;                     *(u32x4*)(AB + off) = w;
;                     asm volatile("" ::: "memory");
;                 }
;         }
;         asm volatile("s_waitcnt vmcnt(0)" ::: "memory"); __builtin_amdgcn_s_barrier(); asm volatile("" ::: "memory");
	v_lshlrev_b32_e32 v30, 16, v232
	v_and_b32_e32 v31, 0xffff0000, v232
	v_pk_mul_f32 v[18:19], v[18:19], v[32:33]
	v_lshlrev_b32_e32 v28, 16, v233
	v_pk_mul_f32 v[18:19], v[18:19], v[30:31]
	v_and_b32_e32 v29, 0xffff0000, v233
	v_cvt_f16_f32_sdwa v18, v18 dst_sel:WORD_1 dst_unused:UNUSED_PAD src0_sel:DWORD
	v_cvt_f16_f32_sdwa v19, v19 dst_sel:WORD_1 dst_unused:UNUSED_PAD src0_sel:DWORD
	v_or_b32_e32 v18, v18, v22
	v_cvt_f16_f32_e32 v22, v23
	v_or_b32_e32 v19, v19, v22
	v_pk_mul_f32 v[22:23], v[24:25], s[88:89] op_sel_hi:[1,0]
	s_nop 0
	v_exp_f32_e32 v22, v22
	v_exp_f32_e32 v23, v23
	s_nop 0
	v_pk_add_f32 v[22:23], v[22:23], 1.0 op_sel_hi:[1,0]
	s_nop 0
	v_rcp_f32_e32 v22, v22
	v_rcp_f32_e32 v23, v23
	s_nop 0
	v_pk_mul_f32 v[22:23], v[22:23], v[60:61]
	s_nop 0
	v_pk_mul_f32 v[24:25], v[22:23], s[82:83] op_sel_hi:[1,0]
	v_cvt_f16_f32_e32 v22, v22
	v_exp_f32_e32 v24, v24
	v_exp_f32_e32 v25, v25
	s_nop 0
	v_pk_add_f32 v[24:25], v[24:25], 1.0 op_sel_hi:[1,0] neg_lo:[1,0] neg_hi:[1,0]
	s_nop 0
	v_max_f32_e32 v25, 0, v25
	v_max_f32_e32 v24, 0, v24
	v_sqrt_f32_e32 v24, v24
	v_sqrt_f32_e32 v25, v25
	s_nop 0
	v_pk_mul_f32 v[20:21], v[20:21], v[24:25]
	s_nop 0
	v_pk_mul_f32 v[20:21], v[20:21], v[28:29]
	v_pk_mul_f32 v[24:25], v[14:15], s[82:83] op_sel_hi:[1,0]
	v_cvt_f16_f32_sdwa v20, v20 dst_sel:WORD_1 dst_unused:UNUSED_PAD src0_sel:DWORD
	v_cvt_f16_f32_sdwa v21, v21 dst_sel:WORD_1 dst_unused:UNUSED_PAD src0_sel:DWORD
	v_exp_f32_e32 v24, v24
	v_exp_f32_e32 v25, v25
	v_or_b32_e32 v20, v20, v22
	v_cvt_f16_f32_e32 v22, v23
	v_cvt_f16_f32_e32 v14, v14
	v_pk_add_f32 v[24:25], v[24:25], 1.0 op_sel_hi:[1,0] neg_lo:[1,0] neg_hi:[1,0]
	v_or_b32_e32 v21, v21, v22
	v_lshl_add_u64 v[22:23], v[26:27], 2, s[20:21]
	global_store_dwordx4 v[22:23], v[18:21], off
	v_max_f32_e32 v25, 0, v25
	v_max_f32_e32 v24, 0, v24
	v_lshl_add_u64 v[18:19], v[90:91], 0, v[152:153]
	v_sqrt_f32_e32 v24, v24
	v_sqrt_f32_e32 v25, v25
	s_waitcnt vmcnt(9) lgkmcnt(0)
	v_lshlrev_b32_e32 v22, 16, v234
	v_and_b32_e32 v23, 0xffff0000, v234
	v_pk_mul_f32 v[10:11], v[10:11], v[24:25]
	v_lshlrev_b32_e32 v20, 16, v235
	v_pk_mul_f32 v[10:11], v[10:11], v[22:23]
	v_and_b32_e32 v21, 0xffff0000, v235
	v_cvt_f16_f32_sdwa v10, v10 dst_sel:WORD_1 dst_unused:UNUSED_PAD src0_sel:DWORD
	v_cvt_f16_f32_sdwa v11, v11 dst_sel:WORD_1 dst_unused:UNUSED_PAD src0_sel:DWORD
	v_or_b32_e32 v10, v10, v14
	v_cvt_f16_f32_e32 v14, v15
	v_or_b32_e32 v11, v11, v14
	v_pk_mul_f32 v[14:15], v[16:17], s[88:89] op_sel_hi:[1,0]
	s_nop 0
	v_exp_f32_e32 v14, v14
	v_exp_f32_e32 v15, v15
	s_nop 0
	v_pk_add_f32 v[14:15], v[14:15], 1.0 op_sel_hi:[1,0]
	s_nop 0
	v_rcp_f32_e32 v14, v14
	v_rcp_f32_e32 v15, v15
	s_nop 0
	v_pk_mul_f32 v[14:15], v[14:15], v[60:61]
	s_nop 0
	v_pk_mul_f32 v[16:17], v[14:15], s[82:83] op_sel_hi:[1,0]
	v_cvt_f16_f32_e32 v14, v14
	v_exp_f32_e32 v16, v16
	v_exp_f32_e32 v17, v17
	s_nop 0
	v_pk_add_f32 v[16:17], v[16:17], 1.0 op_sel_hi:[1,0] neg_lo:[1,0] neg_hi:[1,0]
	s_nop 0
	v_max_f32_e32 v17, 0, v17
	v_max_f32_e32 v16, 0, v16
	v_sqrt_f32_e32 v16, v16
	v_sqrt_f32_e32 v17, v17
	s_nop 0
	v_pk_mul_f32 v[12:13], v[12:13], v[16:17]
	s_nop 0
	v_pk_mul_f32 v[12:13], v[12:13], v[20:21]
	v_pk_mul_f32 v[16:17], v[6:7], s[82:83] op_sel_hi:[1,0]
	v_cvt_f16_f32_sdwa v12, v12 dst_sel:WORD_1 dst_unused:UNUSED_PAD src0_sel:DWORD
	v_cvt_f16_f32_sdwa v13, v13 dst_sel:WORD_1 dst_unused:UNUSED_PAD src0_sel:DWORD
	v_exp_f32_e32 v16, v16
	v_exp_f32_e32 v17, v17
	v_or_b32_e32 v12, v12, v14
	v_cvt_f16_f32_e32 v14, v15
	v_cvt_f16_f32_e32 v6, v6
	v_pk_add_f32 v[16:17], v[16:17], 1.0 op_sel_hi:[1,0] neg_lo:[1,0] neg_hi:[1,0]
	v_or_b32_e32 v13, v13, v14
	v_lshl_add_u64 v[14:15], v[18:19], 2, s[20:21]
	global_store_dwordx4 v[14:15], v[10:13], off
	v_max_f32_e32 v17, 0, v17
	v_max_f32_e32 v16, 0, v16
	v_lshl_add_u64 v[10:11], v[78:79], 0, v[152:153]
	v_sqrt_f32_e32 v16, v16
	v_sqrt_f32_e32 v17, v17
	s_waitcnt vmcnt(8) lgkmcnt(0)
	v_lshlrev_b32_e32 v14, 16, v236
	v_and_b32_e32 v15, 0xffff0000, v236
	v_pk_mul_f32 v[2:3], v[2:3], v[16:17]
	v_lshlrev_b32_e32 v12, 16, v237
	v_pk_mul_f32 v[2:3], v[2:3], v[14:15]
	v_and_b32_e32 v13, 0xffff0000, v237
	v_cvt_f16_f32_sdwa v2, v2 dst_sel:WORD_1 dst_unused:UNUSED_PAD src0_sel:DWORD
	v_cvt_f16_f32_sdwa v3, v3 dst_sel:WORD_1 dst_unused:UNUSED_PAD src0_sel:DWORD
	v_or_b32_e32 v2, v2, v6
	v_cvt_f16_f32_e32 v6, v7
	v_or_b32_e32 v3, v3, v6
	v_pk_mul_f32 v[6:7], v[8:9], s[88:89] op_sel_hi:[1,0]
	s_nop 0
	v_exp_f32_e32 v6, v6
	v_exp_f32_e32 v7, v7
	s_nop 0
	v_pk_add_f32 v[6:7], v[6:7], 1.0 op_sel_hi:[1,0]
	s_nop 0
	v_rcp_f32_e32 v6, v6
	v_rcp_f32_e32 v7, v7
	s_nop 0
	v_pk_mul_f32 v[6:7], v[6:7], v[60:61]
	s_nop 0
	v_pk_mul_f32 v[8:9], v[6:7], s[82:83] op_sel_hi:[1,0]
	v_cvt_f16_f32_e32 v6, v6
	v_exp_f32_e32 v8, v8
	v_exp_f32_e32 v9, v9
	s_nop 0
	v_pk_add_f32 v[8:9], v[8:9], 1.0 op_sel_hi:[1,0] neg_lo:[1,0] neg_hi:[1,0]
	s_nop 0
	v_max_f32_e32 v9, 0, v9
	v_max_f32_e32 v8, 0, v8
	v_sqrt_f32_e32 v8, v8
	v_sqrt_f32_e32 v9, v9
	s_nop 0
	v_pk_mul_f32 v[4:5], v[4:5], v[8:9]
	s_nop 0
	v_pk_mul_f32 v[4:5], v[4:5], v[12:13]
	s_nop 0
	v_cvt_f16_f32_sdwa v4, v4 dst_sel:WORD_1 dst_unused:UNUSED_PAD src0_sel:DWORD
	v_cvt_f16_f32_sdwa v5, v5 dst_sel:WORD_1 dst_unused:UNUSED_PAD src0_sel:DWORD
	v_or_b32_e32 v4, v4, v6
	v_cvt_f16_f32_e32 v6, v7
	v_or_b32_e32 v5, v5, v6
	v_lshl_add_u64 v[6:7], v[10:11], 2, s[20:21]
	global_store_dwordx4 v[6:7], v[2:5], off
	s_waitcnt vmcnt(0)
	s_barrier
;     __device__ __forceinline__ void operator()(const f32x4 (&acc)[2][2][4][2], const Unit& u, int wr, int wc, int fr, int fq) const {
;     ...
;         { const int t = (4 * wr + wc) * 64 + fq * 16 + fr, chunk = t >> 7, c = (u.pn >> 1) * 256 + (u.pn & 1) * 128 + (t & 127), r0 = u.pm * BM + chunk * 64;
;           const unsigned* ab = AB + (size_t)r0 * D + c; float h = 0.f, L = 0.f;
; #pragma unroll
;           for (int b4 = 0; b4 < 4; ++b4) { unsigned w[16];
; #pragma unroll
;               for (int i = 0; i < 16; ++i) w[i] = ab[(size_t)(b4 * 16 + i) * D];
	s_nop 0
	v_and_b32_e32 v2, -16, v170
	v_add_u32_e32 v3, s54, v2
	v_and_b32_e32 v2, 0x70, v3
	v_ashrrev_i32_e32 v3, 1, v3
	v_and_b32_e32 v3, 0xffffffc0, v3
	v_add_u32_e32 v4, s39, v3
	v_ashrrev_i32_e32 v5, 31, v4
	v_or3_b32 v2, s38, v2, v171
	v_lshlrev_b64 v[6:7], 12, v[4:5]
	v_lshl_add_u64 v[6:7], s[20:21], 0, v[6:7]
	v_ashrrev_i32_e32 v3, 31, v2
	v_lshl_add_u64 v[6:7], v[2:3], 2, v[6:7]
	v_ashrrev_i32_e32 v4, 6, v4
	s_mov_b32 s98, 0x1000
	s_mov_b32 s99, 0
	v_mov_b64_e32 v[8:9], v[6:7]
	global_load_dword v26, v[8:9], off
	v_lshl_add_u64 v[8:9], v[8:9], 0, s[98:99]
	global_load_dword v27, v[8:9], off
	v_lshl_add_u64 v[8:9], v[8:9], 0, s[98:99]
	global_load_dword v28, v[8:9], off
	v_lshl_add_u64 v[8:9], v[8:9], 0, s[98:99]
	global_load_dword v29, v[8:9], off
	v_lshl_add_u64 v[8:9], v[8:9], 0, s[98:99]
	global_load_dword v30, v[8:9], off
	v_lshl_add_u64 v[8:9], v[8:9], 0, s[98:99]
	global_load_dword v31, v[8:9], off
	v_lshl_add_u64 v[8:9], v[8:9], 0, s[98:99]
	global_load_dword v32, v[8:9], off
	v_lshl_add_u64 v[8:9], v[8:9], 0, s[98:99]
	global_load_dword v33, v[8:9], off
	v_lshl_add_u64 v[8:9], v[8:9], 0, s[98:99]
	global_load_dword v34, v[8:9], off
	v_lshl_add_u64 v[8:9], v[8:9], 0, s[98:99]
	global_load_dword v35, v[8:9], off
	v_lshl_add_u64 v[8:9], v[8:9], 0, s[98:99]
	global_load_dword v36, v[8:9], off
	v_lshl_add_u64 v[8:9], v[8:9], 0, s[98:99]
	global_load_dword v37, v[8:9], off
	v_lshl_add_u64 v[8:9], v[8:9], 0, s[98:99]
	global_load_dword v38, v[8:9], off
	v_lshl_add_u64 v[8:9], v[8:9], 0, s[98:99]
	global_load_dword v39, v[8:9], off
	v_lshl_add_u64 v[8:9], v[8:9], 0, s[98:99]
	global_load_dword v40, v[8:9], off
	v_lshl_add_u64 v[8:9], v[8:9], 0, s[98:99]
	global_load_dword v41, v[8:9], off
	v_lshl_add_u64 v[8:9], v[8:9], 0, s[98:99]
	global_load_dword v42, v[8:9], off
	v_lshl_add_u64 v[8:9], v[8:9], 0, s[98:99]
	global_load_dword v43, v[8:9], off
	v_lshl_add_u64 v[8:9], v[8:9], 0, s[98:99]
	global_load_dword v44, v[8:9], off
	v_lshl_add_u64 v[8:9], v[8:9], 0, s[98:99]
	global_load_dword v45, v[8:9], off
	v_lshl_add_u64 v[8:9], v[8:9], 0, s[98:99]
	global_load_dword v46, v[8:9], off
	v_lshl_add_u64 v[8:9], v[8:9], 0, s[98:99]
	global_load_dword v47, v[8:9], off
	v_lshl_add_u64 v[8:9], v[8:9], 0, s[98:99]
	global_load_dword v48, v[8:9], off
	v_lshl_add_u64 v[8:9], v[8:9], 0, s[98:99]
	global_load_dword v49, v[8:9], off
	v_lshl_add_u64 v[8:9], v[8:9], 0, s[98:99]
	global_load_dword v50, v[8:9], off
	v_lshl_add_u64 v[8:9], v[8:9], 0, s[98:99]
	global_load_dword v51, v[8:9], off
	v_lshl_add_u64 v[8:9], v[8:9], 0, s[98:99]
	global_load_dword v52, v[8:9], off
	v_lshl_add_u64 v[8:9], v[8:9], 0, s[98:99]
	global_load_dword v53, v[8:9], off
	v_lshl_add_u64 v[8:9], v[8:9], 0, s[98:99]
	global_load_dword v54, v[8:9], off
	v_lshl_add_u64 v[8:9], v[8:9], 0, s[98:99]
	global_load_dword v55, v[8:9], off
	v_lshl_add_u64 v[8:9], v[8:9], 0, s[98:99]
	global_load_dword v56, v[8:9], off
	v_lshl_add_u64 v[8:9], v[8:9], 0, s[98:99]
	global_load_dword v57, v[8:9], off
	v_lshl_add_u64 v[8:9], v[8:9], 0, s[98:99]
	global_load_dword v58, v[8:9], off
	v_lshl_add_u64 v[8:9], v[8:9], 0, s[98:99]
	global_load_dword v59, v[8:9], off
	v_lshl_add_u64 v[8:9], v[8:9], 0, s[98:99]
	global_load_dword v60, v[8:9], off
	v_lshl_add_u64 v[8:9], v[8:9], 0, s[98:99]
	global_load_dword v61, v[8:9], off
	v_lshl_add_u64 v[8:9], v[8:9], 0, s[98:99]
	global_load_dword v62, v[8:9], off
	v_lshl_add_u64 v[8:9], v[8:9], 0, s[98:99]
	global_load_dword v63, v[8:9], off
	v_lshl_add_u64 v[8:9], v[8:9], 0, s[98:99]
	global_load_dword v64, v[8:9], off
	v_lshl_add_u64 v[8:9], v[8:9], 0, s[98:99]
	global_load_dword v65, v[8:9], off
	v_lshl_add_u64 v[8:9], v[8:9], 0, s[98:99]
	global_load_dword v66, v[8:9], off
	v_lshl_add_u64 v[8:9], v[8:9], 0, s[98:99]
	global_load_dword v67, v[8:9], off
	v_lshl_add_u64 v[8:9], v[8:9], 0, s[98:99]
	global_load_dword v68, v[8:9], off
	v_lshl_add_u64 v[8:9], v[8:9], 0, s[98:99]
	global_load_dword v69, v[8:9], off
	v_lshl_add_u64 v[8:9], v[8:9], 0, s[98:99]
	global_load_dword v70, v[8:9], off
	v_lshl_add_u64 v[8:9], v[8:9], 0, s[98:99]
	global_load_dword v71, v[8:9], off
	v_lshl_add_u64 v[8:9], v[8:9], 0, s[98:99]
	global_load_dword v72, v[8:9], off
	v_lshl_add_u64 v[8:9], v[8:9], 0, s[98:99]
	global_load_dword v73, v[8:9], off
	v_lshl_add_u64 v[8:9], v[8:9], 0, s[98:99]
	global_load_dword v74, v[8:9], off
	v_lshl_add_u64 v[8:9], v[8:9], 0, s[98:99]
	global_load_dword v75, v[8:9], off
	v_lshl_add_u64 v[8:9], v[8:9], 0, s[98:99]
	global_load_dword v76, v[8:9], off
	v_lshl_add_u64 v[8:9], v[8:9], 0, s[98:99]
	global_load_dword v77, v[8:9], off
	v_lshl_add_u64 v[8:9], v[8:9], 0, s[98:99]
	global_load_dword v78, v[8:9], off
	v_lshl_add_u64 v[8:9], v[8:9], 0, s[98:99]
	global_load_dword v79, v[8:9], off
	v_lshl_add_u64 v[8:9], v[8:9], 0, s[98:99]
	global_load_dword v80, v[8:9], off
	v_lshl_add_u64 v[8:9], v[8:9], 0, s[98:99]
	global_load_dword v81, v[8:9], off
	v_lshl_add_u64 v[8:9], v[8:9], 0, s[98:99]
	global_load_dword v82, v[8:9], off
	v_lshl_add_u64 v[8:9], v[8:9], 0, s[98:99]
	global_load_dword v83, v[8:9], off
	v_lshl_add_u64 v[8:9], v[8:9], 0, s[98:99]
	global_load_dword v84, v[8:9], off
	v_lshl_add_u64 v[8:9], v[8:9], 0, s[98:99]
	global_load_dword v85, v[8:9], off
	v_lshl_add_u64 v[8:9], v[8:9], 0, s[98:99]
	global_load_dword v86, v[8:9], off
	v_lshl_add_u64 v[8:9], v[8:9], 0, s[98:99]
	global_load_dword v87, v[8:9], off
	v_lshl_add_u64 v[8:9], v[8:9], 0, s[98:99]
	global_load_dword v88, v[8:9], off
	v_lshl_add_u64 v[8:9], v[8:9], 0, s[98:99]
	global_load_dword v89, v[8:9], off
	s_waitcnt vmcnt(63)
; __device__ __forceinline__ float f16_lo(unsigned w) { return (float)__builtin_bit_cast(_Float16, (unsigned short)(w & 0xffffu)); }
; __device__ __forceinline__ float f16_hi(unsigned w) { return (float)__builtin_bit_cast(_Float16, (unsigned short)(w >> 16)); }
;     __device__ __forceinline__ void operator()(const f32x4 (&acc)[2][2][4][2], const Unit& u, int wr, int wc, int fr, int fq) const {
;     ...
;           for (int b4 = 0; b4 < 4; ++b4) { unsigned w[16];
; #pragma unroll
;               for (int i = 0; i < 16; ++i) w[i] = ab[(size_t)(b4 * 16 + i) * D];
; #pragma unroll
;               for (int i = 0; i < 16; ++i) { const float la = f16_lo(w[i]); h = __expf(la) * h + f16_hi(w[i]); L += la; } }
	v_cvt_f32_f16_e32 v10, v26
	v_mul_f32_e32 v11, 0x3fb8aa3b, v10
	v_exp_f32_e32 v11, v11
	v_add_f32_e32 v15, 0, v10
	v_fma_mix_f32 v14, v11, 0, v26 op_sel:[0,0,1] op_sel_hi:[0,0,1]
	s_waitcnt vmcnt(62)
	v_cvt_f32_f16_e32 v12, v27
	v_mul_f32_e32 v13, 0x3fb8aa3b, v12
	v_exp_f32_e32 v13, v13
	v_add_f32_e32 v15, v15, v12
	v_fma_mix_f32 v14, v13, v14, v27 op_sel:[0,0,1] op_sel_hi:[0,0,1]
	s_waitcnt vmcnt(61)
	v_cvt_f32_f16_e32 v10, v28
	v_mul_f32_e32 v11, 0x3fb8aa3b, v10
	v_exp_f32_e32 v11, v11
	v_add_f32_e32 v15, v15, v10
	v_fma_mix_f32 v14, v11, v14, v28 op_sel:[0,0,1] op_sel_hi:[0,0,1]
	s_waitcnt vmcnt(60)
	v_cvt_f32_f16_e32 v12, v29
	v_mul_f32_e32 v13, 0x3fb8aa3b, v12
	v_exp_f32_e32 v13, v13
	v_add_f32_e32 v15, v15, v12
	v_fma_mix_f32 v14, v13, v14, v29 op_sel:[0,0,1] op_sel_hi:[0,0,1]
	s_waitcnt vmcnt(59)
	v_cvt_f32_f16_e32 v10, v30
	v_mul_f32_e32 v11, 0x3fb8aa3b, v10
	v_exp_f32_e32 v11, v11
	v_add_f32_e32 v15, v15, v10
	v_fma_mix_f32 v14, v11, v14, v30 op_sel:[0,0,1] op_sel_hi:[0,0,1]
	s_waitcnt vmcnt(58)
	v_cvt_f32_f16_e32 v12, v31
	v_mul_f32_e32 v13, 0x3fb8aa3b, v12
	v_exp_f32_e32 v13, v13
	v_add_f32_e32 v15, v15, v12
	v_fma_mix_f32 v14, v13, v14, v31 op_sel:[0,0,1] op_sel_hi:[0,0,1]
	s_waitcnt vmcnt(57)
	v_cvt_f32_f16_e32 v10, v32
	v_mul_f32_e32 v11, 0x3fb8aa3b, v10
	v_exp_f32_e32 v11, v11
	v_add_f32_e32 v15, v15, v10
	v_fma_mix_f32 v14, v11, v14, v32 op_sel:[0,0,1] op_sel_hi:[0,0,1]
	s_waitcnt vmcnt(56)
	v_cvt_f32_f16_e32 v12, v33
	v_mul_f32_e32 v13, 0x3fb8aa3b, v12
	v_exp_f32_e32 v13, v13
	v_add_f32_e32 v15, v15, v12
	v_fma_mix_f32 v14, v13, v14, v33 op_sel:[0,0,1] op_sel_hi:[0,0,1]
	s_waitcnt vmcnt(55)
	v_cvt_f32_f16_e32 v10, v34
	v_mul_f32_e32 v11, 0x3fb8aa3b, v10
	v_exp_f32_e32 v11, v11
	v_add_f32_e32 v15, v15, v10
	v_fma_mix_f32 v14, v11, v14, v34 op_sel:[0,0,1] op_sel_hi:[0,0,1]
	s_waitcnt vmcnt(54)
	v_cvt_f32_f16_e32 v12, v35
	v_mul_f32_e32 v13, 0x3fb8aa3b, v12
	v_exp_f32_e32 v13, v13
	v_add_f32_e32 v15, v15, v12
	v_fma_mix_f32 v14, v13, v14, v35 op_sel:[0,0,1] op_sel_hi:[0,0,1]
	s_waitcnt vmcnt(53)
	v_cvt_f32_f16_e32 v10, v36
	v_mul_f32_e32 v11, 0x3fb8aa3b, v10
	v_exp_f32_e32 v11, v11
	v_add_f32_e32 v15, v15, v10
	v_fma_mix_f32 v14, v11, v14, v36 op_sel:[0,0,1] op_sel_hi:[0,0,1]
	s_waitcnt vmcnt(52)
	v_cvt_f32_f16_e32 v12, v37
	v_mul_f32_e32 v13, 0x3fb8aa3b, v12
	v_exp_f32_e32 v13, v13
	v_add_f32_e32 v15, v15, v12
	v_fma_mix_f32 v14, v13, v14, v37 op_sel:[0,0,1] op_sel_hi:[0,0,1]
	s_waitcnt vmcnt(51)
	v_cvt_f32_f16_e32 v10, v38
	v_mul_f32_e32 v11, 0x3fb8aa3b, v10
	v_exp_f32_e32 v11, v11
	v_add_f32_e32 v15, v15, v10
	v_fma_mix_f32 v14, v11, v14, v38 op_sel:[0,0,1] op_sel_hi:[0,0,1]
	s_waitcnt vmcnt(50)
	v_cvt_f32_f16_e32 v12, v39
	v_mul_f32_e32 v13, 0x3fb8aa3b, v12
	v_exp_f32_e32 v13, v13
	v_add_f32_e32 v15, v15, v12
	v_fma_mix_f32 v14, v13, v14, v39 op_sel:[0,0,1] op_sel_hi:[0,0,1]
	s_waitcnt vmcnt(49)
	v_cvt_f32_f16_e32 v10, v40
	v_mul_f32_e32 v11, 0x3fb8aa3b, v10
	v_exp_f32_e32 v11, v11
	v_add_f32_e32 v15, v15, v10
	v_fma_mix_f32 v14, v11, v14, v40 op_sel:[0,0,1] op_sel_hi:[0,0,1]
	s_waitcnt vmcnt(48)
	v_cvt_f32_f16_e32 v12, v41
	v_mul_f32_e32 v13, 0x3fb8aa3b, v12
	v_exp_f32_e32 v13, v13
	v_add_f32_e32 v15, v15, v12
	v_fma_mix_f32 v14, v13, v14, v41 op_sel:[0,0,1] op_sel_hi:[0,0,1]
	s_waitcnt vmcnt(47)
	v_cvt_f32_f16_e32 v10, v42
	v_mul_f32_e32 v11, 0x3fb8aa3b, v10
	v_exp_f32_e32 v11, v11
	v_add_f32_e32 v15, v15, v10
	v_fma_mix_f32 v14, v11, v14, v42 op_sel:[0,0,1] op_sel_hi:[0,0,1]
	s_waitcnt vmcnt(46)
	v_cvt_f32_f16_e32 v12, v43
	v_mul_f32_e32 v13, 0x3fb8aa3b, v12
	v_exp_f32_e32 v13, v13
	v_add_f32_e32 v15, v15, v12
	v_fma_mix_f32 v14, v13, v14, v43 op_sel:[0,0,1] op_sel_hi:[0,0,1]
	s_waitcnt vmcnt(45)
	v_cvt_f32_f16_e32 v10, v44
	v_mul_f32_e32 v11, 0x3fb8aa3b, v10
	v_exp_f32_e32 v11, v11
	v_add_f32_e32 v15, v15, v10
	v_fma_mix_f32 v14, v11, v14, v44 op_sel:[0,0,1] op_sel_hi:[0,0,1]
	s_waitcnt vmcnt(44)
	v_cvt_f32_f16_e32 v12, v45
	v_mul_f32_e32 v13, 0x3fb8aa3b, v12
	v_exp_f32_e32 v13, v13
	v_add_f32_e32 v15, v15, v12
	v_fma_mix_f32 v14, v13, v14, v45 op_sel:[0,0,1] op_sel_hi:[0,0,1]
	s_waitcnt vmcnt(43)
	v_cvt_f32_f16_e32 v10, v46
	v_mul_f32_e32 v11, 0x3fb8aa3b, v10
	v_exp_f32_e32 v11, v11
	v_add_f32_e32 v15, v15, v10
	v_fma_mix_f32 v14, v11, v14, v46 op_sel:[0,0,1] op_sel_hi:[0,0,1]
	s_waitcnt vmcnt(42)
	v_cvt_f32_f16_e32 v12, v47
	v_mul_f32_e32 v13, 0x3fb8aa3b, v12
	v_exp_f32_e32 v13, v13
	v_add_f32_e32 v15, v15, v12
	v_fma_mix_f32 v14, v13, v14, v47 op_sel:[0,0,1] op_sel_hi:[0,0,1]
	s_waitcnt vmcnt(41)
	v_cvt_f32_f16_e32 v10, v48
	v_mul_f32_e32 v11, 0x3fb8aa3b, v10
	v_exp_f32_e32 v11, v11
	v_add_f32_e32 v15, v15, v10
	v_fma_mix_f32 v14, v11, v14, v48 op_sel:[0,0,1] op_sel_hi:[0,0,1]
	s_waitcnt vmcnt(40)
	v_cvt_f32_f16_e32 v12, v49
	v_mul_f32_e32 v13, 0x3fb8aa3b, v12
	v_exp_f32_e32 v13, v13
	v_add_f32_e32 v15, v15, v12
	v_fma_mix_f32 v14, v13, v14, v49 op_sel:[0,0,1] op_sel_hi:[0,0,1]
	s_waitcnt vmcnt(39)
	v_cvt_f32_f16_e32 v10, v50
	v_mul_f32_e32 v11, 0x3fb8aa3b, v10
	v_exp_f32_e32 v11, v11
	v_add_f32_e32 v15, v15, v10
	v_fma_mix_f32 v14, v11, v14, v50 op_sel:[0,0,1] op_sel_hi:[0,0,1]
	s_waitcnt vmcnt(38)
	v_cvt_f32_f16_e32 v12, v51
	v_mul_f32_e32 v13, 0x3fb8aa3b, v12
	v_exp_f32_e32 v13, v13
	v_add_f32_e32 v15, v15, v12
	v_fma_mix_f32 v14, v13, v14, v51 op_sel:[0,0,1] op_sel_hi:[0,0,1]
	s_waitcnt vmcnt(37)
	v_cvt_f32_f16_e32 v10, v52
	v_mul_f32_e32 v11, 0x3fb8aa3b, v10
	v_exp_f32_e32 v11, v11
	v_add_f32_e32 v15, v15, v10
	v_fma_mix_f32 v14, v11, v14, v52 op_sel:[0,0,1] op_sel_hi:[0,0,1]
	s_waitcnt vmcnt(36)
	v_cvt_f32_f16_e32 v12, v53
	v_mul_f32_e32 v13, 0x3fb8aa3b, v12
	v_exp_f32_e32 v13, v13
	v_add_f32_e32 v15, v15, v12
	v_fma_mix_f32 v14, v13, v14, v53 op_sel:[0,0,1] op_sel_hi:[0,0,1]
	s_waitcnt vmcnt(35)
; __device__ __forceinline__ float f16_lo(unsigned w) { return (float)__builtin_bit_cast(_Float16, (unsigned short)(w & 0xffffu)); }
; __device__ __forceinline__ float f16_hi(unsigned w) { return (float)__builtin_bit_cast(_Float16, (unsigned short)(w >> 16)); }
;     __device__ __forceinline__ void operator()(const f32x4 (&acc)[2][2][4][2], const Unit& u, int wr, int wc, int fr, int fq) const {
;     ...
;           for (int b4 = 0; b4 < 4; ++b4) { unsigned w[16];
; #pragma unroll
;               for (int i = 0; i < 16; ++i) w[i] = ab[(size_t)(b4 * 16 + i) * D];
; #pragma unroll
;               for (int i = 0; i < 16; ++i) { const float la = f16_lo(w[i]); h = __expf(la) * h + f16_hi(w[i]); L += la; } }
	v_cvt_f32_f16_e32 v10, v54
	v_mul_f32_e32 v11, 0x3fb8aa3b, v10
	v_exp_f32_e32 v11, v11
	v_add_f32_e32 v15, v15, v10
	v_fma_mix_f32 v14, v11, v14, v54 op_sel:[0,0,1] op_sel_hi:[0,0,1]
	s_waitcnt vmcnt(34)
	v_cvt_f32_f16_e32 v12, v55
	v_mul_f32_e32 v13, 0x3fb8aa3b, v12
	v_exp_f32_e32 v13, v13
	v_add_f32_e32 v15, v15, v12
	v_fma_mix_f32 v14, v13, v14, v55 op_sel:[0,0,1] op_sel_hi:[0,0,1]
	s_waitcnt vmcnt(33)
	v_cvt_f32_f16_e32 v10, v56
	v_mul_f32_e32 v11, 0x3fb8aa3b, v10
	v_exp_f32_e32 v11, v11
	v_add_f32_e32 v15, v15, v10
	v_fma_mix_f32 v14, v11, v14, v56 op_sel:[0,0,1] op_sel_hi:[0,0,1]
	s_waitcnt vmcnt(32)
	v_cvt_f32_f16_e32 v12, v57
	v_mul_f32_e32 v13, 0x3fb8aa3b, v12
	v_exp_f32_e32 v13, v13
	v_add_f32_e32 v15, v15, v12
	v_fma_mix_f32 v14, v13, v14, v57 op_sel:[0,0,1] op_sel_hi:[0,0,1]
	s_waitcnt vmcnt(31)
	v_cvt_f32_f16_e32 v10, v58
	v_mul_f32_e32 v11, 0x3fb8aa3b, v10
	v_exp_f32_e32 v11, v11
	v_add_f32_e32 v15, v15, v10
	v_fma_mix_f32 v14, v11, v14, v58 op_sel:[0,0,1] op_sel_hi:[0,0,1]
	s_waitcnt vmcnt(30)
	v_cvt_f32_f16_e32 v12, v59
	v_mul_f32_e32 v13, 0x3fb8aa3b, v12
	v_exp_f32_e32 v13, v13
	v_add_f32_e32 v15, v15, v12
	v_fma_mix_f32 v14, v13, v14, v59 op_sel:[0,0,1] op_sel_hi:[0,0,1]
	s_waitcnt vmcnt(29)
	v_cvt_f32_f16_e32 v10, v60
	v_mul_f32_e32 v11, 0x3fb8aa3b, v10
	v_exp_f32_e32 v11, v11
	v_add_f32_e32 v15, v15, v10
	v_fma_mix_f32 v14, v11, v14, v60 op_sel:[0,0,1] op_sel_hi:[0,0,1]
	s_waitcnt vmcnt(28)
	v_cvt_f32_f16_e32 v12, v61
	v_mul_f32_e32 v13, 0x3fb8aa3b, v12
	v_exp_f32_e32 v13, v13
	v_add_f32_e32 v15, v15, v12
	v_fma_mix_f32 v14, v13, v14, v61 op_sel:[0,0,1] op_sel_hi:[0,0,1]
	s_waitcnt vmcnt(27)
	v_cvt_f32_f16_e32 v10, v62
	v_mul_f32_e32 v11, 0x3fb8aa3b, v10
	v_exp_f32_e32 v11, v11
	v_add_f32_e32 v15, v15, v10
	v_fma_mix_f32 v14, v11, v14, v62 op_sel:[0,0,1] op_sel_hi:[0,0,1]
	s_waitcnt vmcnt(26)
	v_cvt_f32_f16_e32 v12, v63
	v_mul_f32_e32 v13, 0x3fb8aa3b, v12
	v_exp_f32_e32 v13, v13
	v_add_f32_e32 v15, v15, v12
	v_fma_mix_f32 v14, v13, v14, v63 op_sel:[0,0,1] op_sel_hi:[0,0,1]
	s_waitcnt vmcnt(25)
	v_cvt_f32_f16_e32 v10, v64
	v_mul_f32_e32 v11, 0x3fb8aa3b, v10
	v_exp_f32_e32 v11, v11
	v_add_f32_e32 v15, v15, v10
	v_fma_mix_f32 v14, v11, v14, v64 op_sel:[0,0,1] op_sel_hi:[0,0,1]
	s_waitcnt vmcnt(24)
	v_cvt_f32_f16_e32 v12, v65
	v_mul_f32_e32 v13, 0x3fb8aa3b, v12
	v_exp_f32_e32 v13, v13
	v_add_f32_e32 v15, v15, v12
	v_fma_mix_f32 v14, v13, v14, v65 op_sel:[0,0,1] op_sel_hi:[0,0,1]
	s_waitcnt vmcnt(23)
	v_cvt_f32_f16_e32 v10, v66
	v_mul_f32_e32 v11, 0x3fb8aa3b, v10
	v_exp_f32_e32 v11, v11
	v_add_f32_e32 v15, v15, v10
	v_fma_mix_f32 v14, v11, v14, v66 op_sel:[0,0,1] op_sel_hi:[0,0,1]
	s_waitcnt vmcnt(22)
	v_cvt_f32_f16_e32 v12, v67
	v_mul_f32_e32 v13, 0x3fb8aa3b, v12
	v_exp_f32_e32 v13, v13
	v_add_f32_e32 v15, v15, v12
	v_fma_mix_f32 v14, v13, v14, v67 op_sel:[0,0,1] op_sel_hi:[0,0,1]
	s_waitcnt vmcnt(21)
	v_cvt_f32_f16_e32 v10, v68
	v_mul_f32_e32 v11, 0x3fb8aa3b, v10
	v_exp_f32_e32 v11, v11
	v_add_f32_e32 v15, v15, v10
	v_fma_mix_f32 v14, v11, v14, v68 op_sel:[0,0,1] op_sel_hi:[0,0,1]
	s_waitcnt vmcnt(20)
	v_cvt_f32_f16_e32 v12, v69
	v_mul_f32_e32 v13, 0x3fb8aa3b, v12
	v_exp_f32_e32 v13, v13
	v_add_f32_e32 v15, v15, v12
	v_fma_mix_f32 v14, v13, v14, v69 op_sel:[0,0,1] op_sel_hi:[0,0,1]
	s_waitcnt vmcnt(19)
	v_cvt_f32_f16_e32 v10, v70
	v_mul_f32_e32 v11, 0x3fb8aa3b, v10
	v_exp_f32_e32 v11, v11
	v_add_f32_e32 v15, v15, v10
	v_fma_mix_f32 v14, v11, v14, v70 op_sel:[0,0,1] op_sel_hi:[0,0,1]
	s_waitcnt vmcnt(18)
	v_cvt_f32_f16_e32 v12, v71
	v_mul_f32_e32 v13, 0x3fb8aa3b, v12
	v_exp_f32_e32 v13, v13
	v_add_f32_e32 v15, v15, v12
	v_fma_mix_f32 v14, v13, v14, v71 op_sel:[0,0,1] op_sel_hi:[0,0,1]
	s_waitcnt vmcnt(17)
	v_cvt_f32_f16_e32 v10, v72
	v_mul_f32_e32 v11, 0x3fb8aa3b, v10
	v_exp_f32_e32 v11, v11
	v_add_f32_e32 v15, v15, v10
	v_fma_mix_f32 v14, v11, v14, v72 op_sel:[0,0,1] op_sel_hi:[0,0,1]
	s_waitcnt vmcnt(16)
; __device__ __forceinline__ float f16_lo(unsigned w) { return (float)__builtin_bit_cast(_Float16, (unsigned short)(w & 0xffffu)); }
; __device__ __forceinline__ float f16_hi(unsigned w) { return (float)__builtin_bit_cast(_Float16, (unsigned short)(w >> 16)); }
;     __device__ __forceinline__ void operator()(const f32x4 (&acc)[2][2][4][2], const Unit& u, int wr, int wc, int fr, int fq) const {
;     ...
;           for (int b4 = 0; b4 < 4; ++b4) { unsigned w[16];
; #pragma unroll
;               for (int i = 0; i < 16; ++i) w[i] = ab[(size_t)(b4 * 16 + i) * D];
; #pragma unroll
;               for (int i = 0; i < 16; ++i) { const float la = f16_lo(w[i]); h = __expf(la) * h + f16_hi(w[i]); L += la; } }
;           const size_t o = (size_t)(r0 >> 6) * 1024 + c; Ls[o] = L; Hs[o] = h; }
	v_cvt_f32_f16_e32 v12, v73
	v_mul_f32_e32 v13, 0x3fb8aa3b, v12
	v_exp_f32_e32 v13, v13
	v_add_f32_e32 v15, v15, v12
	v_fma_mix_f32 v14, v13, v14, v73 op_sel:[0,0,1] op_sel_hi:[0,0,1]
	s_waitcnt vmcnt(15)
	v_cvt_f32_f16_e32 v10, v74
	v_mul_f32_e32 v11, 0x3fb8aa3b, v10
	v_exp_f32_e32 v11, v11
	v_add_f32_e32 v15, v15, v10
	v_fma_mix_f32 v14, v11, v14, v74 op_sel:[0,0,1] op_sel_hi:[0,0,1]
	s_waitcnt vmcnt(14)
	v_cvt_f32_f16_e32 v12, v75
	v_mul_f32_e32 v13, 0x3fb8aa3b, v12
	v_exp_f32_e32 v13, v13
	v_add_f32_e32 v15, v15, v12
	v_fma_mix_f32 v14, v13, v14, v75 op_sel:[0,0,1] op_sel_hi:[0,0,1]
	s_waitcnt vmcnt(13)
	v_cvt_f32_f16_e32 v10, v76
	v_mul_f32_e32 v11, 0x3fb8aa3b, v10
	v_exp_f32_e32 v11, v11
	v_add_f32_e32 v15, v15, v10
	v_fma_mix_f32 v14, v11, v14, v76 op_sel:[0,0,1] op_sel_hi:[0,0,1]
	s_waitcnt vmcnt(12)
	v_cvt_f32_f16_e32 v12, v77
	v_mul_f32_e32 v13, 0x3fb8aa3b, v12
	v_exp_f32_e32 v13, v13
	v_add_f32_e32 v15, v15, v12
	v_fma_mix_f32 v14, v13, v14, v77 op_sel:[0,0,1] op_sel_hi:[0,0,1]
	s_waitcnt vmcnt(11)
	v_cvt_f32_f16_e32 v10, v78
	v_mul_f32_e32 v11, 0x3fb8aa3b, v10
	v_exp_f32_e32 v11, v11
	v_add_f32_e32 v15, v15, v10
	v_fma_mix_f32 v14, v11, v14, v78 op_sel:[0,0,1] op_sel_hi:[0,0,1]
	s_waitcnt vmcnt(10)
	v_cvt_f32_f16_e32 v12, v79
	v_mul_f32_e32 v13, 0x3fb8aa3b, v12
	v_exp_f32_e32 v13, v13
	v_add_f32_e32 v15, v15, v12
	v_fma_mix_f32 v14, v13, v14, v79 op_sel:[0,0,1] op_sel_hi:[0,0,1]
	s_waitcnt vmcnt(9)
	v_cvt_f32_f16_e32 v10, v80
	v_mul_f32_e32 v11, 0x3fb8aa3b, v10
	v_exp_f32_e32 v11, v11
	v_add_f32_e32 v15, v15, v10
	v_fma_mix_f32 v14, v11, v14, v80 op_sel:[0,0,1] op_sel_hi:[0,0,1]
	s_waitcnt vmcnt(8)
	v_cvt_f32_f16_e32 v12, v81
	v_mul_f32_e32 v13, 0x3fb8aa3b, v12
	v_exp_f32_e32 v13, v13
	v_add_f32_e32 v15, v15, v12
	v_fma_mix_f32 v14, v13, v14, v81 op_sel:[0,0,1] op_sel_hi:[0,0,1]
	s_waitcnt vmcnt(7)
	v_cvt_f32_f16_e32 v10, v82
	v_mul_f32_e32 v11, 0x3fb8aa3b, v10
	v_exp_f32_e32 v11, v11
	v_add_f32_e32 v15, v15, v10
	v_fma_mix_f32 v14, v11, v14, v82 op_sel:[0,0,1] op_sel_hi:[0,0,1]
	s_waitcnt vmcnt(6)
	v_cvt_f32_f16_e32 v12, v83
	v_mul_f32_e32 v13, 0x3fb8aa3b, v12
	v_exp_f32_e32 v13, v13
	v_add_f32_e32 v15, v15, v12
	v_fma_mix_f32 v14, v13, v14, v83 op_sel:[0,0,1] op_sel_hi:[0,0,1]
	s_waitcnt vmcnt(5)
	v_cvt_f32_f16_e32 v10, v84
	v_mul_f32_e32 v11, 0x3fb8aa3b, v10
	v_exp_f32_e32 v11, v11
	v_add_f32_e32 v15, v15, v10
	v_fma_mix_f32 v14, v11, v14, v84 op_sel:[0,0,1] op_sel_hi:[0,0,1]
	s_waitcnt vmcnt(4)
	v_cvt_f32_f16_e32 v12, v85
	v_mul_f32_e32 v13, 0x3fb8aa3b, v12
	v_exp_f32_e32 v13, v13
	v_add_f32_e32 v15, v15, v12
	v_fma_mix_f32 v14, v13, v14, v85 op_sel:[0,0,1] op_sel_hi:[0,0,1]
	s_waitcnt vmcnt(3)
	v_cvt_f32_f16_e32 v10, v86
	v_mul_f32_e32 v11, 0x3fb8aa3b, v10
	v_exp_f32_e32 v11, v11
	v_add_f32_e32 v15, v15, v10
	v_fma_mix_f32 v14, v11, v14, v86 op_sel:[0,0,1] op_sel_hi:[0,0,1]
	s_waitcnt vmcnt(2)
	v_cvt_f32_f16_e32 v12, v87
	v_mul_f32_e32 v13, 0x3fb8aa3b, v12
	v_exp_f32_e32 v13, v13
	v_add_f32_e32 v15, v15, v12
	v_fma_mix_f32 v14, v13, v14, v87 op_sel:[0,0,1] op_sel_hi:[0,0,1]
	s_waitcnt vmcnt(1)
	v_cvt_f32_f16_e32 v10, v88
	v_mul_f32_e32 v11, 0x3fb8aa3b, v10
	v_exp_f32_e32 v11, v11
	v_add_f32_e32 v15, v15, v10
	v_fma_mix_f32 v14, v11, v14, v88 op_sel:[0,0,1] op_sel_hi:[0,0,1]
	s_waitcnt vmcnt(0)
	v_cvt_f32_f16_e32 v12, v89
	v_mul_f32_e32 v13, 0x3fb8aa3b, v12
	v_exp_f32_e32 v13, v13
	v_add_f32_e32 v15, v15, v12
	v_fma_mix_f32 v14, v13, v14, v89 op_sel:[0,0,1] op_sel_hi:[0,0,1]
	v_mov_b32_e32 v6, v14
	v_mov_b32_e32 v7, v15
	s_mov_b32 s0, 0x3f000
	s_and_b64 vcc, exec, s[4:5]
	v_ashrrev_i32_e32 v5, 31, v4
	v_lshlrev_b64 v[4:5], 10, v[4:5]
	v_lshl_add_u64 v[2:3], v[4:5], 0, v[2:3]
	v_lshlrev_b64 v[2:3], 2, v[2:3]
	v_lshl_add_u64 v[4:5], s[74:75], 0, v[2:3]
	v_lshl_add_u64 v[2:3], s[22:23], 0, v[2:3]
	global_store_dword v[4:5], v7, off
	global_store_dword v[2:3], v6, off
	s_cbranch_vccnz .LBB0_172
	s_andn2_b64 vcc, exec, s[18:19]
	s_cbranch_vccnz .LBB0_171
	s_barrier
	s_branch .LBB0_171

; #define PG8_STAGE(bufoff, gbase, voff) do { _Pragma("unroll") for (int _i = 0; _i < 2; ++_i) \
;         __builtin_amdgcn_global_load_lds((const unsigned*)((const char*)(gbase) + (voff)[_i]), (LAS unsigned*)(lds + (bufoff) + ldsw + _i * 8192), 16, 0, 0); } while (0)
; #define PG8_LDA(dst, b, h) do { _Pragma("unroll") for (int m = 0; m < 4; ++m) _Pragma("unroll") for (int k = 0; k < 2; ++k) dst[m][k] = *(const LAS bf16x8*)(lds + PG8_SA(b, h) + aoff + m * 2048 + k * 1024); } while (0)
; #define PG8_LDB(dst, b, h) do { _Pragma("unroll") for (int n = 0; n < 2; ++n) _Pragma("unroll") for (int k = 0; k < 2; ++k) dst[n][k] = *(const LAS bf16x8*)(lds + PG8_SB(b, h) + boff + n * 2048 + k * 1024); } while (0)
; #define PG8_MMA(ai, bj, At, Bt) do { __builtin_amdgcn_s_setprio(1); _Pragma("unroll") for (int m = 0; m < 4; ++m) _Pragma("unroll") for (int n = 0; n < 2; ++n) _Pragma("unroll") for (int k = 0; k < 2; ++k) \
;         acc[ai][bj][m][n] = __builtin_amdgcn_mfma_f32_16x16x32_bf16(Bt[n][k], At[m][k], acc[ai][bj][m][n], 0, 0, 0); __builtin_amdgcn_s_setprio(0); } while (0)
; #define PG8_WAIT_V(n) asm volatile("s_waitcnt vmcnt(" #n ")" ::: "memory")
; #define PG8_WAIT_L(n) asm volatile("s_waitcnt lgkmcnt(" #n ")" ::: "memory")
; #define PG8_BAR __builtin_amdgcn_s_barrier()
; #define PG8_SCHED __builtin_amdgcn_sched_barrier(0)
; template <class Epi>
; __device__ __forceinline__ void gemm_phase(LAS unsigned char* lds, const Gemm g, const StaticOrder& S, const Epi& E, const int tid) {
;     ...
;         for (int t = 0; t < nt; t += 2) {
;             const bool last = (t == nt - 2);
;             const char* a1 = cA + (size_t)(t + 1) * kstep;
;             const char* a2 = last ? nA : cA + (size_t)(t + 2) * kstep; const char* b2 = last ? nB : cB + (size_t)(t + 2) * kstep;
;             const char* a3 = a2 + kstep; const char* b3 = b2 + kstep;
;             PG8_LDB(B0, 0, 0); PG8_LDB(B1, 0, 1); PG8_SCHED; PG8_LDA(At, 0, 0); PG8_STAGE(PG8_SA(1, 1), a1 + hstepA, voffA);
;             PG8_WAIT_V(8); PG8_WAIT_L(0); PG8_BAR; PG8_MMA(0, 0, At, B0); PG8_MMA(0, 1, At, B1); PG8_BAR; PG8_SCHED;
;             PG8_LDA(At, 0, 1); PG8_STAGE(PG8_SB(0, 0), b2, voffB); PG8_STAGE(PG8_SB(0, 1), b2 + hstepB, voffB); PG8_STAGE(PG8_SA(0, 0), a2, voffA);
;             PG8_WAIT_V(8); PG8_WAIT_L(0); PG8_BAR; PG8_MMA(1, 0, At, B0); PG8_MMA(1, 1, At, B1); PG8_BAR; PG8_SCHED;
.LBB0_296:
	v_mov_b32_e32 v125, 0
	s_andn2_b64 vcc, exec, s[24:25]
	s_cbranch_vccnz .LBB0_300
	s_add_u32 s0, s34, 0x100
	s_addc_u32 s1, s35, 0
	s_add_u32 s6, s36, 0x80
	s_addc_u32 s7, s37, 0
	s_mov_b32 s34, 0
	s_add_i32 s36, s34, 2
	s_add_u32 s37, s6, 0x80
	s_addc_u32 s35, s7, 0
	s_add_i32 s60, 0, 0x10000
	s_cmp_eq_u32 s51, s34
	s_cselect_b32 s35, s29, s35
	s_cselect_b32 s34, s28, s37
	s_cselect_b32 s59, s31, s1
	s_cselect_b32 s58, s30, s0
	s_add_i32 s37, 0, 0x14000
	v_add_u32_e32 v142, s60, v248
	v_add_u32_e32 v158, s37, v248
	ds_read_b128 v[130:133], v142
	ds_read_b128 v[134:137], v142 offset:1024
	ds_read_b128 v[138:141], v142 offset:2048
	ds_read_b128 v[142:145], v142 offset:3072
	ds_read_b128 v[146:149], v158
	ds_read_b128 v[150:153], v158 offset:1024
	ds_read_b128 v[154:157], v158 offset:2048
	ds_read_b128 v[158:161], v158 offset:3072
	v_lshl_add_u64 v[212:213], s[6:7], 0, v[210:211]
	s_add_i32 m0, s38, 0xc000
	ds_read_b128 v[162:165], v194
	ds_read_b128 v[166:169], v194 offset:1024
	ds_read_b128 v[170:173], v194 offset:2048
	ds_read_b128 v[174:177], v194 offset:3072
	ds_read_b128 v[178:181], v194 offset:4096
	ds_read_b128 v[182:185], v194 offset:5120
	ds_read_b128 v[186:189], v194 offset:6144
	ds_read_b128 v[190:193], v194 offset:7168
	global_load_lds_dwordx4 v[212:213], off
	v_lshl_add_u64 v[212:213], s[6:7], 0, v[208:209]
	s_add_i32 m0, s38, 0xe000
	s_nop 0
	global_load_lds_dwordx4 v[212:213], off
	s_waitcnt vmcnt(18)
	s_waitcnt lgkmcnt(0)
	s_barrier
	s_setprio 1
	s_waitcnt lgkmcnt(0)
	v_mfma_f32_16x16x32_bf16 v[122:125], v[130:133], v[162:165], 0
	v_mfma_f32_16x16x32_bf16 v[126:129], v[138:141], v[162:165], 0
	v_mfma_f32_16x16x32_bf16 v[110:113], v[130:133], v[170:173], 0
	v_mfma_f32_16x16x32_bf16 v[106:109], v[138:141], v[170:173], 0
	v_mfma_f32_16x16x32_bf16 v[94:97], v[130:133], v[178:181], 0
	v_mfma_f32_16x16x32_bf16 v[90:93], v[138:141], v[178:181], 0
	v_mfma_f32_16x16x32_bf16 v[78:81], v[130:133], v[186:189], 0
	v_mfma_f32_16x16x32_bf16 v[74:77], v[138:141], v[186:189], 0
	v_mfma_f32_16x16x32_bf16 v[122:125], v[134:137], v[166:169], v[122:125]
	v_mfma_f32_16x16x32_bf16 v[126:129], v[142:145], v[166:169], v[126:129]
	v_mfma_f32_16x16x32_bf16 v[110:113], v[134:137], v[174:177], v[110:113]
	v_mfma_f32_16x16x32_bf16 v[106:109], v[142:145], v[174:177], v[106:109]
	v_mfma_f32_16x16x32_bf16 v[94:97], v[134:137], v[182:185], v[94:97]
	v_mfma_f32_16x16x32_bf16 v[90:93], v[142:145], v[182:185], v[90:93]
	v_mfma_f32_16x16x32_bf16 v[78:81], v[134:137], v[190:193], v[78:81]
	v_mfma_f32_16x16x32_bf16 v[74:77], v[142:145], v[190:193], v[74:77]
	s_setprio 0
	s_setprio 1
	v_mfma_f32_16x16x32_bf16 v[118:121], v[146:149], v[162:165], 0
	v_mfma_f32_16x16x32_bf16 v[114:117], v[154:157], v[162:165], 0
	v_mfma_f32_16x16x32_bf16 v[102:105], v[146:149], v[170:173], 0
	v_mfma_f32_16x16x32_bf16 v[98:101], v[154:157], v[170:173], 0
	v_mfma_f32_16x16x32_bf16 v[86:89], v[146:149], v[178:181], 0
	v_mfma_f32_16x16x32_bf16 v[82:85], v[154:157], v[178:181], 0
	v_mfma_f32_16x16x32_bf16 v[70:73], v[146:149], v[186:189], 0
	v_mfma_f32_16x16x32_bf16 v[66:69], v[154:157], v[186:189], 0
	v_mfma_f32_16x16x32_bf16 v[118:121], v[150:153], v[166:169], v[118:121]
	v_mfma_f32_16x16x32_bf16 v[114:117], v[158:161], v[166:169], v[114:117]
	v_mfma_f32_16x16x32_bf16 v[102:105], v[150:153], v[174:177], v[102:105]
	v_mfma_f32_16x16x32_bf16 v[98:101], v[158:161], v[174:177], v[98:101]
	v_mfma_f32_16x16x32_bf16 v[86:89], v[150:153], v[182:185], v[86:89]
	v_mfma_f32_16x16x32_bf16 v[82:85], v[158:161], v[182:185], v[82:85]
	v_mfma_f32_16x16x32_bf16 v[70:73], v[150:153], v[190:193], v[70:73]
	v_mfma_f32_16x16x32_bf16 v[66:69], v[158:161], v[190:193], v[66:69]
	s_setprio 0
	s_barrier
	s_add_i32 s60, s60, s11
	v_lshl_add_u64 v[212:213], s[58:59], 0, v[0:1]
	s_mov_b32 m0, s60
	ds_read_b128 v[162:165], v194 offset:16384
	ds_read_b128 v[166:169], v194 offset:17408
	ds_read_b128 v[170:173], v194 offset:18432
	ds_read_b128 v[174:177], v194 offset:19456
	ds_read_b128 v[178:181], v194 offset:20480
	ds_read_b128 v[182:185], v194 offset:21504
	ds_read_b128 v[186:189], v194 offset:22528
	ds_read_b128 v[190:193], v194 offset:23552
	global_load_lds_dwordx4 v[212:213], off
	s_add_i32 m0, s60, 0x2000
	v_lshl_add_u64 v[214:215], s[58:59], 0, v[206:207]
	s_add_u32 s58, s58, s14
	s_addc_u32 s59, s59, s15
	s_add_i32 s37, s37, s11
	global_load_lds_dwordx4 v[214:215], off
	v_lshl_add_u64 v[216:217], s[58:59], 0, v[0:1]
	s_mov_b32 m0, s37
	v_lshl_add_u64 v[218:219], s[58:59], 0, v[206:207]
	global_load_lds_dwordx4 v[216:217], off
	s_add_i32 m0, s37, 0x2000
	v_lshl_add_u64 v[220:221], s[34:35], 0, v[202:203]
	global_load_lds_dwordx4 v[218:219], off
	s_mov_b32 m0, s38
	v_lshl_add_u64 v[222:223], s[34:35], 0, v[204:205]
	global_load_lds_dwordx4 v[220:221], off
	s_mov_b32 m0, s39
	s_nop 0
	global_load_lds_dwordx4 v[222:223], off
	s_cmp_eq_u32 s53, 1
	s_cbranch_scc1 .Lkl298_w1f
	s_waitcnt vmcnt(24)
	s_branch .Lkl298_w1j
; #define PG8_STAGE(bufoff, gbase, voff) do { _Pragma("unroll") for (int _i = 0; _i < 2; ++_i) \
;         __builtin_amdgcn_global_load_lds((const unsigned*)((const char*)(gbase) + (voff)[_i]), (LAS unsigned*)(lds + (bufoff) + ldsw + _i * 8192), 16, 0, 0); } while (0)
; #define PG8_LDA(dst, b, h) do { _Pragma("unroll") for (int m = 0; m < 4; ++m) _Pragma("unroll") for (int k = 0; k < 2; ++k) dst[m][k] = *(const LAS bf16x8*)(lds + PG8_SA(b, h) + aoff + m * 2048 + k * 1024); } while (0)
; #define PG8_MMA(ai, bj, At, Bt) do { __builtin_amdgcn_s_setprio(1); _Pragma("unroll") for (int m = 0; m < 4; ++m) _Pragma("unroll") for (int n = 0; n < 2; ++n) _Pragma("unroll") for (int k = 0; k < 2; ++k) \
;         acc[ai][bj][m][n] = __builtin_amdgcn_mfma_f32_16x16x32_bf16(Bt[n][k], At[m][k], acc[ai][bj][m][n], 0, 0, 0); __builtin_amdgcn_s_setprio(0); } while (0)
; #define PG8_WAIT_V(n) asm volatile("s_waitcnt vmcnt(" #n ")" ::: "memory")
; #define PG8_WAIT_L(n) asm volatile("s_waitcnt lgkmcnt(" #n ")" ::: "memory")
; #define PG8_BAR __builtin_amdgcn_s_barrier()
; #define PG8_SCHED __builtin_amdgcn_sched_barrier(0)
; template <class Epi>
; __device__ __forceinline__ void gemm_phase(LAS unsigned char* lds, const Gemm g, const StaticOrder& S, const Epi& E, const int tid) {
;     ...
;             PG8_LDA(At, 0, 1); PG8_STAGE(PG8_SB(0, 0), b2, voffB); PG8_STAGE(PG8_SB(0, 1), b2 + hstepB, voffB); PG8_STAGE(PG8_SA(0, 0), a2, voffA);
;             PG8_WAIT_V(8); PG8_WAIT_L(0); PG8_BAR; PG8_MMA(1, 0, At, B0); PG8_MMA(1, 1, At, B1); PG8_BAR; PG8_SCHED;
.Lkl298_w1f:
	s_waitcnt vmcnt(8)
.Lkl298_w1j:
	s_waitcnt lgkmcnt(0)
	s_barrier
	s_setprio 1
	s_waitcnt lgkmcnt(0)
	v_mfma_f32_16x16x32_bf16 v[62:65], v[130:133], v[162:165], 0
	v_mfma_f32_16x16x32_bf16 v[58:61], v[138:141], v[162:165], 0
	v_mfma_f32_16x16x32_bf16 v[46:49], v[130:133], v[170:173], 0
	v_mfma_f32_16x16x32_bf16 v[42:45], v[138:141], v[170:173], 0
	v_mfma_f32_16x16x32_bf16 v[30:33], v[130:133], v[178:181], 0
	v_mfma_f32_16x16x32_bf16 v[26:29], v[138:141], v[178:181], 0
	v_mfma_f32_16x16x32_bf16 v[14:17], v[130:133], v[186:189], 0
	v_mfma_f32_16x16x32_bf16 v[10:13], v[138:141], v[186:189], 0
	v_mfma_f32_16x16x32_bf16 v[62:65], v[134:137], v[166:169], v[62:65]
	v_mfma_f32_16x16x32_bf16 v[58:61], v[142:145], v[166:169], v[58:61]
	v_mfma_f32_16x16x32_bf16 v[46:49], v[134:137], v[174:177], v[46:49]
	v_mfma_f32_16x16x32_bf16 v[42:45], v[142:145], v[174:177], v[42:45]
	v_mfma_f32_16x16x32_bf16 v[30:33], v[134:137], v[182:185], v[30:33]
	v_mfma_f32_16x16x32_bf16 v[26:29], v[142:145], v[182:185], v[26:29]
	v_mfma_f32_16x16x32_bf16 v[14:17], v[134:137], v[190:193], v[14:17]
	v_mfma_f32_16x16x32_bf16 v[10:13], v[142:145], v[190:193], v[10:13]
	s_setprio 0
	s_setprio 1
	v_mfma_f32_16x16x32_bf16 v[54:57], v[146:149], v[162:165], 0
	v_mfma_f32_16x16x32_bf16 v[50:53], v[154:157], v[162:165], 0
	v_mfma_f32_16x16x32_bf16 v[38:41], v[146:149], v[170:173], 0
	v_mfma_f32_16x16x32_bf16 v[34:37], v[154:157], v[170:173], 0
	v_mfma_f32_16x16x32_bf16 v[22:25], v[146:149], v[178:181], 0
	v_mfma_f32_16x16x32_bf16 v[18:21], v[154:157], v[178:181], 0
	v_mfma_f32_16x16x32_bf16 v[6:9], v[146:149], v[186:189], 0
	v_mfma_f32_16x16x32_bf16 v[2:5], v[154:157], v[186:189], 0
	v_mfma_f32_16x16x32_bf16 v[54:57], v[150:153], v[166:169], v[54:57]
	v_mfma_f32_16x16x32_bf16 v[50:53], v[158:161], v[166:169], v[50:53]
	v_mfma_f32_16x16x32_bf16 v[38:41], v[150:153], v[174:177], v[38:41]
	v_mfma_f32_16x16x32_bf16 v[34:37], v[158:161], v[174:177], v[34:37]
	v_mfma_f32_16x16x32_bf16 v[22:25], v[150:153], v[182:185], v[22:25]
	v_mfma_f32_16x16x32_bf16 v[18:21], v[158:161], v[182:185], v[18:21]
	v_mfma_f32_16x16x32_bf16 v[6:9], v[150:153], v[190:193], v[6:9]
	v_mfma_f32_16x16x32_bf16 v[2:5], v[158:161], v[190:193], v[2:5]
	s_setprio 0
	s_barrier
	s_branch .Lkl298_sp2

; #define PG8_BAR __builtin_amdgcn_s_barrier()
; template <class Epi>
; __device__ __forceinline__ void gemm_phase(LAS unsigned char* lds, const Gemm g, const StaticOrder& S, const Epi& E, const int tid) {
;     ...
;         if (!has_next) break;
; #pragma unroll
;         for (int a = 0; a < 2; ++a)
; #pragma unroll
;             for (int b = 0; b < 2; ++b)
; #pragma unroll
;                 for (int m = 0; m < 4; ++m)
; #pragma unroll
;                     for (int n = 0; n < 2; ++n) acc[a][b][m][n] = (f32x4){0.f, 0.f, 0.f, 0.f};
;         cur = nxt; cA = nA; cB = nB; ++ui;
;         if (wr == 1) PG8_BAR;
.LBB0_318:
	s_waitcnt vmcnt(16)
	s_or_b64 exec, exec, s[0:1]
	s_and_b64 vcc, exec, s[4:5]
	s_mov_b64 s[0:1], -1
	s_cbranch_vccnz .LBB0_285
	s_andn2_b64 vcc, exec, s[20:21]
	s_cbranch_vccnz .LBB0_284
	s_barrier
	s_branch .LBB0_284

; #define PG8_STAGE(bufoff, gbase, voff) do { _Pragma("unroll") for (int _i = 0; _i < 2; ++_i) \
;         __builtin_amdgcn_global_load_lds((const unsigned*)((const char*)(gbase) + (voff)[_i]), (LAS unsigned*)(lds + (bufoff) + ldsw + _i * 8192), 16, 0, 0); } while (0)
; #define PG8_LDA(dst, b, h) do { _Pragma("unroll") for (int m = 0; m < 4; ++m) _Pragma("unroll") for (int k = 0; k < 2; ++k) dst[m][k] = *(const LAS bf16x8*)(lds + PG8_SA(b, h) + aoff + m * 2048 + k * 1024); } while (0)
; #define PG8_LDB(dst, b, h) do { _Pragma("unroll") for (int n = 0; n < 2; ++n) _Pragma("unroll") for (int k = 0; k < 2; ++k) dst[n][k] = *(const LAS bf16x8*)(lds + PG8_SB(b, h) + boff + n * 2048 + k * 1024); } while (0)
; #define PG8_MMA(ai, bj, At, Bt) do { __builtin_amdgcn_s_setprio(1); _Pragma("unroll") for (int m = 0; m < 4; ++m) _Pragma("unroll") for (int n = 0; n < 2; ++n) _Pragma("unroll") for (int k = 0; k < 2; ++k) \
;         acc[ai][bj][m][n] = __builtin_amdgcn_mfma_f32_16x16x32_bf16(Bt[n][k], At[m][k], acc[ai][bj][m][n], 0, 0, 0); __builtin_amdgcn_s_setprio(0); } while (0)
; #define PG8_WAIT_V(n) asm volatile("s_waitcnt vmcnt(" #n ")" ::: "memory")
; #define PG8_WAIT_L(n) asm volatile("s_waitcnt lgkmcnt(" #n ")" ::: "memory")
; #define PG8_BAR __builtin_amdgcn_s_barrier()
; #define PG8_SCHED __builtin_amdgcn_sched_barrier(0)
; template <class Epi>
; __device__ __forceinline__ void gemm_phase(LAS unsigned char* lds, const Gemm g, const StaticOrder& S, const Epi& E, const int tid) {
;     ...
;         for (int t = 0; t < nt; t += 2) {
;             const bool last = (t == nt - 2);
;             const char* a1 = cA + (size_t)(t + 1) * kstep;
;             const char* a2 = last ? nA : cA + (size_t)(t + 2) * kstep; const char* b2 = last ? nB : cB + (size_t)(t + 2) * kstep;
;             const char* a3 = a2 + kstep; const char* b3 = b2 + kstep;
;             PG8_LDB(B0, 0, 0); PG8_LDB(B1, 0, 1); PG8_SCHED; PG8_LDA(At, 0, 0); PG8_STAGE(PG8_SA(1, 1), a1 + hstepA, voffA);
;             PG8_WAIT_V(8); PG8_WAIT_L(0); PG8_BAR; PG8_MMA(0, 0, At, B0); PG8_MMA(0, 1, At, B1); PG8_BAR; PG8_SCHED;
;             PG8_LDA(At, 0, 1); PG8_STAGE(PG8_SB(0, 0), b2, voffB); PG8_STAGE(PG8_SB(0, 1), b2 + hstepB, voffB); PG8_STAGE(PG8_SA(0, 0), a2, voffA);
;             PG8_WAIT_V(8); PG8_WAIT_L(0); PG8_BAR; PG8_MMA(1, 0, At, B0); PG8_MMA(1, 1, At, B1); PG8_BAR; PG8_SCHED;
.LBB0_425:
	v_mov_b32_e32 v145, 0
	s_andn2_b64 vcc, exec, s[48:49]
	s_cbranch_vccnz .LBB0_428
	s_add_u32 s0, s66, 0x100
	s_addc_u32 s1, s67, 0
	s_add_u32 s6, s68, 0x80
	s_addc_u32 s7, s69, 0
	s_mov_b32 s8, 0
	s_add_i32 s10, s8, 2
	s_add_u32 s11, s6, 0x80
	s_addc_u32 s9, s7, 0
	s_add_i32 s66, 0, 0x10000
	s_cmp_eq_u32 s43, s8
	s_cselect_b32 s9, s63, s9
	s_cselect_b32 s8, s62, s11
	s_cselect_b32 s13, s65, s1
	s_cselect_b32 s12, s64, s0
	s_add_i32 s11, 0, 0x14000
	v_add_u32_e32 v78, s66, v222
	v_add_u32_e32 v168, s11, v222
	ds_read_b128 v[66:69], v78
	ds_read_b128 v[70:73], v78 offset:1024
	ds_read_b128 v[74:77], v78 offset:2048
	ds_read_b128 v[78:81], v78 offset:3072
	ds_read_b128 v[156:159], v168
	ds_read_b128 v[160:163], v168 offset:1024
	ds_read_b128 v[164:167], v168 offset:2048
	ds_read_b128 v[168:171], v168 offset:3072
	v_lshl_add_u64 v[210:211], s[6:7], 0, v[154:155]
	s_add_i32 m0, s44, 0xc000
	ds_read_b128 v[172:175], v223
	ds_read_b128 v[176:179], v223 offset:1024
	ds_read_b128 v[180:183], v223 offset:2048
	ds_read_b128 v[184:187], v223 offset:3072
	ds_read_b128 v[188:191], v223 offset:4096
	ds_read_b128 v[192:195], v223 offset:5120
	ds_read_b128 v[202:205], v223 offset:6144
	ds_read_b128 v[206:209], v223 offset:7168
	global_load_lds_dwordx4 v[210:211], off
	v_lshl_add_u64 v[210:211], s[6:7], 0, v[152:153]
	s_add_i32 m0, s44, 0xe000
	s_nop 0
	global_load_lds_dwordx4 v[210:211], off
	s_waitcnt vmcnt(18)
	s_waitcnt lgkmcnt(0)
	s_barrier
	s_setprio 1
	s_waitcnt lgkmcnt(0)
	v_mfma_f32_16x16x32_bf16 v[142:145], v[66:69], v[172:175], 0
	v_mfma_f32_16x16x32_bf16 v[138:141], v[74:77], v[172:175], 0
	v_mfma_f32_16x16x32_bf16 v[126:129], v[66:69], v[180:183], 0
	v_mfma_f32_16x16x32_bf16 v[122:125], v[74:77], v[180:183], 0
	v_mfma_f32_16x16x32_bf16 v[110:113], v[66:69], v[188:191], 0
	v_mfma_f32_16x16x32_bf16 v[106:109], v[74:77], v[188:191], 0
	v_mfma_f32_16x16x32_bf16 v[94:97], v[66:69], v[202:205], 0
	v_mfma_f32_16x16x32_bf16 v[90:93], v[74:77], v[202:205], 0
	v_mfma_f32_16x16x32_bf16 v[142:145], v[70:73], v[176:179], v[142:145]
	v_mfma_f32_16x16x32_bf16 v[138:141], v[78:81], v[176:179], v[138:141]
	v_mfma_f32_16x16x32_bf16 v[126:129], v[70:73], v[184:187], v[126:129]
	v_mfma_f32_16x16x32_bf16 v[122:125], v[78:81], v[184:187], v[122:125]
	v_mfma_f32_16x16x32_bf16 v[110:113], v[70:73], v[192:195], v[110:113]
	v_mfma_f32_16x16x32_bf16 v[106:109], v[78:81], v[192:195], v[106:109]
	v_mfma_f32_16x16x32_bf16 v[94:97], v[70:73], v[206:209], v[94:97]
	v_mfma_f32_16x16x32_bf16 v[90:93], v[78:81], v[206:209], v[90:93]
	s_setprio 0
	s_setprio 1
	v_mfma_f32_16x16x32_bf16 v[134:137], v[156:159], v[172:175], 0
	v_mfma_f32_16x16x32_bf16 v[130:133], v[164:167], v[172:175], 0
	v_mfma_f32_16x16x32_bf16 v[118:121], v[156:159], v[180:183], 0
	v_mfma_f32_16x16x32_bf16 v[114:117], v[164:167], v[180:183], 0
	v_mfma_f32_16x16x32_bf16 v[102:105], v[156:159], v[188:191], 0
	v_mfma_f32_16x16x32_bf16 v[98:101], v[164:167], v[188:191], 0
	v_mfma_f32_16x16x32_bf16 v[86:89], v[156:159], v[202:205], 0
	v_mfma_f32_16x16x32_bf16 v[82:85], v[164:167], v[202:205], 0
	v_mfma_f32_16x16x32_bf16 v[134:137], v[160:163], v[176:179], v[134:137]
	v_mfma_f32_16x16x32_bf16 v[130:133], v[168:171], v[176:179], v[130:133]
	v_mfma_f32_16x16x32_bf16 v[118:121], v[160:163], v[184:187], v[118:121]
	v_mfma_f32_16x16x32_bf16 v[114:117], v[168:171], v[184:187], v[114:117]
	v_mfma_f32_16x16x32_bf16 v[102:105], v[160:163], v[192:195], v[102:105]
	v_mfma_f32_16x16x32_bf16 v[98:101], v[168:171], v[192:195], v[98:101]
	v_mfma_f32_16x16x32_bf16 v[86:89], v[160:163], v[206:209], v[86:89]
	v_mfma_f32_16x16x32_bf16 v[82:85], v[168:171], v[206:209], v[82:85]
	s_setprio 0
	s_barrier
	s_add_i32 s66, s66, s85
	v_lshl_add_u64 v[210:211], s[12:13], 0, v[0:1]
	s_mov_b32 m0, s66
	ds_read_b128 v[172:175], v223 offset:16384
	ds_read_b128 v[176:179], v223 offset:17408
	ds_read_b128 v[180:183], v223 offset:18432
	ds_read_b128 v[184:187], v223 offset:19456
	ds_read_b128 v[188:191], v223 offset:20480
	ds_read_b128 v[192:195], v223 offset:21504
	ds_read_b128 v[202:205], v223 offset:22528
	ds_read_b128 v[206:209], v223 offset:23552
	global_load_lds_dwordx4 v[210:211], off
	s_add_i32 m0, s66, 0x2000
	v_lshl_add_u64 v[212:213], s[12:13], 0, v[150:151]
	s_add_u32 s12, s12, s26
	s_addc_u32 s13, s13, s27
	s_add_i32 s11, s11, s85
	global_load_lds_dwordx4 v[212:213], off
	v_lshl_add_u64 v[214:215], s[12:13], 0, v[0:1]
	s_mov_b32 m0, s11
	v_lshl_add_u64 v[216:217], s[12:13], 0, v[150:151]
	global_load_lds_dwordx4 v[214:215], off
	s_add_i32 m0, s11, 0x2000
	v_lshl_add_u64 v[218:219], s[8:9], 0, v[146:147]
	global_load_lds_dwordx4 v[216:217], off
	s_mov_b32 m0, s44
	v_lshl_add_u64 v[220:221], s[8:9], 0, v[148:149]
	global_load_lds_dwordx4 v[218:219], off
	s_mov_b32 m0, s45
	s_nop 0
	global_load_lds_dwordx4 v[220:221], off
	s_cmp_eq_u32 s42, 1
	s_cbranch_scc1 .Lkl427_w1f
	s_waitcnt vmcnt(24)
	s_branch .Lkl427_w1j

; #define PG8_STAGE(bufoff, gbase, voff) do { _Pragma("unroll") for (int _i = 0; _i < 2; ++_i) \
;         __builtin_amdgcn_global_load_lds((const unsigned*)((const char*)(gbase) + (voff)[_i]), (LAS unsigned*)(lds + (bufoff) + ldsw + _i * 8192), 16, 0, 0); } while (0)
; #define PG8_LDA(dst, b, h) do { _Pragma("unroll") for (int m = 0; m < 4; ++m) _Pragma("unroll") for (int k = 0; k < 2; ++k) dst[m][k] = *(const LAS bf16x8*)(lds + PG8_SA(b, h) + aoff + m * 2048 + k * 1024); } while (0)
; #define PG8_MMA(ai, bj, At, Bt) do { __builtin_amdgcn_s_setprio(1); _Pragma("unroll") for (int m = 0; m < 4; ++m) _Pragma("unroll") for (int n = 0; n < 2; ++n) _Pragma("unroll") for (int k = 0; k < 2; ++k) \
;         acc[ai][bj][m][n] = __builtin_amdgcn_mfma_f32_16x16x32_bf16(Bt[n][k], At[m][k], acc[ai][bj][m][n], 0, 0, 0); __builtin_amdgcn_s_setprio(0); } while (0)
; #define PG8_WAIT_V(n) asm volatile("s_waitcnt vmcnt(" #n ")" ::: "memory")
; #define PG8_WAIT_L(n) asm volatile("s_waitcnt lgkmcnt(" #n ")" ::: "memory")
; #define PG8_BAR __builtin_amdgcn_s_barrier()
; #define PG8_SCHED __builtin_amdgcn_sched_barrier(0)
; template <class Epi>
; __device__ __forceinline__ void gemm_phase(LAS unsigned char* lds, const Gemm g, const StaticOrder& S, const Epi& E, const int tid) {
;     ...
;             PG8_LDA(At, 0, 1); PG8_STAGE(PG8_SB(0, 0), b2, voffB); PG8_STAGE(PG8_SB(0, 1), b2 + hstepB, voffB); PG8_STAGE(PG8_SA(0, 0), a2, voffA);
;             PG8_WAIT_V(8); PG8_WAIT_L(0); PG8_BAR; PG8_MMA(1, 0, At, B0); PG8_MMA(1, 1, At, B1); PG8_BAR; PG8_SCHED;
.Lkl427_w1j:
	s_waitcnt lgkmcnt(0)
	s_barrier
	s_setprio 1
	s_waitcnt lgkmcnt(0)
	v_mfma_f32_16x16x32_bf16 v[62:65], v[66:69], v[172:175], 0
	v_mfma_f32_16x16x32_bf16 v[58:61], v[74:77], v[172:175], 0
	v_mfma_f32_16x16x32_bf16 v[46:49], v[66:69], v[180:183], 0
	v_mfma_f32_16x16x32_bf16 v[42:45], v[74:77], v[180:183], 0
	v_mfma_f32_16x16x32_bf16 v[30:33], v[66:69], v[188:191], 0
	v_mfma_f32_16x16x32_bf16 v[26:29], v[74:77], v[188:191], 0
	v_mfma_f32_16x16x32_bf16 v[14:17], v[66:69], v[202:205], 0
	v_mfma_f32_16x16x32_bf16 v[10:13], v[74:77], v[202:205], 0
	v_mfma_f32_16x16x32_bf16 v[62:65], v[70:73], v[176:179], v[62:65]
	v_mfma_f32_16x16x32_bf16 v[58:61], v[78:81], v[176:179], v[58:61]
	v_mfma_f32_16x16x32_bf16 v[46:49], v[70:73], v[184:187], v[46:49]
	v_mfma_f32_16x16x32_bf16 v[42:45], v[78:81], v[184:187], v[42:45]
	v_mfma_f32_16x16x32_bf16 v[30:33], v[70:73], v[192:195], v[30:33]
	v_mfma_f32_16x16x32_bf16 v[26:29], v[78:81], v[192:195], v[26:29]
	v_mfma_f32_16x16x32_bf16 v[14:17], v[70:73], v[206:209], v[14:17]
	v_mfma_f32_16x16x32_bf16 v[10:13], v[78:81], v[206:209], v[10:13]
	s_setprio 0
	s_setprio 1
	v_mfma_f32_16x16x32_bf16 v[54:57], v[156:159], v[172:175], 0
	v_mfma_f32_16x16x32_bf16 v[50:53], v[164:167], v[172:175], 0
	v_mfma_f32_16x16x32_bf16 v[38:41], v[156:159], v[180:183], 0
	v_mfma_f32_16x16x32_bf16 v[34:37], v[164:167], v[180:183], 0
	v_mfma_f32_16x16x32_bf16 v[22:25], v[156:159], v[188:191], 0
	v_mfma_f32_16x16x32_bf16 v[18:21], v[164:167], v[188:191], 0
	v_mfma_f32_16x16x32_bf16 v[6:9], v[156:159], v[202:205], 0
	v_mfma_f32_16x16x32_bf16 v[2:5], v[164:167], v[202:205], 0
	v_mfma_f32_16x16x32_bf16 v[54:57], v[160:163], v[176:179], v[54:57]
	v_mfma_f32_16x16x32_bf16 v[50:53], v[168:171], v[176:179], v[50:53]
	v_mfma_f32_16x16x32_bf16 v[38:41], v[160:163], v[184:187], v[38:41]
	v_mfma_f32_16x16x32_bf16 v[34:37], v[168:171], v[184:187], v[34:37]
	v_mfma_f32_16x16x32_bf16 v[22:25], v[160:163], v[192:195], v[22:25]
	v_mfma_f32_16x16x32_bf16 v[18:21], v[168:171], v[192:195], v[18:21]
	v_mfma_f32_16x16x32_bf16 v[6:9], v[160:163], v[206:209], v[6:9]
	v_mfma_f32_16x16x32_bf16 v[2:5], v[168:171], v[206:209], v[2:5]
	s_setprio 0
	s_barrier
	s_branch .Lkl427_sp2

; #define PG8_BAR __builtin_amdgcn_s_barrier()
; template <class Epi>
; __device__ __forceinline__ void gemm_phase(LAS unsigned char* lds, const Gemm g, const StaticOrder& S, const Epi& E, const int tid) {
;     ...
;         if (!has_next) break;
; #pragma unroll
;         for (int a = 0; a < 2; ++a)
; #pragma unroll
;             for (int b = 0; b < 2; ++b)
; #pragma unroll
;                 for (int m = 0; m < 4; ++m)
; #pragma unroll
;                     for (int n = 0; n < 2; ++n) acc[a][b][m][n] = (f32x4){0.f, 0.f, 0.f, 0.f};
;         cur = nxt; cA = nA; cB = nB; ++ui;
;         if (wr == 1) PG8_BAR;
.LBB0_618:
	s_waitcnt vmcnt(16)
	s_and_b64 vcc, exec, s[4:5]
	s_mov_b64 s[0:1], -1
	s_cbranch_vccnz .LBB0_418
	v_readlane_b32 s0, v254, 42
	v_readlane_b32 s1, v254, 43
	s_andn2_b64 vcc, exec, s[0:1]
	s_cbranch_vccnz .LBB0_417
	s_barrier
	s_branch .LBB0_417

; #define LAS __attribute__((address_space(3)))
; __device__ __forceinline__ void tr_load(const TrJob& j, float (&wv)[32], int lane) {
;     const int kb = j.r / j.nblk, nb = j.r % j.nblk, k0 = 64 * kb, c0 = 32 * nb;
;     const float* src = j.W + (size_t)(k0 + (lane >> 5)) * j.ldw + j.sc0 + c0 + (lane & 31);
; #pragma unroll
;     for (int i = 0; i < 32; ++i) wv[i] = src[(size_t)(2 * i) * j.ldw];
; }
; __device__ __forceinline__ void tr_store(const TrJob& j, const float (&wv)[32], LAS float* scr, int lane) {
;     const int kb = j.r / j.nblk, nb = j.r % j.nblk, k0 = 64 * kb, c0 = 32 * nb;
; #pragma unroll
;     for (int i = 0; i < 32; ++i) { const int kk = 2 * i + (lane >> 5); scr[kk * 33 + (lane & 31)] = wv[i]; }
;     asm volatile("s_waitcnt lgkmcnt(0)" ::: "memory");
;     const int c = lane & 7;
;     f32x4 g0 = (f32x4){1.f, 1.f, 1.f, 1.f}, g1 = g0;
;     if (j.gain) { g0 = *(const f32x4*)(j.gain + k0 + 8 * c); g1 = *(const f32x4*)(j.gain + k0 + 8 * c + 4); }
; #pragma unroll
;     for (int q = 0; q < 4; ++q) { const int n = (lane >> 3) + 8 * q; const LAS float* s = scr + (8 * c) * 33 + n;
; __device__ __forceinline__ void prologue_phase(const Params& p, LAS unsigned char* lds, const int tid, const int bx) {
;     ...
;             if (hn) { jobn = tr_select(p, WB, itn); tr_load(jobn, nxt, lane); }
;             tr_store(job, cur, scr, lane);
.LBB0_1017:
	s_or_b64 exec, exec, s[12:13]
	v_sub_u32_e32 v0, 0, v105
	v_max_i32_e32 v35, v105, v0
	v_cvt_f32_u32_e32 v37, v35
	v_lshlrev_b32_e32 v0, 2, v36
	v_sub_u32_e32 v41, 0, v103
	v_xor_b32_e32 v40, v103, v105
	v_rcp_iflag_f32_e32 v43, v37
	s_waitcnt vmcnt(0)
	v_lshl_add_u64 v[36:37], v[38:39], 0, v[0:1]
	v_lshlrev_b32_e32 v0, 1, v34
	v_lshl_add_u64 v[84:85], s[52:53], 0, v[0:1]
	v_mul_f32_e32 v38, 0x4f7ffffe, v43
	v_cvt_u32_f32_e32 v38, v38
	v_sub_u32_e32 v0, 0, v35
	v_max_i32_e32 v39, v103, v41
	v_ashrrev_i32_e32 v34, 31, v40
	v_mul_lo_u32 v0, v0, v38
	v_mul_hi_u32 v0, v38, v0
	v_add_u32_e32 v0, v38, v0
	v_mul_hi_u32 v0, v39, v0
	v_mul_lo_u32 v38, v0, v35
	v_sub_u32_e32 v38, v39, v38
	v_add_u32_e32 v39, 1, v0
	v_cmp_ge_u32_e64 s[6:7], v38, v35
	v_mov_b32_e32 v81, v1
	s_nop 0
	v_cndmask_b32_e64 v0, v0, v39, s[6:7]
	v_sub_u32_e32 v39, v38, v35
	v_cndmask_b32_e64 v38, v38, v39, s[6:7]
	v_add_u32_e32 v39, 1, v0
	v_cmp_ge_u32_e64 s[6:7], v38, v35
	s_nop 1
	v_cndmask_b32_e64 v0, v0, v39, s[6:7]
	v_xor_b32_e32 v0, v0, v34
	v_sub_u32_e32 v0, v0, v34
	v_mul_lo_u32 v34, v0, v105
	v_lshl_or_b32 v0, v0, 6, v95
	v_sub_u32_e32 v34, v103, v34
	v_mad_i64_i32 v[38:39], s[6:7], v0, v42, 0
	v_lshlrev_b32_e32 v34, 5, v34
	v_lshl_add_u64 v[36:37], v[38:39], 2, v[36:37]
	v_lshlrev_b32_e32 v0, 2, v44
	v_lshl_add_u64 v[36:37], v[36:37], 0, v[0:1]
	v_ashrrev_i32_e32 v35, 31, v34
	v_lshl_add_u64 v[34:35], v[34:35], 2, v[36:37]
	v_lshl_add_u64 v[34:35], v[34:35], 0, v[80:81]
.LBB0_1018:
	s_or_b64 exec, exec, s[10:11]
	v_sub_u32_e32 v0, 0, v92
	v_max_i32_e32 v0, v92, v0
	v_cvt_f32_u32_e32 v66, v0
	v_sub_u32_e32 v69, 0, v0
	v_sub_u32_e32 v68, 0, v90
	v_max_i32_e32 v68, v90, v68
	v_rcp_iflag_f32_e32 v66, v66
	s_and_b64 s[4:5], exec, s[4:5]
	s_or_b64 s[8:9], s[4:5], s[8:9]
	v_xor_b32_e32 v67, v90, v92
	v_mul_f32_e32 v66, 0x4f7ffffe, v66
	v_cvt_u32_f32_e32 v66, v66
	v_ashrrev_i32_e32 v67, 31, v67
	s_waitcnt vmcnt(0)
	ds_write2_b32 v101, v2, v3 offset1:66
	ds_write2_b32 v101, v4, v5 offset0:132 offset1:198
	v_mov_b32_e32 v71, 1.0
	v_mul_lo_u32 v69, v69, v66
	v_mul_hi_u32 v69, v66, v69
	v_add_u32_e32 v66, v66, v69
	v_mul_hi_u32 v66, v68, v66
	v_mul_lo_u32 v69, v66, v0
	v_sub_u32_e32 v68, v68, v69
	v_add_u32_e32 v70, 1, v66
	v_cmp_ge_u32_e64 s[4:5], v68, v0
	v_sub_u32_e32 v69, v68, v0
	v_mov_b32_e32 v72, 1.0
	v_cndmask_b32_e64 v66, v66, v70, s[4:5]
	v_cndmask_b32_e64 v68, v68, v69, s[4:5]
	v_add_u32_e32 v69, 1, v66
	v_cmp_ge_u32_e64 s[4:5], v68, v0
	v_mov_b32_e32 v68, 1.0
	v_mov_b32_e32 v70, 1.0
	v_cndmask_b32_e64 v0, v66, v69, s[4:5]
	v_xor_b32_e32 v0, v0, v67
	v_sub_u32_e32 v81, v0, v67
	v_add_u32_e32 v0, 0x400, v101
	ds_write2_b32 v0, v6, v7 offset0:8 offset1:74
	ds_write2_b32 v0, v8, v9 offset0:140 offset1:206
	v_add_u32_e32 v0, 0x800, v101
	ds_write2_b32 v0, v10, v11 offset0:16 offset1:82
	ds_write2_b32 v0, v12, v13 offset0:148 offset1:214
	v_add_u32_e32 v0, 0xc00, v101
	ds_write2_b32 v0, v14, v15 offset0:24 offset1:90
	ds_write2_b32 v0, v16, v17 offset0:156 offset1:222
	v_add_u32_e32 v0, 0x1000, v101
	ds_write2_b32 v0, v18, v19 offset0:32 offset1:98
	ds_write2_b32 v0, v20, v21 offset0:164 offset1:230
	v_add_u32_e32 v0, 0x1400, v101
	ds_write2_b32 v0, v22, v23 offset0:40 offset1:106
	ds_write2_b32 v0, v24, v25 offset0:172 offset1:238
	v_add_u32_e32 v0, 0x1800, v101
	ds_write2_b32 v0, v26, v27 offset0:48 offset1:114
	ds_write2_b32 v0, v28, v29 offset0:180 offset1:246
	v_add_u32_e32 v0, 0x1c00, v101
	ds_write2_b32 v0, v30, v31 offset0:56 offset1:122
	ds_write2_b32 v0, v32, v33 offset0:188 offset1:254
	s_waitcnt lgkmcnt(0)
	v_lshlrev_b32_e32 v86, 6, v81
	v_cmp_ne_u64_e64 s[4:5], 0, v[74:75]
	v_ashrrev_i32_e32 v87, 31, v86
	v_mov_b32_e32 v66, 1.0
	v_mov_b32_e32 v67, 1.0
	v_mov_b32_e32 v69, 1.0
	v_mov_b32_e32 v73, 1.0
	s_and_saveexec_b64 s[6:7], s[4:5]
	s_cbranch_execz .LBB0_1020
	v_lshl_add_u64 v[66:67], v[86:87], 2, v[74:75]
	v_lshlrev_b32_e32 v0, 2, v78
	v_lshl_add_u64 v[70:71], v[66:67], 0, v[0:1]
	global_load_dwordx4 v[66:69], v[70:71], off offset:16
	s_nop 0
	global_load_dwordx4 v[70:73], v[70:71], off
.LBB0_1020:
	s_or_b64 exec, exec, s[6:7]
	s_cbranch_vccz .Ltr_nonext
	v_mov_b32_e32 v133, 0
	v_lshlrev_b32_e32 v132, 3, v42
	v_lshl_add_u64 v[36:37], v[34:35], 0, v[132:133]
	v_lshl_add_u64 v[38:39], v[36:37], 0, v[132:133]
	v_lshl_add_u64 v[40:41], v[38:39], 0, v[132:133]
	v_lshl_add_u64 v[42:43], v[40:41], 0, v[132:133]
	global_load_dword v34, v[34:35], off
	s_nop 0
	global_load_dword v35, v[36:37], off
	s_nop 0
	global_load_dword v36, v[38:39], off
	global_load_dword v37, v[40:41], off
	s_nop 0
	global_load_dword v38, v[42:43], off
	v_lshl_add_u64 v[40:41], v[42:43], 0, v[132:133]
	v_lshl_add_u64 v[42:43], v[40:41], 0, v[132:133]
	global_load_dword v39, v[40:41], off
	s_nop 0
	global_load_dword v40, v[42:43], off
	v_lshl_add_u64 v[42:43], v[42:43], 0, v[132:133]
	v_lshl_add_u64 v[44:45], v[42:43], 0, v[132:133]
	global_load_dword v41, v[42:43], off
	s_nop 0
	global_load_dword v42, v[44:45], off
	v_lshl_add_u64 v[44:45], v[44:45], 0, v[132:133]
	v_lshl_add_u64 v[46:47], v[44:45], 0, v[132:133]
	global_load_dword v43, v[44:45], off
	s_nop 0
	global_load_dword v44, v[46:47], off
	v_lshl_add_u64 v[46:47], v[46:47], 0, v[132:133]
	v_lshl_add_u64 v[48:49], v[46:47], 0, v[132:133]
	global_load_dword v45, v[46:47], off
	s_nop 0
	global_load_dword v46, v[48:49], off
	v_lshl_add_u64 v[48:49], v[48:49], 0, v[132:133]
	v_lshl_add_u64 v[50:51], v[48:49], 0, v[132:133]
	global_load_dword v47, v[48:49], off
	s_nop 0
	global_load_dword v48, v[50:51], off
	v_lshl_add_u64 v[50:51], v[50:51], 0, v[132:133]
	v_lshl_add_u64 v[52:53], v[50:51], 0, v[132:133]
; #define LAS __attribute__((address_space(3)))
; __device__ __forceinline__ void tr_load(const TrJob& j, float (&wv)[32], int lane) {
;     ...
;     for (int i = 0; i < 32; ++i) wv[i] = src[(size_t)(2 * i) * j.ldw];
; }
; __device__ __forceinline__ void tr_store(const TrJob& j, const float (&wv)[32], LAS float* scr, int lane) {
;     const int kb = j.r / j.nblk, nb = j.r % j.nblk, k0 = 64 * kb, c0 = 32 * nb;
; #pragma unroll
;     for (int i = 0; i < 32; ++i) { const int kk = 2 * i + (lane >> 5); scr[kk * 33 + (lane & 31)] = wv[i]; }
;     asm volatile("s_waitcnt lgkmcnt(0)" ::: "memory");
;     const int c = lane & 7;
;     f32x4 g0 = (f32x4){1.f, 1.f, 1.f, 1.f}, g1 = g0;
;     if (j.gain) { g0 = *(const f32x4*)(j.gain + k0 + 8 * c); g1 = *(const f32x4*)(j.gain + k0 + 8 * c + 4); }
; #pragma unroll
;     for (int q = 0; q < 4; ++q) { const int n = (lane >> 3) + 8 * q; const LAS float* s = scr + (8 * c) * 33 + n;
;         const int crel = c0 + n; const int drow = j.drb + (j.inter ? ((crel >> 7) * 256 + (crel & 127)) : crel);
;         u32x4 o; o.x = cvt_pk_bf16(s[0 * 33] * g0[0], s[1 * 33] * g0[1]); o.y = cvt_pk_bf16(s[2 * 33] * g0[2], s[3 * 33] * g0[3]); o.z = cvt_pk_bf16(s[4 * 33] * g1[0], s[5 * 33] * g1[1]); o.w = cvt_pk_bf16(s[6 * 33] * g1[2], s[7 * 33] * g1[3]);
;         *(u32x4*)(j.dst + (size_t)drow * j.K + k0 + 8 * c) = o; }
;     asm volatile("s_waitcnt lgkmcnt(0)" ::: "memory");
; }
; __device__ __forceinline__ void prologue_phase(const Params& p, LAS unsigned char* lds, const int tid, const int bx) {
;     const int lane = tid & 63, wave = tid >> 6;
;     const int gw = bx * 8 + wave, NGW = gridDim.x * 8;
;     LAS float* scr = (LAS float*)(lds + wave * 16384);
;     bf16_t* WB = (bf16_t*)(p.ws + WS_W);
;     constexpr int TOTAL = (int)(O_END / 2048);
;     {
;         int it = gw; float cur[32], nxt[32]; TrJob job, jobn;
;         if (it < TOTAL) { job = tr_select(p, WB, it); tr_load(job, cur, lane); }
;         while (it < TOTAL) {
;             const int itn = it + NGW; const bool hn = itn < TOTAL;
;             if (hn) { jobn = tr_select(p, WB, itn); tr_load(jobn, nxt, lane); }
;             tr_store(job, cur, scr, lane);
;             if (hn) { job = jobn;
; #pragma unroll
;                 for (int i = 0; i < 32; ++i) cur[i] = nxt[i]; }
	global_load_dword v49, v[50:51], off
	s_nop 0
	global_load_dword v50, v[52:53], off
	v_lshl_add_u64 v[52:53], v[52:53], 0, v[132:133]
	v_lshl_add_u64 v[54:55], v[52:53], 0, v[132:133]
	global_load_dword v51, v[52:53], off
	s_nop 0
	global_load_dword v52, v[54:55], off
	v_lshl_add_u64 v[54:55], v[54:55], 0, v[132:133]
	v_lshl_add_u64 v[56:57], v[54:55], 0, v[132:133]
	global_load_dword v53, v[54:55], off
	s_nop 0
	global_load_dword v54, v[56:57], off
	v_lshl_add_u64 v[56:57], v[56:57], 0, v[132:133]
	v_lshl_add_u64 v[58:59], v[56:57], 0, v[132:133]
	global_load_dword v55, v[56:57], off
	s_nop 0
	global_load_dword v56, v[58:59], off
	v_lshl_add_u64 v[58:59], v[58:59], 0, v[132:133]
	v_lshl_add_u64 v[60:61], v[58:59], 0, v[132:133]
	global_load_dword v57, v[58:59], off
	s_nop 0
	global_load_dword v58, v[60:61], off
	v_lshl_add_u64 v[60:61], v[60:61], 0, v[132:133]
	v_lshl_add_u64 v[62:63], v[60:61], 0, v[132:133]
	global_load_dword v59, v[60:61], off
	s_nop 0
	global_load_dword v60, v[62:63], off
	v_lshl_add_u64 v[62:63], v[62:63], 0, v[132:133]
	v_lshl_add_u64 v[64:65], v[62:63], 0, v[132:133]
	global_load_dword v61, v[62:63], off
	s_nop 0
	global_load_dword v62, v[64:65], off
	v_lshl_add_u64 v[64:65], v[64:65], 0, v[132:133]
	v_lshl_add_u64 v[134:135], v[64:65], 0, v[132:133]
	global_load_dword v63, v[64:65], off
	s_nop 0
	global_load_dword v64, v[134:135], off
	v_lshl_add_u64 v[134:135], v[134:135], 0, v[132:133]
	global_load_dword v65, v[134:135], off
.Ltr_nonext:
	v_mul_lo_u32 v0, v81, v92
	v_sub_u32_e32 v0, v90, v0
	v_lshlrev_b32_e32 v81, 5, v0
	v_lshlrev_b32_e32 v0, 6, v0
	ds_read2_b32 v[112:113], v97 offset1:8
	ds_read2_b32 v[114:115], v97 offset0:33 offset1:41
	v_and_b32_e32 v130, 0xffffff00, v0
	v_or_b32_e32 v0, v81, v96
	s_movk_i32 s3, 0x67
	ds_read2_b32 v[116:117], v97 offset0:66 offset1:74
	ds_read2_b32 v[118:119], v97 offset0:99 offset1:107
	v_and_or_b32 v108, v0, s3, v130
	v_cmp_eq_u32_e64 s[4:5], 0, v93
	ds_read2_b32 v[120:121], v97 offset0:132 offset1:140
	ds_read2_b32 v[122:123], v97 offset0:165 offset1:173
	v_cndmask_b32_e64 v0, v108, v0, s[4:5]
	v_add_u32_e32 v0, v0, v94
	ds_read2_b32 v[124:125], v97 offset0:198 offset1:206
	ds_read2_b32 v[126:127], v97 offset0:231 offset1:239
	s_cbranch_vccz .Ltr_w0
	s_waitcnt vmcnt(32) lgkmcnt(7)
	s_branch .Ltr_wj
.Ltr_w0:
	s_waitcnt vmcnt(0) lgkmcnt(7)
.Ltr_wj:
	v_mul_f32_e32 v108, v70, v112
	s_waitcnt lgkmcnt(6)
	v_mul_f32_e32 v109, v71, v114
	v_mad_i64_i32 v[128:129], s[6:7], v0, v91, 0
	v_cvt_pk_bf16_f32 v108, v108, v109
	s_waitcnt lgkmcnt(5)
	v_mul_f32_e32 v109, v72, v116
	s_waitcnt lgkmcnt(4)
	v_mul_f32_e32 v110, v73, v118
	v_lshl_add_u64 v[128:129], v[128:129], 1, v[76:77]
	v_lshlrev_b64 v[86:87], 1, v[86:87]
	v_cvt_pk_bf16_f32 v109, v109, v110
	s_waitcnt lgkmcnt(3)
	v_mul_f32_e32 v110, v66, v120
	s_waitcnt lgkmcnt(2)
	v_mul_f32_e32 v111, v67, v122
	v_lshl_add_u64 v[128:129], v[128:129], 0, v[86:87]
	v_lshlrev_b32_e32 v0, 1, v78
	v_cvt_pk_bf16_f32 v110, v110, v111
	s_waitcnt lgkmcnt(1)
	v_mul_f32_e32 v111, v68, v124
	v_lshl_add_u64 v[128:129], v[128:129], 0, v[0:1]
	s_waitcnt lgkmcnt(0)
	v_mul_f32_e32 v112, v69, v126
	v_cvt_pk_bf16_f32 v111, v111, v112
	global_store_dwordx4 v[128:129], v[108:111], off
	s_movk_i32 s3, 0x6f
	s_nop 0
	v_or_b32_e32 v108, v81, v98
	v_and_or_b32 v109, v108, s3, v130
	v_cndmask_b32_e64 v108, v109, v108, s[4:5]
	v_add_u32_e32 v112, v108, v94
	v_mul_f32_e32 v108, v70, v113
	v_mul_f32_e32 v109, v71, v115
	v_cvt_pk_bf16_f32 v108, v108, v109
	v_mul_f32_e32 v109, v72, v117
	v_mul_f32_e32 v110, v73, v119
	v_cvt_pk_bf16_f32 v109, v109, v110
	v_mul_f32_e32 v110, v66, v121
	v_mul_f32_e32 v111, v67, v123
	v_cvt_pk_bf16_f32 v110, v110, v111
	v_mul_f32_e32 v111, v68, v125
	v_mul_f32_e32 v113, v69, v127
	v_cvt_pk_bf16_f32 v111, v111, v113
	v_mad_i64_i32 v[112:113], s[6:7], v112, v91, 0
	v_lshl_add_u64 v[112:113], v[112:113], 1, v[76:77]
	v_lshl_add_u64 v[112:113], v[112:113], 0, v[86:87]
	v_lshl_add_u64 v[112:113], v[112:113], 0, v[0:1]
	global_store_dwordx4 v[112:113], v[108:111], off
	ds_read2_b32 v[112:113], v97 offset0:16 offset1:24
	ds_read2_b32 v[114:115], v97 offset0:49 offset1:57
	v_or_b32_e32 v108, v81, v99
	s_movk_i32 s3, 0x77
	ds_read2_b32 v[116:117], v97 offset0:82 offset1:90
	ds_read2_b32 v[118:119], v97 offset0:115 offset1:123
	v_and_or_b32 v109, v108, s3, v130
	ds_read2_b32 v[120:121], v97 offset0:148 offset1:156
	ds_read2_b32 v[122:123], v97 offset0:181 offset1:189
	v_cndmask_b32_e64 v108, v109, v108, s[4:5]
	v_add_u32_e32 v128, v108, v94
	ds_read2_b32 v[124:125], v97 offset0:214 offset1:222
	ds_read2_b32 v[126:127], v97 offset0:247 offset1:255
	s_waitcnt lgkmcnt(7)
	v_mul_f32_e32 v108, v70, v112
	s_waitcnt lgkmcnt(6)
	v_mul_f32_e32 v109, v71, v114
	v_mad_i64_i32 v[128:129], s[6:7], v128, v91, 0
	v_cvt_pk_bf16_f32 v108, v108, v109
	s_waitcnt lgkmcnt(5)
	v_mul_f32_e32 v109, v72, v116
	s_waitcnt lgkmcnt(4)
	v_mul_f32_e32 v110, v73, v118
	v_lshl_add_u64 v[128:129], v[128:129], 1, v[76:77]
	v_cvt_pk_bf16_f32 v109, v109, v110
	s_waitcnt lgkmcnt(3)
	v_mul_f32_e32 v110, v66, v120
	s_waitcnt lgkmcnt(2)
	v_mul_f32_e32 v111, v67, v122
	v_lshl_add_u64 v[128:129], v[128:129], 0, v[86:87]
	v_cvt_pk_bf16_f32 v110, v110, v111
	s_waitcnt lgkmcnt(1)
	v_mul_f32_e32 v111, v68, v124
	v_lshl_add_u64 v[128:129], v[128:129], 0, v[0:1]
	v_or_b32_e32 v81, v81, v100
	s_movk_i32 s3, 0x7f
	s_waitcnt lgkmcnt(0)
	v_mul_f32_e32 v112, v69, v126
	v_cvt_pk_bf16_f32 v111, v111, v112
	global_store_dwordx4 v[128:129], v[108:111], off
	v_mul_f32_e32 v70, v70, v113
	v_mul_f32_e32 v71, v71, v115
	v_and_or_b32 v108, v81, s3, v130
	v_cndmask_b32_e64 v81, v108, v81, s[4:5]
	v_cvt_pk_bf16_f32 v70, v70, v71
	v_mul_f32_e32 v71, v72, v117
	v_mul_f32_e32 v72, v73, v119
	v_mul_f32_e32 v66, v66, v121
	v_mul_f32_e32 v67, v67, v123
	v_add_u32_e32 v81, v81, v94
	v_cvt_pk_bf16_f32 v71, v71, v72
	v_cvt_pk_bf16_f32 v72, v66, v67
	v_mul_f32_e32 v66, v68, v125
	v_mul_f32_e32 v67, v69, v127
	v_cvt_pk_bf16_f32 v73, v66, v67
	v_mad_i64_i32 v[66:67], s[4:5], v81, v91, 0
	v_lshl_add_u64 v[66:67], v[66:67], 1, v[76:77]
	v_lshl_add_u64 v[66:67], v[66:67], 0, v[86:87]
	v_lshl_add_u64 v[66:67], v[66:67], 0, v[0:1]
	global_store_dwordx4 v[66:67], v[70:73], off
	s_waitcnt lgkmcnt(0)
	s_and_saveexec_b64 s[4:5], vcc
	s_cbranch_execz .LBB0_887
	s_waitcnt vmcnt(4)
	v_mov_b64_e32 v[2:3], v[34:35]
	v_mov_b32_e32 v90, v103
	v_mov_b32_e32 v93, v106
	v_mov_b32_e32 v94, v107
	v_mov_b32_e32 v91, v104
	v_mov_b32_e32 v92, v105
	v_mov_b64_e32 v[76:77], v[84:85]
	v_mov_b64_e32 v[74:75], v[82:83]
	v_mov_b64_e32 v[4:5], v[36:37]
	v_mov_b64_e32 v[6:7], v[38:39]
	v_mov_b64_e32 v[8:9], v[40:41]
	v_mov_b64_e32 v[10:11], v[42:43]
	v_mov_b64_e32 v[12:13], v[44:45]
	v_mov_b64_e32 v[14:15], v[46:47]
	v_mov_b64_e32 v[16:17], v[48:49]
	v_mov_b64_e32 v[18:19], v[50:51]
	v_mov_b64_e32 v[20:21], v[52:53]
	v_mov_b64_e32 v[22:23], v[54:55]
	v_mov_b64_e32 v[24:25], v[56:57]
	v_mov_b64_e32 v[26:27], v[58:59]
	v_mov_b64_e32 v[28:29], v[60:61]
	v_mov_b64_e32 v[30:31], v[62:63]
	v_mov_b64_e32 v[32:33], v[64:65]
	s_branch .LBB0_887
